# GEMM K-loops: removed the zero-duration s_setprio 0/1 flip pairs between the two 16-MFMA sub-blocks (2 issue slots inside each MFMA-paced segment); stacks on v7
# baseline (speedup 1.0000x reference)
; #define PG8_STAGE(bufoff, gbase, voff) do { _Pragma("unroll") for (int _i = 0; _i < 2; ++_i) \
;         __builtin_amdgcn_global_load_lds((const unsigned*)((const char*)(gbase) + (voff)[_i]), (PG8_LAS unsigned*)(lds + (bufoff) + ldsw + _i * 8192), 16, 0, 0); } while (0)
; #define PG8_LDA(dst, b, h) do { _Pragma("unroll") for (int m = 0; m < 4; ++m) _Pragma("unroll") for (int k = 0; k < 2; ++k) dst[m][k] = *(const PG8_LAS bf16x8*)(lds + PG8_SA(b, h) + aoff + m * 2048 + k * 1024); } while (0)
; #define PG8_LDB(dst, b, h) do { _Pragma("unroll") for (int n = 0; n < 2; ++n) _Pragma("unroll") for (int k = 0; k < 2; ++k) dst[n][k] = *(const PG8_LAS bf16x8*)(lds + PG8_SB(b, h) + boff + n * 2048 + k * 1024); } while (0)
; #define PG8_MMA(ai, bj, At, Bt) do { __builtin_amdgcn_s_setprio(1); _Pragma("unroll") for (int m = 0; m < 4; ++m) _Pragma("unroll") for (int n = 0; n < 2; ++n) _Pragma("unroll") for (int k = 0; k < 2; ++k) \
;         acc[ai][bj][m][n] = __builtin_amdgcn_mfma_f32_16x16x32_bf16(Bt[n][k], At[m][k], acc[ai][bj][m][n], 0, 0, 0); __builtin_amdgcn_s_setprio(0); } while (0)
; #define PG8_WAIT_V(n) asm volatile("s_waitcnt vmcnt(" #n ")" ::: "memory")
; #define PG8_BAR __builtin_amdgcn_s_barrier()
; template <class Epi, class Sched, bool ALIGN_EPI = false, bool SP2 = false>
; __device__ __forceinline__ void gemm_phase(PG8_LAS unsigned char* lds, const Gemm g, const Sched& S, const Epi& E) {
;     ...
;         for (int t = 0; t < nt; t += 2) {
;             const bool last = (t == nt - 2);
;             const char* a1 = cA + (size_t)(t + 1) * kstep;
;             const char* a2 = last ? nA : cA + (size_t)(t + 2) * kstep; const char* b2 = last ? nB : cB + (size_t)(t + 2) * kstep;
;             const char* a3 = a2 + kstep; const char* b3 = b2 + kstep;
;             if (last && has_next) S.a_ready(nxt);
;             if constexpr (SP2) {
;             PG8_LDB(B0, 0, 0); PG8_LDB(B1, 0, 1); PG8_SCHED; PG8_LDA(At, 0, 0); PG8_STAGE(PG8_SA(1, 1), a1 + hstep, voffA);
;             PG8_WAIT_V(8); PG8_WAIT_L(0); PG8_BAR; PG8_MMA(0, 0, At, B0); PG8_MMA(0, 1, At, B1); PG8_BAR; PG8_SCHED;
;             PG8_LDA(At, 0, 1); PG8_STAGE(PG8_SB(0, 0), b2, voffB); PG8_STAGE(PG8_SB(0, 1), b2 + hstep, voffB); PG8_STAGE(PG8_SA(0, 0), a2, voffA);
;             PG8_WAIT_V(8); PG8_WAIT_L(0); PG8_BAR; PG8_MMA(1, 0, At, B0); PG8_MMA(1, 1, At, B1); PG8_BAR; PG8_SCHED;
.LBB0_205:
	ds_read_b128 v[128:131], v190
	ds_read_b128 v[132:135], v190 offset:1024
	ds_read_b128 v[136:139], v190 offset:2048
	ds_read_b128 v[140:143], v190 offset:3072
	ds_read_b128 v[144:147], v191
	ds_read_b128 v[148:151], v191 offset:1024
	ds_read_b128 v[152:155], v191 offset:2048
	ds_read_b128 v[156:159], v191 offset:3072
	s_add_u32 s6, s4, 0xfff80080
	s_addc_u32 s7, s5, -1
	s_cmp_eq_u32 s51, 28
	s_cselect_b32 s29, s1, s7
	s_cselect_b32 s28, s3, s6
	s_cselect_b32 s7, s21, s50
	s_cselect_b32 s6, s23, s33
	v_lshl_add_u64 v[184:185], s[4:5], 0, v[172:173]
	s_add_i32 m0, s31, 0xc000
	ds_read_b128 v[180:183], v192
	ds_read_b128 v[194:197], v192 offset:1024
	ds_read_b128 v[198:201], v192 offset:2048
	ds_read_b128 v[202:205], v192 offset:3072
	ds_read_b128 v[206:209], v192 offset:4096
	ds_read_b128 v[210:213], v192 offset:5120
	ds_read_b128 v[214:217], v192 offset:6144
	ds_read_b128 v[218:221], v192 offset:7168
	global_load_lds_dwordx4 v[184:185], off
	v_lshl_add_u64 v[184:185], s[4:5], 0, v[174:175]
	s_add_i32 m0, s31, 0xe000
	s_nop 0
	global_load_lds_dwordx4 v[184:185], off
	s_waitcnt vmcnt(8)
	s_waitcnt lgkmcnt(0)
	s_barrier
	s_setprio 1
	s_waitcnt lgkmcnt(0)
	v_mfma_f32_16x16x32_bf16 v[124:127], v[128:131], v[180:183], v[124:127]
	v_mfma_f32_16x16x32_bf16 v[120:123], v[136:139], v[180:183], v[120:123]
	v_mfma_f32_16x16x32_bf16 v[108:111], v[128:131], v[198:201], v[108:111]
	v_mfma_f32_16x16x32_bf16 v[104:107], v[136:139], v[198:201], v[104:107]
	v_mfma_f32_16x16x32_bf16 v[92:95], v[128:131], v[206:209], v[92:95]
	v_mfma_f32_16x16x32_bf16 v[88:91], v[136:139], v[206:209], v[88:91]
	v_mfma_f32_16x16x32_bf16 v[76:79], v[128:131], v[214:217], v[76:79]
	v_mfma_f32_16x16x32_bf16 v[72:75], v[136:139], v[214:217], v[72:75]
	v_mfma_f32_16x16x32_bf16 v[124:127], v[132:135], v[194:197], v[124:127]
	v_mfma_f32_16x16x32_bf16 v[120:123], v[140:143], v[194:197], v[120:123]
	v_mfma_f32_16x16x32_bf16 v[108:111], v[132:135], v[202:205], v[108:111]
	v_mfma_f32_16x16x32_bf16 v[104:107], v[140:143], v[202:205], v[104:107]
	v_mfma_f32_16x16x32_bf16 v[92:95], v[132:135], v[210:213], v[92:95]
	v_mfma_f32_16x16x32_bf16 v[88:91], v[140:143], v[210:213], v[88:91]
	v_mfma_f32_16x16x32_bf16 v[76:79], v[132:135], v[218:221], v[76:79]
	v_mfma_f32_16x16x32_bf16 v[72:75], v[140:143], v[218:221], v[72:75]
	v_mfma_f32_16x16x32_bf16 v[116:119], v[144:147], v[180:183], v[116:119]
	v_mfma_f32_16x16x32_bf16 v[112:115], v[152:155], v[180:183], v[112:115]
	v_mfma_f32_16x16x32_bf16 v[100:103], v[144:147], v[198:201], v[100:103]
	v_mfma_f32_16x16x32_bf16 v[96:99], v[152:155], v[198:201], v[96:99]
	v_mfma_f32_16x16x32_bf16 v[84:87], v[144:147], v[206:209], v[84:87]
	v_mfma_f32_16x16x32_bf16 v[80:83], v[152:155], v[206:209], v[80:83]
	v_mfma_f32_16x16x32_bf16 v[68:71], v[144:147], v[214:217], v[68:71]
	v_mfma_f32_16x16x32_bf16 v[64:67], v[152:155], v[214:217], v[64:67]
	v_mfma_f32_16x16x32_bf16 v[116:119], v[148:151], v[194:197], v[116:119]
	v_mfma_f32_16x16x32_bf16 v[112:115], v[156:159], v[194:197], v[112:115]
	v_mfma_f32_16x16x32_bf16 v[100:103], v[148:151], v[202:205], v[100:103]
	v_mfma_f32_16x16x32_bf16 v[96:99], v[156:159], v[202:205], v[96:99]
	v_mfma_f32_16x16x32_bf16 v[84:87], v[148:151], v[210:213], v[84:87]
	v_mfma_f32_16x16x32_bf16 v[80:83], v[156:159], v[210:213], v[80:83]
	v_mfma_f32_16x16x32_bf16 v[68:71], v[148:151], v[218:221], v[68:71]
	v_mfma_f32_16x16x32_bf16 v[64:67], v[156:159], v[218:221], v[64:67]
	s_setprio 0
	s_barrier
	s_add_i32 s52, s43, s30
	v_lshl_add_u64 v[184:185], s[6:7], 0, v[164:165]
	s_mov_b32 m0, s52
	ds_read_b128 v[180:183], v192 offset:16384
	ds_read_b128 v[194:197], v192 offset:17408
	ds_read_b128 v[198:201], v192 offset:18432
	ds_read_b128 v[202:205], v192 offset:19456
	ds_read_b128 v[206:209], v192 offset:20480
	ds_read_b128 v[210:213], v192 offset:21504
	ds_read_b128 v[214:217], v192 offset:22528
	ds_read_b128 v[218:221], v192 offset:23552
	global_load_lds_dwordx4 v[184:185], off
	s_add_i32 m0, s52, 0x2000
	s_add_u32 s52, s6, 0x80000
	v_lshl_add_u64 v[222:223], s[6:7], 0, v[168:169]
	s_addc_u32 s53, s7, 0
	s_add_i32 s54, s44, s30
	global_load_lds_dwordx4 v[222:223], off
	v_lshl_add_u64 v[224:225], s[52:53], 0, v[164:165]
	s_mov_b32 m0, s54
	v_lshl_add_u64 v[226:227], s[28:29], 0, v[166:167]
	global_load_lds_dwordx4 v[224:225], off
	v_lshl_add_u64 v[224:225], s[52:53], 0, v[168:169]
	s_add_i32 m0, s54, 0x2000
	s_nop 0
	global_load_lds_dwordx4 v[224:225], off
	v_lshl_add_u64 v[224:225], s[28:29], 0, v[162:163]
	s_mov_b32 m0, s31
	s_nop 0
	global_load_lds_dwordx4 v[224:225], off
	s_mov_b32 m0, s34
	s_nop 0
	global_load_lds_dwordx4 v[226:227], off
	s_waitcnt vmcnt(8)
	s_waitcnt lgkmcnt(0)
	s_barrier
; #define PG8_STAGE(bufoff, gbase, voff) do { _Pragma("unroll") for (int _i = 0; _i < 2; ++_i) \
;         __builtin_amdgcn_global_load_lds((const unsigned*)((const char*)(gbase) + (voff)[_i]), (PG8_LAS unsigned*)(lds + (bufoff) + ldsw + _i * 8192), 16, 0, 0); } while (0)
; #define PG8_LDA(dst, b, h) do { _Pragma("unroll") for (int m = 0; m < 4; ++m) _Pragma("unroll") for (int k = 0; k < 2; ++k) dst[m][k] = *(const PG8_LAS bf16x8*)(lds + PG8_SA(b, h) + aoff + m * 2048 + k * 1024); } while (0)
; #define PG8_LDB(dst, b, h) do { _Pragma("unroll") for (int n = 0; n < 2; ++n) _Pragma("unroll") for (int k = 0; k < 2; ++k) dst[n][k] = *(const PG8_LAS bf16x8*)(lds + PG8_SB(b, h) + boff + n * 2048 + k * 1024); } while (0)
; #define PG8_MMA(ai, bj, At, Bt) do { __builtin_amdgcn_s_setprio(1); _Pragma("unroll") for (int m = 0; m < 4; ++m) _Pragma("unroll") for (int n = 0; n < 2; ++n) _Pragma("unroll") for (int k = 0; k < 2; ++k) \
;         acc[ai][bj][m][n] = __builtin_amdgcn_mfma_f32_16x16x32_bf16(Bt[n][k], At[m][k], acc[ai][bj][m][n], 0, 0, 0); __builtin_amdgcn_s_setprio(0); } while (0)
; #define PG8_WAIT_V(n) asm volatile("s_waitcnt vmcnt(" #n ")" ::: "memory")
; #define PG8_WAIT_L(n) asm volatile("s_waitcnt lgkmcnt(" #n ")" ::: "memory")
; #define PG8_BAR __builtin_amdgcn_s_barrier()
; #define PG8_SCHED __builtin_amdgcn_sched_barrier(0)
; template <class Epi, class Sched, bool ALIGN_EPI = false, bool SP2 = false>
; __device__ __forceinline__ void gemm_phase(PG8_LAS unsigned char* lds, const Gemm g, const Sched& S, const Epi& E) {
;     ...
;             PG8_WAIT_V(8); PG8_WAIT_L(0); PG8_BAR; PG8_MMA(0, 0, At, B0); PG8_MMA(0, 1, At, B1); PG8_BAR; PG8_SCHED;
;             PG8_LDA(At, 0, 1); PG8_STAGE(PG8_SB(0, 0), b2, voffB); PG8_STAGE(PG8_SB(0, 1), b2 + hstep, voffB); PG8_STAGE(PG8_SA(0, 0), a2, voffA);
;             PG8_WAIT_V(8); PG8_WAIT_L(0); PG8_BAR; PG8_MMA(1, 0, At, B0); PG8_MMA(1, 1, At, B1); PG8_BAR; PG8_SCHED;
;             PG8_LDB(B0, 1, 0); PG8_LDB(B1, 1, 1); PG8_SCHED; PG8_LDA(At, 1, 0); PG8_STAGE(PG8_SA(0, 1), a2 + hstep, voffA);
;             PG8_WAIT_V(8); PG8_WAIT_L(0); PG8_BAR; PG8_MMA(0, 0, At, B0); PG8_MMA(0, 1, At, B1); PG8_BAR; PG8_SCHED;
	s_setprio 1
	s_waitcnt lgkmcnt(0)
	v_mfma_f32_16x16x32_bf16 v[60:63], v[128:131], v[180:183], v[60:63]
	v_mfma_f32_16x16x32_bf16 v[56:59], v[136:139], v[180:183], v[56:59]
	v_mfma_f32_16x16x32_bf16 v[44:47], v[128:131], v[198:201], v[44:47]
	v_mfma_f32_16x16x32_bf16 v[40:43], v[136:139], v[198:201], v[40:43]
	v_mfma_f32_16x16x32_bf16 v[28:31], v[128:131], v[206:209], v[28:31]
	v_mfma_f32_16x16x32_bf16 v[24:27], v[136:139], v[206:209], v[24:27]
	v_mfma_f32_16x16x32_bf16 v[12:15], v[128:131], v[214:217], v[12:15]
	v_mfma_f32_16x16x32_bf16 v[8:11], v[136:139], v[214:217], v[8:11]
	v_mfma_f32_16x16x32_bf16 v[60:63], v[132:135], v[194:197], v[60:63]
	v_mfma_f32_16x16x32_bf16 v[56:59], v[140:143], v[194:197], v[56:59]
	v_mfma_f32_16x16x32_bf16 v[44:47], v[132:135], v[202:205], v[44:47]
	v_mfma_f32_16x16x32_bf16 v[40:43], v[140:143], v[202:205], v[40:43]
	v_mfma_f32_16x16x32_bf16 v[28:31], v[132:135], v[210:213], v[28:31]
	v_mfma_f32_16x16x32_bf16 v[24:27], v[140:143], v[210:213], v[24:27]
	v_mfma_f32_16x16x32_bf16 v[12:15], v[132:135], v[218:221], v[12:15]
	v_mfma_f32_16x16x32_bf16 v[8:11], v[140:143], v[218:221], v[8:11]
	v_mfma_f32_16x16x32_bf16 v[52:55], v[144:147], v[180:183], v[52:55]
	v_mfma_f32_16x16x32_bf16 v[48:51], v[152:155], v[180:183], v[48:51]
	v_mfma_f32_16x16x32_bf16 v[36:39], v[144:147], v[198:201], v[36:39]
	v_mfma_f32_16x16x32_bf16 v[32:35], v[152:155], v[198:201], v[32:35]
	v_mfma_f32_16x16x32_bf16 v[20:23], v[144:147], v[206:209], v[20:23]
	v_mfma_f32_16x16x32_bf16 v[16:19], v[152:155], v[206:209], v[16:19]
	v_mfma_f32_16x16x32_bf16 v[4:7], v[144:147], v[214:217], v[4:7]
	v_mfma_f32_16x16x32_bf16 v[0:3], v[152:155], v[214:217], v[0:3]
	v_mfma_f32_16x16x32_bf16 v[52:55], v[148:151], v[194:197], v[52:55]
	v_mfma_f32_16x16x32_bf16 v[48:51], v[156:159], v[194:197], v[48:51]
	v_mfma_f32_16x16x32_bf16 v[36:39], v[148:151], v[202:205], v[36:39]
	v_mfma_f32_16x16x32_bf16 v[32:35], v[156:159], v[202:205], v[32:35]
	v_mfma_f32_16x16x32_bf16 v[20:23], v[148:151], v[210:213], v[20:23]
	v_mfma_f32_16x16x32_bf16 v[16:19], v[156:159], v[210:213], v[16:19]
	v_mfma_f32_16x16x32_bf16 v[4:7], v[148:151], v[218:221], v[4:7]
	v_mfma_f32_16x16x32_bf16 v[0:3], v[156:159], v[218:221], v[0:3]
	s_setprio 0
	s_barrier
	s_add_i32 s52, 0, 0x18000
	s_add_i32 s53, 0, 0x1c000
	v_add_u32_e32 v140, s52, v188
	v_add_u32_e32 v156, s53, v188
	ds_read_b128 v[128:131], v140
	ds_read_b128 v[132:135], v140 offset:1024
	ds_read_b128 v[136:139], v140 offset:2048
	ds_read_b128 v[140:143], v140 offset:3072
	ds_read_b128 v[144:147], v156
	ds_read_b128 v[148:151], v156 offset:1024
	ds_read_b128 v[152:155], v156 offset:2048
	ds_read_b128 v[156:159], v156 offset:3072
	s_add_u32 s28, s28, 0x80000
	s_addc_u32 s29, s29, 0
	s_mov_b32 m0, s35
	v_lshl_add_u64 v[228:229], s[28:29], 0, v[162:163]
	ds_read_b128 v[180:183], v192 offset:32768
	ds_read_b128 v[194:197], v192 offset:33792
	ds_read_b128 v[198:201], v192 offset:34816
	ds_read_b128 v[202:205], v192 offset:35840
	ds_read_b128 v[206:209], v192 offset:36864
	ds_read_b128 v[210:213], v192 offset:37888
	ds_read_b128 v[214:217], v192 offset:38912
	ds_read_b128 v[218:221], v192 offset:39936
	global_load_lds_dwordx4 v[228:229], off
	v_lshl_add_u64 v[228:229], s[28:29], 0, v[166:167]
	s_mov_b32 m0, s36
	s_nop 0
	global_load_lds_dwordx4 v[228:229], off
	s_waitcnt vmcnt(8)
	s_waitcnt lgkmcnt(0)
	s_barrier
	s_setprio 1
	s_waitcnt lgkmcnt(0)
	v_mfma_f32_16x16x32_bf16 v[124:127], v[128:131], v[180:183], v[124:127]
	v_mfma_f32_16x16x32_bf16 v[120:123], v[136:139], v[180:183], v[120:123]
	v_mfma_f32_16x16x32_bf16 v[108:111], v[128:131], v[198:201], v[108:111]
	v_mfma_f32_16x16x32_bf16 v[104:107], v[136:139], v[198:201], v[104:107]
	v_mfma_f32_16x16x32_bf16 v[92:95], v[128:131], v[206:209], v[92:95]
	v_mfma_f32_16x16x32_bf16 v[88:91], v[136:139], v[206:209], v[88:91]
	v_mfma_f32_16x16x32_bf16 v[76:79], v[128:131], v[214:217], v[76:79]
	v_mfma_f32_16x16x32_bf16 v[72:75], v[136:139], v[214:217], v[72:75]
	v_mfma_f32_16x16x32_bf16 v[124:127], v[132:135], v[194:197], v[124:127]
	v_mfma_f32_16x16x32_bf16 v[120:123], v[140:143], v[194:197], v[120:123]
	v_mfma_f32_16x16x32_bf16 v[108:111], v[132:135], v[202:205], v[108:111]
	v_mfma_f32_16x16x32_bf16 v[104:107], v[140:143], v[202:205], v[104:107]
	v_mfma_f32_16x16x32_bf16 v[92:95], v[132:135], v[210:213], v[92:95]
	v_mfma_f32_16x16x32_bf16 v[88:91], v[140:143], v[210:213], v[88:91]
	v_mfma_f32_16x16x32_bf16 v[76:79], v[132:135], v[218:221], v[76:79]
	v_mfma_f32_16x16x32_bf16 v[72:75], v[140:143], v[218:221], v[72:75]
	v_mfma_f32_16x16x32_bf16 v[116:119], v[144:147], v[180:183], v[116:119]
	v_mfma_f32_16x16x32_bf16 v[112:115], v[152:155], v[180:183], v[112:115]
	v_mfma_f32_16x16x32_bf16 v[100:103], v[144:147], v[198:201], v[100:103]
	v_mfma_f32_16x16x32_bf16 v[96:99], v[152:155], v[198:201], v[96:99]
	v_mfma_f32_16x16x32_bf16 v[84:87], v[144:147], v[206:209], v[84:87]
	v_mfma_f32_16x16x32_bf16 v[80:83], v[152:155], v[206:209], v[80:83]
	v_mfma_f32_16x16x32_bf16 v[68:71], v[144:147], v[214:217], v[68:71]
	v_mfma_f32_16x16x32_bf16 v[64:67], v[152:155], v[214:217], v[64:67]
	v_mfma_f32_16x16x32_bf16 v[116:119], v[148:151], v[194:197], v[116:119]
	v_mfma_f32_16x16x32_bf16 v[112:115], v[156:159], v[194:197], v[112:115]
	v_mfma_f32_16x16x32_bf16 v[100:103], v[148:151], v[202:205], v[100:103]
	v_mfma_f32_16x16x32_bf16 v[96:99], v[156:159], v[202:205], v[96:99]
	v_mfma_f32_16x16x32_bf16 v[84:87], v[148:151], v[210:213], v[84:87]
	v_mfma_f32_16x16x32_bf16 v[80:83], v[156:159], v[210:213], v[80:83]
	v_mfma_f32_16x16x32_bf16 v[68:71], v[148:151], v[218:221], v[68:71]
	v_mfma_f32_16x16x32_bf16 v[64:67], v[156:159], v[218:221], v[64:67]
	s_setprio 0
	s_barrier
; #define PG8_STAGE(bufoff, gbase, voff) do { _Pragma("unroll") for (int _i = 0; _i < 2; ++_i) \
;         __builtin_amdgcn_global_load_lds((const unsigned*)((const char*)(gbase) + (voff)[_i]), (PG8_LAS unsigned*)(lds + (bufoff) + ldsw + _i * 8192), 16, 0, 0); } while (0)
; #define PG8_LDA(dst, b, h) do { _Pragma("unroll") for (int m = 0; m < 4; ++m) _Pragma("unroll") for (int k = 0; k < 2; ++k) dst[m][k] = *(const PG8_LAS bf16x8*)(lds + PG8_SA(b, h) + aoff + m * 2048 + k * 1024); } while (0)
; #define PG8_LDB(dst, b, h) do { _Pragma("unroll") for (int n = 0; n < 2; ++n) _Pragma("unroll") for (int k = 0; k < 2; ++k) dst[n][k] = *(const PG8_LAS bf16x8*)(lds + PG8_SB(b, h) + boff + n * 2048 + k * 1024); } while (0)
; template <class Epi, class Sched, bool ALIGN_EPI = false, bool SP2 = false>
; __device__ __forceinline__ void gemm_phase(PG8_LAS unsigned char* lds, const Gemm g, const Sched& S, const Epi& E) {
;     ...
;         for (int t = 0; t < nt; t += 2) {
;             const bool last = (t == nt - 2);
;             const char* a1 = cA + (size_t)(t + 1) * kstep;
;             const char* a2 = last ? nA : cA + (size_t)(t + 2) * kstep; const char* b2 = last ? nB : cB + (size_t)(t + 2) * kstep;
;             const char* a3 = a2 + kstep; const char* b3 = b2 + kstep;
;             if (last && has_next) S.a_ready(nxt);
;             if constexpr (SP2) {
;             PG8_LDB(B0, 0, 0); PG8_LDB(B1, 0, 1); PG8_SCHED; PG8_LDA(At, 0, 0); PG8_STAGE(PG8_SA(1, 1), a1 + hstep, voffA);
;             PG8_WAIT_V(8); PG8_WAIT_L(0); PG8_BAR; PG8_MMA(0, 0, At, B0); PG8_MMA(0, 1, At, B1); PG8_BAR; PG8_SCHED;
;             PG8_LDA(At, 0, 1); PG8_STAGE(PG8_SB(0, 0), b2, voffB); PG8_STAGE(PG8_SB(0, 1), b2 + hstep, voffB); PG8_STAGE(PG8_SA(0, 0), a2, voffA);
;             PG8_WAIT_V(8); PG8_WAIT_L(0); PG8_BAR; PG8_MMA(1, 0, At, B0); PG8_MMA(1, 1, At, B1); PG8_BAR; PG8_SCHED;
;             PG8_LDB(B0, 1, 0); PG8_LDB(B1, 1, 1); PG8_SCHED; PG8_LDA(At, 1, 0); PG8_STAGE(PG8_SA(0, 1), a2 + hstep, voffA);
;             PG8_WAIT_V(8); PG8_WAIT_L(0); PG8_BAR; PG8_MMA(0, 0, At, B0); PG8_MMA(0, 1, At, B1); PG8_BAR; PG8_SCHED;
;             PG8_LDA(At, 1, 1); PG8_STAGE(PG8_SB(1, 0), b3, voffB); PG8_STAGE(PG8_SB(1, 1), b3 + hstep, voffB); PG8_STAGE(PG8_SA(1, 0), a3, voffA);
;             PG8_WAIT_V(8); PG8_WAIT_L(0); PG8_BAR; PG8_MMA(1, 0, At, B0); PG8_MMA(1, 1, At, B1); PG8_BAR; PG8_SCHED;
	s_add_i32 s28, s52, s30
	v_lshl_add_u64 v[184:185], v[184:185], 0, s[16:17]
	s_mov_b32 m0, s28
	ds_read_b128 v[180:183], v192 offset:49152
	ds_read_b128 v[194:197], v192 offset:50176
	ds_read_b128 v[198:201], v192 offset:51200
	ds_read_b128 v[202:205], v192 offset:52224
	ds_read_b128 v[206:209], v192 offset:53248
	ds_read_b128 v[210:213], v192 offset:54272
	ds_read_b128 v[214:217], v192 offset:55296
	ds_read_b128 v[218:221], v192 offset:56320
	global_load_lds_dwordx4 v[184:185], off
	s_add_i32 m0, s28, 0x2000
	s_add_u32 s6, s6, 0x80080
	v_lshl_add_u64 v[184:185], v[222:223], 0, s[16:17]
	s_addc_u32 s7, s7, 0
	s_add_i32 s28, s53, s30
	global_load_lds_dwordx4 v[184:185], off
	v_lshl_add_u64 v[184:185], s[6:7], 0, v[164:165]
	s_mov_b32 m0, s28
	s_nop 0
	global_load_lds_dwordx4 v[184:185], off
	v_lshl_add_u64 v[184:185], s[6:7], 0, v[168:169]
	s_add_i32 m0, s28, 0x2000
	s_nop 0
	global_load_lds_dwordx4 v[184:185], off
	v_lshl_add_u64 v[184:185], v[224:225], 0, s[16:17]
	s_mov_b32 m0, s38
	s_nop 0
	global_load_lds_dwordx4 v[184:185], off
	v_lshl_add_u64 v[184:185], v[226:227], 0, s[16:17]
	s_mov_b32 m0, s39
	s_nop 0
	global_load_lds_dwordx4 v[184:185], off
	s_waitcnt vmcnt(8)
	s_waitcnt lgkmcnt(0)
	s_barrier
	s_setprio 1
	s_waitcnt lgkmcnt(0)
	v_mfma_f32_16x16x32_bf16 v[60:63], v[128:131], v[180:183], v[60:63]
	v_mfma_f32_16x16x32_bf16 v[56:59], v[136:139], v[180:183], v[56:59]
	v_mfma_f32_16x16x32_bf16 v[44:47], v[128:131], v[198:201], v[44:47]
	v_mfma_f32_16x16x32_bf16 v[40:43], v[136:139], v[198:201], v[40:43]
	v_mfma_f32_16x16x32_bf16 v[28:31], v[128:131], v[206:209], v[28:31]
	v_mfma_f32_16x16x32_bf16 v[24:27], v[136:139], v[206:209], v[24:27]
	v_mfma_f32_16x16x32_bf16 v[12:15], v[128:131], v[214:217], v[12:15]
	v_mfma_f32_16x16x32_bf16 v[8:11], v[136:139], v[214:217], v[8:11]
	v_mfma_f32_16x16x32_bf16 v[60:63], v[132:135], v[194:197], v[60:63]
	v_mfma_f32_16x16x32_bf16 v[56:59], v[140:143], v[194:197], v[56:59]
	v_mfma_f32_16x16x32_bf16 v[44:47], v[132:135], v[202:205], v[44:47]
	v_mfma_f32_16x16x32_bf16 v[40:43], v[140:143], v[202:205], v[40:43]
	v_mfma_f32_16x16x32_bf16 v[28:31], v[132:135], v[210:213], v[28:31]
	v_mfma_f32_16x16x32_bf16 v[24:27], v[140:143], v[210:213], v[24:27]
	v_mfma_f32_16x16x32_bf16 v[12:15], v[132:135], v[218:221], v[12:15]
	v_mfma_f32_16x16x32_bf16 v[8:11], v[140:143], v[218:221], v[8:11]
	v_mfma_f32_16x16x32_bf16 v[52:55], v[144:147], v[180:183], v[52:55]
	v_mfma_f32_16x16x32_bf16 v[48:51], v[152:155], v[180:183], v[48:51]
	v_mfma_f32_16x16x32_bf16 v[36:39], v[144:147], v[198:201], v[36:39]
	v_mfma_f32_16x16x32_bf16 v[32:35], v[152:155], v[198:201], v[32:35]
	v_mfma_f32_16x16x32_bf16 v[20:23], v[144:147], v[206:209], v[20:23]
	v_mfma_f32_16x16x32_bf16 v[16:19], v[152:155], v[206:209], v[16:19]
	v_mfma_f32_16x16x32_bf16 v[4:7], v[144:147], v[214:217], v[4:7]
	v_mfma_f32_16x16x32_bf16 v[0:3], v[152:155], v[214:217], v[0:3]
	v_mfma_f32_16x16x32_bf16 v[52:55], v[148:151], v[194:197], v[52:55]
	v_mfma_f32_16x16x32_bf16 v[48:51], v[156:159], v[194:197], v[48:51]
	v_mfma_f32_16x16x32_bf16 v[36:39], v[148:151], v[202:205], v[36:39]
	v_mfma_f32_16x16x32_bf16 v[32:35], v[156:159], v[202:205], v[32:35]
	v_mfma_f32_16x16x32_bf16 v[20:23], v[148:151], v[210:213], v[20:23]
	v_mfma_f32_16x16x32_bf16 v[16:19], v[156:159], v[210:213], v[16:19]
	v_mfma_f32_16x16x32_bf16 v[4:7], v[148:151], v[218:221], v[4:7]
	v_mfma_f32_16x16x32_bf16 v[0:3], v[156:159], v[218:221], v[0:3]
	s_setprio 0
	s_barrier
	s_add_i32 s51, s51, 2
	s_add_u32 s4, s4, 0x100
	s_addc_u32 s5, s5, 0
	s_add_u32 s33, s33, 0x100
	s_addc_u32 s50, s50, 0
	s_cmp_gt_u32 s51, 29
	s_cbranch_scc0 .LBB0_205
	s_and_b64 vcc, exec, s[18:19]
	s_cbranch_vccz .LBB0_208
	s_barrier

; #define PG8_STAGE(bufoff, gbase, voff) do { _Pragma("unroll") for (int _i = 0; _i < 2; ++_i) \
;         __builtin_amdgcn_global_load_lds((const unsigned*)((const char*)(gbase) + (voff)[_i]), (PG8_LAS unsigned*)(lds + (bufoff) + ldsw + _i * 8192), 16, 0, 0); } while (0)
; #define PG8_LDA(dst, b, h) do { _Pragma("unroll") for (int m = 0; m < 4; ++m) _Pragma("unroll") for (int k = 0; k < 2; ++k) dst[m][k] = *(const PG8_LAS bf16x8*)(lds + PG8_SA(b, h) + aoff + m * 2048 + k * 1024); } while (0)
; #define PG8_LDB(dst, b, h) do { _Pragma("unroll") for (int n = 0; n < 2; ++n) _Pragma("unroll") for (int k = 0; k < 2; ++k) dst[n][k] = *(const PG8_LAS bf16x8*)(lds + PG8_SB(b, h) + boff + n * 2048 + k * 1024); } while (0)
; #define PG8_MMA(ai, bj, At, Bt) do { __builtin_amdgcn_s_setprio(1); _Pragma("unroll") for (int m = 0; m < 4; ++m) _Pragma("unroll") for (int n = 0; n < 2; ++n) _Pragma("unroll") for (int k = 0; k < 2; ++k) \
;         acc[ai][bj][m][n] = __builtin_amdgcn_mfma_f32_16x16x32_bf16(Bt[n][k], At[m][k], acc[ai][bj][m][n], 0, 0, 0); __builtin_amdgcn_s_setprio(0); } while (0)
; #define PG8_WAIT_V(n) asm volatile("s_waitcnt vmcnt(" #n ")" ::: "memory")
; #define PG8_WAIT_L(n) asm volatile("s_waitcnt lgkmcnt(" #n ")" ::: "memory")
; #define PG8_BAR __builtin_amdgcn_s_barrier()
; #define PG8_SCHED __builtin_amdgcn_sched_barrier(0)
; template <class Epi, class Sched, bool ALIGN_EPI = false, bool SP2 = false>
; __device__ __forceinline__ void gemm_phase(PG8_LAS unsigned char* lds, const Gemm g, const Sched& S, const Epi& E) {
;     ...
;             PG8_LDB(B0, 0, 0); PG8_LDB(B1, 0, 1); PG8_SCHED; PG8_LDA(At, 0, 0); PG8_STAGE(PG8_SA(1, 1), a1 + hstep, voffA);
;             PG8_WAIT_V(8); PG8_WAIT_L(0); PG8_BAR; PG8_MMA(0, 0, At, B0); PG8_MMA(0, 1, At, B1); PG8_BAR; PG8_SCHED;
;             PG8_LDA(At, 0, 1); PG8_STAGE(PG8_SB(0, 0), b2, voffB); PG8_STAGE(PG8_SB(0, 1), b2 + hstep, voffB); PG8_STAGE(PG8_SA(0, 0), a2, voffA);
.LBB0_572:
	ds_read_b128 v[146:149], v159
	ds_read_b128 v[150:153], v159 offset:1024
	ds_read_b128 v[164:167], v159 offset:2048
	ds_read_b128 v[168:171], v159 offset:3072
	ds_read_b128 v[172:175], v161
	ds_read_b128 v[176:179], v161 offset:1024
	ds_read_b128 v[180:183], v161 offset:2048
	ds_read_b128 v[188:191], v161 offset:3072
	s_add_u32 s24, s22, 0xfffc0080
	s_addc_u32 s25, s23, -1
	s_cmp_eq_u32 s46, 12
	s_cselect_b32 s27, s7, s25
	s_cselect_b32 s26, s15, s24
	s_cselect_b32 s25, s13, s45
	s_cselect_b32 s24, s21, s44
	v_lshl_add_u64 v[154:155], s[22:23], 0, v[138:139]
	s_add_i32 m0, s31, 0xc000
	ds_read_b128 v[192:195], v162
	ds_read_b128 v[196:199], v162 offset:1024
	ds_read_b128 v[200:203], v162 offset:2048
	ds_read_b128 v[204:207], v162 offset:3072
	ds_read_b128 v[208:211], v162 offset:4096
	ds_read_b128 v[212:215], v162 offset:5120
	ds_read_b128 v[216:219], v162 offset:6144
	ds_read_b128 v[220:223], v162 offset:7168
	global_load_lds_dwordx4 v[154:155], off
	v_lshl_add_u64 v[154:155], s[22:23], 0, v[140:141]
	s_add_i32 m0, s31, 0xe000
	s_nop 0
	global_load_lds_dwordx4 v[154:155], off
	s_waitcnt vmcnt(8)
	s_waitcnt lgkmcnt(0)
	s_barrier
	s_setprio 1
	s_waitcnt lgkmcnt(0)
	v_mfma_f32_16x16x32_bf16 v[124:127], v[146:149], v[192:195], v[124:127]
	v_mfma_f32_16x16x32_bf16 v[120:123], v[164:167], v[192:195], v[120:123]
	v_mfma_f32_16x16x32_bf16 v[108:111], v[146:149], v[200:203], v[108:111]
	v_mfma_f32_16x16x32_bf16 v[104:107], v[164:167], v[200:203], v[104:107]
	v_mfma_f32_16x16x32_bf16 v[92:95], v[146:149], v[208:211], v[92:95]
	v_mfma_f32_16x16x32_bf16 v[88:91], v[164:167], v[208:211], v[88:91]
	v_mfma_f32_16x16x32_bf16 v[76:79], v[146:149], v[216:219], v[76:79]
	v_mfma_f32_16x16x32_bf16 v[72:75], v[164:167], v[216:219], v[72:75]
	v_mfma_f32_16x16x32_bf16 v[124:127], v[150:153], v[196:199], v[124:127]
	v_mfma_f32_16x16x32_bf16 v[120:123], v[168:171], v[196:199], v[120:123]
	v_mfma_f32_16x16x32_bf16 v[108:111], v[150:153], v[204:207], v[108:111]
	v_mfma_f32_16x16x32_bf16 v[104:107], v[168:171], v[204:207], v[104:107]
	v_mfma_f32_16x16x32_bf16 v[92:95], v[150:153], v[212:215], v[92:95]
	v_mfma_f32_16x16x32_bf16 v[88:91], v[168:171], v[212:215], v[88:91]
	v_mfma_f32_16x16x32_bf16 v[76:79], v[150:153], v[220:223], v[76:79]
	v_mfma_f32_16x16x32_bf16 v[72:75], v[168:171], v[220:223], v[72:75]
	v_mfma_f32_16x16x32_bf16 v[116:119], v[172:175], v[192:195], v[116:119]
	v_mfma_f32_16x16x32_bf16 v[112:115], v[180:183], v[192:195], v[112:115]
	v_mfma_f32_16x16x32_bf16 v[100:103], v[172:175], v[200:203], v[100:103]
	v_mfma_f32_16x16x32_bf16 v[96:99], v[180:183], v[200:203], v[96:99]
	v_mfma_f32_16x16x32_bf16 v[84:87], v[172:175], v[208:211], v[84:87]
	v_mfma_f32_16x16x32_bf16 v[80:83], v[180:183], v[208:211], v[80:83]
	v_mfma_f32_16x16x32_bf16 v[68:71], v[172:175], v[216:219], v[68:71]
	v_mfma_f32_16x16x32_bf16 v[64:67], v[180:183], v[216:219], v[64:67]
	v_mfma_f32_16x16x32_bf16 v[116:119], v[176:179], v[196:199], v[116:119]
	v_mfma_f32_16x16x32_bf16 v[112:115], v[188:191], v[196:199], v[112:115]
	v_mfma_f32_16x16x32_bf16 v[100:103], v[176:179], v[204:207], v[100:103]
	v_mfma_f32_16x16x32_bf16 v[96:99], v[188:191], v[204:207], v[96:99]
	v_mfma_f32_16x16x32_bf16 v[84:87], v[176:179], v[212:215], v[84:87]
	v_mfma_f32_16x16x32_bf16 v[80:83], v[188:191], v[212:215], v[80:83]
	v_mfma_f32_16x16x32_bf16 v[68:71], v[176:179], v[220:223], v[68:71]
	v_mfma_f32_16x16x32_bf16 v[64:67], v[188:191], v[220:223], v[64:67]
	s_setprio 0
	s_barrier
	s_add_i32 s47, s39, s28
	v_lshl_add_u64 v[154:155], s[24:25], 0, v[130:131]
	s_mov_b32 m0, s47
	ds_read_b128 v[192:195], v162 offset:16384
	ds_read_b128 v[196:199], v162 offset:17408
	ds_read_b128 v[200:203], v162 offset:18432
	ds_read_b128 v[204:207], v162 offset:19456
	ds_read_b128 v[208:211], v162 offset:20480
	ds_read_b128 v[212:215], v162 offset:21504
	ds_read_b128 v[216:219], v162 offset:22528
	ds_read_b128 v[220:223], v162 offset:23552
	global_load_lds_dwordx4 v[154:155], off
	s_add_i32 m0, s47, 0x2000
	s_add_u32 s48, s24, 0x40000
	v_lshl_add_u64 v[184:185], s[24:25], 0, v[134:135]
	s_addc_u32 s49, s25, 0
	s_add_i32 s47, s40, s28
	global_load_lds_dwordx4 v[184:185], off
	v_lshl_add_u64 v[224:225], s[48:49], 0, v[130:131]
	s_mov_b32 m0, s47
	v_lshl_add_u64 v[226:227], s[26:27], 0, v[132:133]
	global_load_lds_dwordx4 v[224:225], off
	v_lshl_add_u64 v[224:225], s[48:49], 0, v[134:135]
	s_add_i32 m0, s47, 0x2000
	s_nop 0
	global_load_lds_dwordx4 v[224:225], off
	v_lshl_add_u64 v[224:225], s[26:27], 0, v[128:129]
	s_mov_b32 m0, s31
	s_nop 0
	global_load_lds_dwordx4 v[224:225], off
	s_mov_b32 m0, s33
	s_nop 0
	global_load_lds_dwordx4 v[226:227], off
	s_waitcnt vmcnt(8)
	s_waitcnt lgkmcnt(0)
	s_barrier
; #define PG8_STAGE(bufoff, gbase, voff) do { _Pragma("unroll") for (int _i = 0; _i < 2; ++_i) \
;         __builtin_amdgcn_global_load_lds((const unsigned*)((const char*)(gbase) + (voff)[_i]), (PG8_LAS unsigned*)(lds + (bufoff) + ldsw + _i * 8192), 16, 0, 0); } while (0)
; #define PG8_LDA(dst, b, h) do { _Pragma("unroll") for (int m = 0; m < 4; ++m) _Pragma("unroll") for (int k = 0; k < 2; ++k) dst[m][k] = *(const PG8_LAS bf16x8*)(lds + PG8_SA(b, h) + aoff + m * 2048 + k * 1024); } while (0)
; #define PG8_LDB(dst, b, h) do { _Pragma("unroll") for (int n = 0; n < 2; ++n) _Pragma("unroll") for (int k = 0; k < 2; ++k) dst[n][k] = *(const PG8_LAS bf16x8*)(lds + PG8_SB(b, h) + boff + n * 2048 + k * 1024); } while (0)
; #define PG8_MMA(ai, bj, At, Bt) do { __builtin_amdgcn_s_setprio(1); _Pragma("unroll") for (int m = 0; m < 4; ++m) _Pragma("unroll") for (int n = 0; n < 2; ++n) _Pragma("unroll") for (int k = 0; k < 2; ++k) \
;         acc[ai][bj][m][n] = __builtin_amdgcn_mfma_f32_16x16x32_bf16(Bt[n][k], At[m][k], acc[ai][bj][m][n], 0, 0, 0); __builtin_amdgcn_s_setprio(0); } while (0)
; #define PG8_WAIT_V(n) asm volatile("s_waitcnt vmcnt(" #n ")" ::: "memory")
; #define PG8_WAIT_L(n) asm volatile("s_waitcnt lgkmcnt(" #n ")" ::: "memory")
; #define PG8_BAR __builtin_amdgcn_s_barrier()
; #define PG8_SCHED __builtin_amdgcn_sched_barrier(0)
; template <class Epi, class Sched, bool ALIGN_EPI = false, bool SP2 = false>
; __device__ __forceinline__ void gemm_phase(PG8_LAS unsigned char* lds, const Gemm g, const Sched& S, const Epi& E) {
;     ...
;             PG8_WAIT_V(8); PG8_WAIT_L(0); PG8_BAR; PG8_MMA(1, 0, At, B0); PG8_MMA(1, 1, At, B1); PG8_BAR; PG8_SCHED;
;             PG8_LDB(B0, 1, 0); PG8_LDB(B1, 1, 1); PG8_SCHED; PG8_LDA(At, 1, 0); PG8_STAGE(PG8_SA(0, 1), a2 + hstep, voffA);
;             PG8_WAIT_V(8); PG8_WAIT_L(0); PG8_BAR; PG8_MMA(0, 0, At, B0); PG8_MMA(0, 1, At, B1); PG8_BAR; PG8_SCHED;
	s_setprio 1
	s_waitcnt lgkmcnt(0)
	v_mfma_f32_16x16x32_bf16 v[60:63], v[146:149], v[192:195], v[60:63]
	v_mfma_f32_16x16x32_bf16 v[56:59], v[164:167], v[192:195], v[56:59]
	v_mfma_f32_16x16x32_bf16 v[44:47], v[146:149], v[200:203], v[44:47]
	v_mfma_f32_16x16x32_bf16 v[40:43], v[164:167], v[200:203], v[40:43]
	v_mfma_f32_16x16x32_bf16 v[28:31], v[146:149], v[208:211], v[28:31]
	v_mfma_f32_16x16x32_bf16 v[24:27], v[164:167], v[208:211], v[24:27]
	v_mfma_f32_16x16x32_bf16 v[12:15], v[146:149], v[216:219], v[12:15]
	v_mfma_f32_16x16x32_bf16 v[8:11], v[164:167], v[216:219], v[8:11]
	v_mfma_f32_16x16x32_bf16 v[60:63], v[150:153], v[196:199], v[60:63]
	v_mfma_f32_16x16x32_bf16 v[56:59], v[168:171], v[196:199], v[56:59]
	v_mfma_f32_16x16x32_bf16 v[44:47], v[150:153], v[204:207], v[44:47]
	v_mfma_f32_16x16x32_bf16 v[40:43], v[168:171], v[204:207], v[40:43]
	v_mfma_f32_16x16x32_bf16 v[28:31], v[150:153], v[212:215], v[28:31]
	v_mfma_f32_16x16x32_bf16 v[24:27], v[168:171], v[212:215], v[24:27]
	v_mfma_f32_16x16x32_bf16 v[12:15], v[150:153], v[220:223], v[12:15]
	v_mfma_f32_16x16x32_bf16 v[8:11], v[168:171], v[220:223], v[8:11]
	v_mfma_f32_16x16x32_bf16 v[52:55], v[172:175], v[192:195], v[52:55]
	v_mfma_f32_16x16x32_bf16 v[48:51], v[180:183], v[192:195], v[48:51]
	v_mfma_f32_16x16x32_bf16 v[36:39], v[172:175], v[200:203], v[36:39]
	v_mfma_f32_16x16x32_bf16 v[32:35], v[180:183], v[200:203], v[32:35]
	v_mfma_f32_16x16x32_bf16 v[20:23], v[172:175], v[208:211], v[20:23]
	v_mfma_f32_16x16x32_bf16 v[16:19], v[180:183], v[208:211], v[16:19]
	v_mfma_f32_16x16x32_bf16 v[4:7], v[172:175], v[216:219], v[4:7]
	v_mfma_f32_16x16x32_bf16 v[0:3], v[180:183], v[216:219], v[0:3]
	v_mfma_f32_16x16x32_bf16 v[52:55], v[176:179], v[196:199], v[52:55]
	v_mfma_f32_16x16x32_bf16 v[48:51], v[188:191], v[196:199], v[48:51]
	v_mfma_f32_16x16x32_bf16 v[36:39], v[176:179], v[204:207], v[36:39]
	v_mfma_f32_16x16x32_bf16 v[32:35], v[188:191], v[204:207], v[32:35]
	v_mfma_f32_16x16x32_bf16 v[20:23], v[176:179], v[212:215], v[20:23]
	v_mfma_f32_16x16x32_bf16 v[16:19], v[188:191], v[212:215], v[16:19]
	v_mfma_f32_16x16x32_bf16 v[4:7], v[176:179], v[220:223], v[4:7]
	v_mfma_f32_16x16x32_bf16 v[0:3], v[188:191], v[220:223], v[0:3]
	s_setprio 0
	s_barrier
	s_add_i32 s47, 0, 0x18000
	v_add_u32_e32 v136, s47, v157
	s_add_i32 s48, 0, 0x1c000
	ds_read_b128 v[146:149], v136
	ds_read_b128 v[150:153], v136 offset:1024
	ds_read_b128 v[164:167], v136 offset:2048
	ds_read_b128 v[168:171], v136 offset:3072
	v_add_u32_e32 v136, s48, v157
	ds_read_b128 v[172:175], v136
	ds_read_b128 v[176:179], v136 offset:1024
	ds_read_b128 v[180:183], v136 offset:2048
	ds_read_b128 v[188:191], v136 offset:3072
	s_add_u32 s26, s26, 0x40000
	s_addc_u32 s27, s27, 0
	s_mov_b32 m0, s34
	v_lshl_add_u64 v[228:229], s[26:27], 0, v[128:129]
	ds_read_b128 v[192:195], v162 offset:32768
	ds_read_b128 v[196:199], v162 offset:33792
	ds_read_b128 v[200:203], v162 offset:34816
	ds_read_b128 v[204:207], v162 offset:35840
	ds_read_b128 v[208:211], v162 offset:36864
	ds_read_b128 v[212:215], v162 offset:37888
	ds_read_b128 v[216:219], v162 offset:38912
	ds_read_b128 v[220:223], v162 offset:39936
	global_load_lds_dwordx4 v[228:229], off
	v_lshl_add_u64 v[228:229], s[26:27], 0, v[132:133]
	s_mov_b32 m0, s35
	s_nop 0
	global_load_lds_dwordx4 v[228:229], off
	s_waitcnt vmcnt(8)
	s_waitcnt lgkmcnt(0)
	s_barrier
	s_setprio 1
	s_waitcnt lgkmcnt(0)
	v_mfma_f32_16x16x32_bf16 v[124:127], v[146:149], v[192:195], v[124:127]
	v_mfma_f32_16x16x32_bf16 v[120:123], v[164:167], v[192:195], v[120:123]
	v_mfma_f32_16x16x32_bf16 v[108:111], v[146:149], v[200:203], v[108:111]
	v_mfma_f32_16x16x32_bf16 v[104:107], v[164:167], v[200:203], v[104:107]
	v_mfma_f32_16x16x32_bf16 v[92:95], v[146:149], v[208:211], v[92:95]
	v_mfma_f32_16x16x32_bf16 v[88:91], v[164:167], v[208:211], v[88:91]
	v_mfma_f32_16x16x32_bf16 v[76:79], v[146:149], v[216:219], v[76:79]
	v_mfma_f32_16x16x32_bf16 v[72:75], v[164:167], v[216:219], v[72:75]
	v_mfma_f32_16x16x32_bf16 v[124:127], v[150:153], v[196:199], v[124:127]
	v_mfma_f32_16x16x32_bf16 v[120:123], v[168:171], v[196:199], v[120:123]
	v_mfma_f32_16x16x32_bf16 v[108:111], v[150:153], v[204:207], v[108:111]
	v_mfma_f32_16x16x32_bf16 v[104:107], v[168:171], v[204:207], v[104:107]
	v_mfma_f32_16x16x32_bf16 v[92:95], v[150:153], v[212:215], v[92:95]
	v_mfma_f32_16x16x32_bf16 v[88:91], v[168:171], v[212:215], v[88:91]
	v_mfma_f32_16x16x32_bf16 v[76:79], v[150:153], v[220:223], v[76:79]
	v_mfma_f32_16x16x32_bf16 v[72:75], v[168:171], v[220:223], v[72:75]
	v_mfma_f32_16x16x32_bf16 v[116:119], v[172:175], v[192:195], v[116:119]
	v_mfma_f32_16x16x32_bf16 v[112:115], v[180:183], v[192:195], v[112:115]
	v_mfma_f32_16x16x32_bf16 v[100:103], v[172:175], v[200:203], v[100:103]
	v_mfma_f32_16x16x32_bf16 v[96:99], v[180:183], v[200:203], v[96:99]
	v_mfma_f32_16x16x32_bf16 v[84:87], v[172:175], v[208:211], v[84:87]
	v_mfma_f32_16x16x32_bf16 v[80:83], v[180:183], v[208:211], v[80:83]
	v_mfma_f32_16x16x32_bf16 v[68:71], v[172:175], v[216:219], v[68:71]
	v_mfma_f32_16x16x32_bf16 v[64:67], v[180:183], v[216:219], v[64:67]
	v_mfma_f32_16x16x32_bf16 v[116:119], v[176:179], v[196:199], v[116:119]
	v_mfma_f32_16x16x32_bf16 v[112:115], v[188:191], v[196:199], v[112:115]
	v_mfma_f32_16x16x32_bf16 v[100:103], v[176:179], v[204:207], v[100:103]
	v_mfma_f32_16x16x32_bf16 v[96:99], v[188:191], v[204:207], v[96:99]
	v_mfma_f32_16x16x32_bf16 v[84:87], v[176:179], v[212:215], v[84:87]
	v_mfma_f32_16x16x32_bf16 v[80:83], v[188:191], v[212:215], v[80:83]
	v_mfma_f32_16x16x32_bf16 v[68:71], v[176:179], v[220:223], v[68:71]
	v_mfma_f32_16x16x32_bf16 v[64:67], v[188:191], v[220:223], v[64:67]
	s_setprio 0
	s_barrier
; #define PG8_STAGE(bufoff, gbase, voff) do { _Pragma("unroll") for (int _i = 0; _i < 2; ++_i) \
;         __builtin_amdgcn_global_load_lds((const unsigned*)((const char*)(gbase) + (voff)[_i]), (PG8_LAS unsigned*)(lds + (bufoff) + ldsw + _i * 8192), 16, 0, 0); } while (0)
; #define PG8_LDA(dst, b, h) do { _Pragma("unroll") for (int m = 0; m < 4; ++m) _Pragma("unroll") for (int k = 0; k < 2; ++k) dst[m][k] = *(const PG8_LAS bf16x8*)(lds + PG8_SA(b, h) + aoff + m * 2048 + k * 1024); } while (0)
; #define PG8_MMA(ai, bj, At, Bt) do { __builtin_amdgcn_s_setprio(1); _Pragma("unroll") for (int m = 0; m < 4; ++m) _Pragma("unroll") for (int n = 0; n < 2; ++n) _Pragma("unroll") for (int k = 0; k < 2; ++k) \
;         acc[ai][bj][m][n] = __builtin_amdgcn_mfma_f32_16x16x32_bf16(Bt[n][k], At[m][k], acc[ai][bj][m][n], 0, 0, 0); __builtin_amdgcn_s_setprio(0); } while (0)
; #define PG8_WAIT_V(n) asm volatile("s_waitcnt vmcnt(" #n ")" ::: "memory")
; #define PG8_WAIT_L(n) asm volatile("s_waitcnt lgkmcnt(" #n ")" ::: "memory")
; #define PG8_BAR __builtin_amdgcn_s_barrier()
; #define PG8_SCHED __builtin_amdgcn_sched_barrier(0)
; template <class Epi, class Sched, bool ALIGN_EPI = false, bool SP2 = false>
; __device__ __forceinline__ void gemm_phase(PG8_LAS unsigned char* lds, const Gemm g, const Sched& S, const Epi& E) {
;     ...
;             PG8_LDA(At, 1, 1); PG8_STAGE(PG8_SB(1, 0), b3, voffB); PG8_STAGE(PG8_SB(1, 1), b3 + hstep, voffB); PG8_STAGE(PG8_SA(1, 0), a3, voffA);
;             PG8_WAIT_V(8); PG8_WAIT_L(0); PG8_BAR; PG8_MMA(1, 0, At, B0); PG8_MMA(1, 1, At, B1); PG8_BAR; PG8_SCHED;
;     ...
;         if constexpr (ALIGN_EPI) { if (wr == 0) PG8_BAR; }
	s_add_i32 s26, s47, s28
	v_lshl_add_u64 v[154:155], v[154:155], 0, s[8:9]
	s_mov_b32 m0, s26
	ds_read_b128 v[192:195], v162 offset:49152
	ds_read_b128 v[196:199], v162 offset:50176
	ds_read_b128 v[200:203], v162 offset:51200
	ds_read_b128 v[204:207], v162 offset:52224
	ds_read_b128 v[208:211], v162 offset:53248
	ds_read_b128 v[212:215], v162 offset:54272
	ds_read_b128 v[216:219], v162 offset:55296
	ds_read_b128 v[220:223], v162 offset:56320
	global_load_lds_dwordx4 v[154:155], off
	s_add_i32 m0, s26, 0x2000
	s_add_u32 s24, s24, 0x40080
	v_lshl_add_u64 v[154:155], v[184:185], 0, s[8:9]
	s_addc_u32 s25, s25, 0
	s_add_i32 s26, s48, s28
	global_load_lds_dwordx4 v[154:155], off
	v_lshl_add_u64 v[154:155], s[24:25], 0, v[130:131]
	s_mov_b32 m0, s26
	s_nop 0
	global_load_lds_dwordx4 v[154:155], off
	v_lshl_add_u64 v[154:155], s[24:25], 0, v[134:135]
	s_add_i32 m0, s26, 0x2000
	s_nop 0
	global_load_lds_dwordx4 v[154:155], off
	v_lshl_add_u64 v[154:155], v[224:225], 0, s[8:9]
	s_mov_b32 m0, s36
	s_nop 0
	global_load_lds_dwordx4 v[154:155], off
	v_lshl_add_u64 v[154:155], v[226:227], 0, s[8:9]
	s_mov_b32 m0, s37
	s_nop 0
	global_load_lds_dwordx4 v[154:155], off
	s_waitcnt vmcnt(8)
	s_waitcnt lgkmcnt(0)
	s_barrier
	s_setprio 1
	s_waitcnt lgkmcnt(0)
	v_mfma_f32_16x16x32_bf16 v[60:63], v[146:149], v[192:195], v[60:63]
	v_mfma_f32_16x16x32_bf16 v[56:59], v[164:167], v[192:195], v[56:59]
	v_mfma_f32_16x16x32_bf16 v[44:47], v[146:149], v[200:203], v[44:47]
	v_mfma_f32_16x16x32_bf16 v[40:43], v[164:167], v[200:203], v[40:43]
	v_mfma_f32_16x16x32_bf16 v[28:31], v[146:149], v[208:211], v[28:31]
	v_mfma_f32_16x16x32_bf16 v[24:27], v[164:167], v[208:211], v[24:27]
	v_mfma_f32_16x16x32_bf16 v[12:15], v[146:149], v[216:219], v[12:15]
	v_mfma_f32_16x16x32_bf16 v[8:11], v[164:167], v[216:219], v[8:11]
	v_mfma_f32_16x16x32_bf16 v[60:63], v[150:153], v[196:199], v[60:63]
	v_mfma_f32_16x16x32_bf16 v[56:59], v[168:171], v[196:199], v[56:59]
	v_mfma_f32_16x16x32_bf16 v[44:47], v[150:153], v[204:207], v[44:47]
	v_mfma_f32_16x16x32_bf16 v[40:43], v[168:171], v[204:207], v[40:43]
	v_mfma_f32_16x16x32_bf16 v[28:31], v[150:153], v[212:215], v[28:31]
	v_mfma_f32_16x16x32_bf16 v[24:27], v[168:171], v[212:215], v[24:27]
	v_mfma_f32_16x16x32_bf16 v[12:15], v[150:153], v[220:223], v[12:15]
	v_mfma_f32_16x16x32_bf16 v[8:11], v[168:171], v[220:223], v[8:11]
	v_mfma_f32_16x16x32_bf16 v[52:55], v[172:175], v[192:195], v[52:55]
	v_mfma_f32_16x16x32_bf16 v[48:51], v[180:183], v[192:195], v[48:51]
	v_mfma_f32_16x16x32_bf16 v[36:39], v[172:175], v[200:203], v[36:39]
	v_mfma_f32_16x16x32_bf16 v[32:35], v[180:183], v[200:203], v[32:35]
	v_mfma_f32_16x16x32_bf16 v[20:23], v[172:175], v[208:211], v[20:23]
	v_mfma_f32_16x16x32_bf16 v[16:19], v[180:183], v[208:211], v[16:19]
	v_mfma_f32_16x16x32_bf16 v[4:7], v[172:175], v[216:219], v[4:7]
	v_mfma_f32_16x16x32_bf16 v[0:3], v[180:183], v[216:219], v[0:3]
	v_mfma_f32_16x16x32_bf16 v[52:55], v[176:179], v[196:199], v[52:55]
	v_mfma_f32_16x16x32_bf16 v[48:51], v[188:191], v[196:199], v[48:51]
	v_mfma_f32_16x16x32_bf16 v[36:39], v[176:179], v[204:207], v[36:39]
	v_mfma_f32_16x16x32_bf16 v[32:35], v[188:191], v[204:207], v[32:35]
	v_mfma_f32_16x16x32_bf16 v[20:23], v[176:179], v[212:215], v[20:23]
	v_mfma_f32_16x16x32_bf16 v[16:19], v[188:191], v[212:215], v[16:19]
	v_mfma_f32_16x16x32_bf16 v[4:7], v[176:179], v[220:223], v[4:7]
	v_mfma_f32_16x16x32_bf16 v[0:3], v[188:191], v[220:223], v[0:3]
	s_setprio 0
	s_barrier
	s_add_i32 s46, s46, 2
	s_add_u32 s22, s22, 0x100
	s_addc_u32 s23, s23, 0
	s_add_u32 s44, s44, 0x100
	s_addc_u32 s45, s45, 0
	s_cmp_gt_u32 s46, 13
	s_cbranch_scc0 .LBB0_572
	s_and_b64 vcc, exec, s[10:11]
	s_cbranch_vccz .LBB0_575
	s_barrier

; #define PG8_STAGE(bufoff, gbase, voff) do { _Pragma("unroll") for (int _i = 0; _i < 2; ++_i) \
;         __builtin_amdgcn_global_load_lds((const unsigned*)((const char*)(gbase) + (voff)[_i]), (PG8_LAS unsigned*)(lds + (bufoff) + ldsw + _i * 8192), 16, 0, 0); } while (0)
; #define PG8_LDA(dst, b, h) do { _Pragma("unroll") for (int m = 0; m < 4; ++m) _Pragma("unroll") for (int k = 0; k < 2; ++k) dst[m][k] = *(const PG8_LAS bf16x8*)(lds + PG8_SA(b, h) + aoff + m * 2048 + k * 1024); } while (0)
; #define PG8_LDB(dst, b, h) do { _Pragma("unroll") for (int n = 0; n < 2; ++n) _Pragma("unroll") for (int k = 0; k < 2; ++k) dst[n][k] = *(const PG8_LAS bf16x8*)(lds + PG8_SB(b, h) + boff + n * 2048 + k * 1024); } while (0)
; #define PG8_WAIT_V(n) asm volatile("s_waitcnt vmcnt(" #n ")" ::: "memory")
; #define PG8_WAIT_L(n) asm volatile("s_waitcnt lgkmcnt(" #n ")" ::: "memory")
; #define PG8_BAR __builtin_amdgcn_s_barrier()
; #define PG8_SCHED __builtin_amdgcn_sched_barrier(0)
; template <class Epi, class Sched, bool ALIGN_EPI = false, bool SP2 = false>
; __device__ __forceinline__ void gemm_phase(PG8_LAS unsigned char* lds, const Gemm g, const Sched& S, const Epi& E) {
;     ...
;         const char* nA = has_next ? (const char*)g.A + (size_t)nxt.pm * tstep : cA; const char* nB = has_next ? (const char*)g.Bt + (size_t)nxt.pn * tstep : cB;
;         for (int t = 0; t < nt; t += 2) {
;             const bool last = (t == nt - 2);
;             const char* a1 = cA + (size_t)(t + 1) * kstep;
;             const char* a2 = last ? nA : cA + (size_t)(t + 2) * kstep; const char* b2 = last ? nB : cB + (size_t)(t + 2) * kstep;
;             const char* a3 = a2 + kstep; const char* b3 = b2 + kstep;
;             if (last && has_next) S.a_ready(nxt);
;             if constexpr (SP2) {
;             PG8_LDB(B0, 0, 0); PG8_LDB(B1, 0, 1); PG8_SCHED; PG8_LDA(At, 0, 0); PG8_STAGE(PG8_SA(1, 1), a1 + hstep, voffA);
;             PG8_WAIT_V(8); PG8_WAIT_L(0); PG8_BAR; PG8_MMA(0, 0, At, B0); PG8_MMA(0, 1, At, B1); PG8_BAR; PG8_SCHED;
;             PG8_LDA(At, 0, 1); PG8_STAGE(PG8_SB(0, 0), b2, voffB); PG8_STAGE(PG8_SB(0, 1), b2 + hstep, voffB); PG8_STAGE(PG8_SA(0, 0), a2, voffA);
;             PG8_WAIT_V(8); PG8_WAIT_L(0); PG8_BAR; PG8_MMA(1, 0, At, B0); PG8_MMA(1, 1, At, B1); PG8_BAR; PG8_SCHED;
.LBB0_681:
	ds_read_b128 v[128:131], v162
	ds_read_b128 v[132:135], v162 offset:1024
	ds_read_b128 v[136:139], v162 offset:2048
	ds_read_b128 v[140:143], v162 offset:3072
	ds_read_b128 v[166:169], v163
	ds_read_b128 v[170:173], v163 offset:1024
	ds_read_b128 v[174:177], v163 offset:2048
	ds_read_b128 v[178:181], v163 offset:3072
	s_add_u32 s30, s28, 0xfff80080
	s_addc_u32 s31, s29, -1
	s_cmp_eq_u32 s54, 28
	s_cselect_b32 s35, s21, s31
	s_cselect_b32 s34, s50, s30
	s_cselect_b32 s31, s19, s53
	s_cselect_b32 s30, s51, s52
	v_lshl_add_u64 v[156:157], s[28:29], 0, v[148:149]
	s_add_i32 m0, s27, 0xc000
	ds_read_b128 v[182:185], v164
	ds_read_b128 v[188:191], v164 offset:1024
	ds_read_b128 v[192:195], v164 offset:2048
	ds_read_b128 v[196:199], v164 offset:3072
	ds_read_b128 v[200:203], v164 offset:4096
	ds_read_b128 v[204:207], v164 offset:5120
	ds_read_b128 v[208:211], v164 offset:6144
	ds_read_b128 v[212:215], v164 offset:7168
	global_load_lds_dwordx4 v[156:157], off
	v_lshl_add_u64 v[156:157], s[28:29], 0, v[150:151]
	s_add_i32 m0, s27, 0xe000
	s_nop 0
	global_load_lds_dwordx4 v[156:157], off
	s_waitcnt vmcnt(8)
	s_waitcnt lgkmcnt(0)
	s_barrier
	s_setprio 1
	s_waitcnt lgkmcnt(0)
	v_mfma_f32_16x16x32_bf16 v[124:127], v[128:131], v[182:185], v[124:127]
	v_mfma_f32_16x16x32_bf16 v[120:123], v[136:139], v[182:185], v[120:123]
	v_mfma_f32_16x16x32_bf16 v[112:115], v[128:131], v[192:195], v[112:115]
	v_mfma_f32_16x16x32_bf16 v[108:111], v[136:139], v[192:195], v[108:111]
	v_mfma_f32_16x16x32_bf16 v[96:99], v[128:131], v[200:203], v[96:99]
	v_mfma_f32_16x16x32_bf16 v[92:95], v[136:139], v[200:203], v[92:95]
	v_mfma_f32_16x16x32_bf16 v[80:83], v[128:131], v[208:211], v[80:83]
	v_mfma_f32_16x16x32_bf16 v[76:79], v[136:139], v[208:211], v[76:79]
	v_mfma_f32_16x16x32_bf16 v[124:127], v[132:135], v[188:191], v[124:127]
	v_mfma_f32_16x16x32_bf16 v[120:123], v[140:143], v[188:191], v[120:123]
	v_mfma_f32_16x16x32_bf16 v[112:115], v[132:135], v[196:199], v[112:115]
	v_mfma_f32_16x16x32_bf16 v[108:111], v[140:143], v[196:199], v[108:111]
	v_mfma_f32_16x16x32_bf16 v[96:99], v[132:135], v[204:207], v[96:99]
	v_mfma_f32_16x16x32_bf16 v[92:95], v[140:143], v[204:207], v[92:95]
	v_mfma_f32_16x16x32_bf16 v[80:83], v[132:135], v[212:215], v[80:83]
	v_mfma_f32_16x16x32_bf16 v[76:79], v[140:143], v[212:215], v[76:79]
	v_mfma_f32_16x16x32_bf16 v[116:119], v[166:169], v[182:185], v[116:119]
	v_mfma_f32_16x16x32_bf16 v[104:107], v[174:177], v[182:185], v[104:107]
	v_mfma_f32_16x16x32_bf16 v[100:103], v[166:169], v[192:195], v[100:103]
	v_mfma_f32_16x16x32_bf16 v[88:91], v[174:177], v[192:195], v[88:91]
	v_mfma_f32_16x16x32_bf16 v[84:87], v[166:169], v[200:203], v[84:87]
	v_mfma_f32_16x16x32_bf16 v[72:75], v[174:177], v[200:203], v[72:75]
	v_mfma_f32_16x16x32_bf16 v[68:71], v[166:169], v[208:211], v[68:71]
	v_mfma_f32_16x16x32_bf16 v[64:67], v[174:177], v[208:211], v[64:67]
	v_mfma_f32_16x16x32_bf16 v[116:119], v[170:173], v[188:191], v[116:119]
	v_mfma_f32_16x16x32_bf16 v[104:107], v[178:181], v[188:191], v[104:107]
	v_mfma_f32_16x16x32_bf16 v[100:103], v[170:173], v[196:199], v[100:103]
	v_mfma_f32_16x16x32_bf16 v[88:91], v[178:181], v[196:199], v[88:91]
	v_mfma_f32_16x16x32_bf16 v[84:87], v[170:173], v[204:207], v[84:87]
	v_mfma_f32_16x16x32_bf16 v[72:75], v[178:181], v[204:207], v[72:75]
	v_mfma_f32_16x16x32_bf16 v[68:71], v[170:173], v[212:215], v[68:71]
	v_mfma_f32_16x16x32_bf16 v[64:67], v[178:181], v[212:215], v[64:67]
	s_setprio 0
	s_barrier
	s_add_i32 s55, s47, s36
	v_lshl_add_u64 v[156:157], s[30:31], 0, v[144:145]
	s_mov_b32 m0, s55
	ds_read_b128 v[182:185], v164 offset:16384
	ds_read_b128 v[188:191], v164 offset:17408
	ds_read_b128 v[192:195], v164 offset:18432
	ds_read_b128 v[196:199], v164 offset:19456
	ds_read_b128 v[200:203], v164 offset:20480
	ds_read_b128 v[204:207], v164 offset:21504
	ds_read_b128 v[208:211], v164 offset:22528
	ds_read_b128 v[212:215], v164 offset:23552
	global_load_lds_dwordx4 v[156:157], off
	s_add_i32 m0, s55, 0x2000
	s_add_u32 s56, s30, 0x80000
	v_lshl_add_u64 v[216:217], s[30:31], 0, v[146:147]
	s_addc_u32 s57, s31, 0
	s_add_i32 s55, s48, s36
	global_load_lds_dwordx4 v[216:217], off
	v_lshl_add_u64 v[218:219], s[56:57], 0, v[144:145]
	s_mov_b32 m0, s55
	v_lshl_add_u64 v[220:221], s[34:35], 0, v[146:147]
	global_load_lds_dwordx4 v[218:219], off
	v_lshl_add_u64 v[218:219], s[56:57], 0, v[146:147]
	s_add_i32 m0, s55, 0x2000
	s_nop 0
	global_load_lds_dwordx4 v[218:219], off
	v_lshl_add_u64 v[218:219], s[34:35], 0, v[144:145]
	s_mov_b32 m0, s27
	s_nop 0
	global_load_lds_dwordx4 v[218:219], off
	s_mov_b32 m0, s37
	s_nop 0
	global_load_lds_dwordx4 v[220:221], off
	s_waitcnt vmcnt(8)
	s_waitcnt lgkmcnt(0)
	s_barrier
; #define PG8_STAGE(bufoff, gbase, voff) do { _Pragma("unroll") for (int _i = 0; _i < 2; ++_i) \
;         __builtin_amdgcn_global_load_lds((const unsigned*)((const char*)(gbase) + (voff)[_i]), (PG8_LAS unsigned*)(lds + (bufoff) + ldsw + _i * 8192), 16, 0, 0); } while (0)
; #define PG8_LDA(dst, b, h) do { _Pragma("unroll") for (int m = 0; m < 4; ++m) _Pragma("unroll") for (int k = 0; k < 2; ++k) dst[m][k] = *(const PG8_LAS bf16x8*)(lds + PG8_SA(b, h) + aoff + m * 2048 + k * 1024); } while (0)
; #define PG8_LDB(dst, b, h) do { _Pragma("unroll") for (int n = 0; n < 2; ++n) _Pragma("unroll") for (int k = 0; k < 2; ++k) dst[n][k] = *(const PG8_LAS bf16x8*)(lds + PG8_SB(b, h) + boff + n * 2048 + k * 1024); } while (0)
; #define PG8_MMA(ai, bj, At, Bt) do { __builtin_amdgcn_s_setprio(1); _Pragma("unroll") for (int m = 0; m < 4; ++m) _Pragma("unroll") for (int n = 0; n < 2; ++n) _Pragma("unroll") for (int k = 0; k < 2; ++k) \
;         acc[ai][bj][m][n] = __builtin_amdgcn_mfma_f32_16x16x32_bf16(Bt[n][k], At[m][k], acc[ai][bj][m][n], 0, 0, 0); __builtin_amdgcn_s_setprio(0); } while (0)
; #define PG8_WAIT_V(n) asm volatile("s_waitcnt vmcnt(" #n ")" ::: "memory")
; #define PG8_WAIT_L(n) asm volatile("s_waitcnt lgkmcnt(" #n ")" ::: "memory")
; #define PG8_BAR __builtin_amdgcn_s_barrier()
; #define PG8_SCHED __builtin_amdgcn_sched_barrier(0)
; template <class Epi, class Sched, bool ALIGN_EPI = false, bool SP2 = false>
; __device__ __forceinline__ void gemm_phase(PG8_LAS unsigned char* lds, const Gemm g, const Sched& S, const Epi& E) {
;     ...
;             PG8_WAIT_V(8); PG8_WAIT_L(0); PG8_BAR; PG8_MMA(1, 0, At, B0); PG8_MMA(1, 1, At, B1); PG8_BAR; PG8_SCHED;
;             PG8_LDB(B0, 1, 0); PG8_LDB(B1, 1, 1); PG8_SCHED; PG8_LDA(At, 1, 0); PG8_STAGE(PG8_SA(0, 1), a2 + hstep, voffA);
;             PG8_WAIT_V(8); PG8_WAIT_L(0); PG8_BAR; PG8_MMA(0, 0, At, B0); PG8_MMA(0, 1, At, B1); PG8_BAR; PG8_SCHED;
	s_setprio 1
	s_waitcnt lgkmcnt(0)
	v_mfma_f32_16x16x32_bf16 v[60:63], v[128:131], v[182:185], v[60:63]
	v_mfma_f32_16x16x32_bf16 v[56:59], v[136:139], v[182:185], v[56:59]
	v_mfma_f32_16x16x32_bf16 v[48:51], v[128:131], v[192:195], v[48:51]
	v_mfma_f32_16x16x32_bf16 v[44:47], v[136:139], v[192:195], v[44:47]
	v_mfma_f32_16x16x32_bf16 v[32:35], v[128:131], v[200:203], v[32:35]
	v_mfma_f32_16x16x32_bf16 v[28:31], v[136:139], v[200:203], v[28:31]
	v_mfma_f32_16x16x32_bf16 v[16:19], v[128:131], v[208:211], v[16:19]
	v_mfma_f32_16x16x32_bf16 v[12:15], v[136:139], v[208:211], v[12:15]
	v_mfma_f32_16x16x32_bf16 v[60:63], v[132:135], v[188:191], v[60:63]
	v_mfma_f32_16x16x32_bf16 v[56:59], v[140:143], v[188:191], v[56:59]
	v_mfma_f32_16x16x32_bf16 v[48:51], v[132:135], v[196:199], v[48:51]
	v_mfma_f32_16x16x32_bf16 v[44:47], v[140:143], v[196:199], v[44:47]
	v_mfma_f32_16x16x32_bf16 v[32:35], v[132:135], v[204:207], v[32:35]
	v_mfma_f32_16x16x32_bf16 v[28:31], v[140:143], v[204:207], v[28:31]
	v_mfma_f32_16x16x32_bf16 v[16:19], v[132:135], v[212:215], v[16:19]
	v_mfma_f32_16x16x32_bf16 v[12:15], v[140:143], v[212:215], v[12:15]
	v_mfma_f32_16x16x32_bf16 v[52:55], v[166:169], v[182:185], v[52:55]
	v_mfma_f32_16x16x32_bf16 v[40:43], v[174:177], v[182:185], v[40:43]
	v_mfma_f32_16x16x32_bf16 v[36:39], v[166:169], v[192:195], v[36:39]
	v_mfma_f32_16x16x32_bf16 v[24:27], v[174:177], v[192:195], v[24:27]
	v_mfma_f32_16x16x32_bf16 v[20:23], v[166:169], v[200:203], v[20:23]
	v_mfma_f32_16x16x32_bf16 v[8:11], v[174:177], v[200:203], v[8:11]
	v_mfma_f32_16x16x32_bf16 v[4:7], v[166:169], v[208:211], v[4:7]
	v_mfma_f32_16x16x32_bf16 v[0:3], v[174:177], v[208:211], v[0:3]
	v_mfma_f32_16x16x32_bf16 v[52:55], v[170:173], v[188:191], v[52:55]
	v_mfma_f32_16x16x32_bf16 v[40:43], v[178:181], v[188:191], v[40:43]
	v_mfma_f32_16x16x32_bf16 v[36:39], v[170:173], v[196:199], v[36:39]
	v_mfma_f32_16x16x32_bf16 v[24:27], v[178:181], v[196:199], v[24:27]
	v_mfma_f32_16x16x32_bf16 v[20:23], v[170:173], v[204:207], v[20:23]
	v_mfma_f32_16x16x32_bf16 v[8:11], v[178:181], v[204:207], v[8:11]
	v_mfma_f32_16x16x32_bf16 v[4:7], v[170:173], v[212:215], v[4:7]
	v_mfma_f32_16x16x32_bf16 v[0:3], v[178:181], v[212:215], v[0:3]
	s_setprio 0
	s_barrier
	s_add_i32 s55, 0, 0x18000
	s_add_i32 s56, 0, 0x1c000
	v_add_u32_e32 v140, s55, v159
	v_add_u32_e32 v165, s56, v159
	ds_read_b128 v[128:131], v140
	ds_read_b128 v[132:135], v140 offset:1024
	ds_read_b128 v[136:139], v140 offset:2048
	ds_read_b128 v[140:143], v140 offset:3072
	ds_read_b128 v[166:169], v165
	ds_read_b128 v[170:173], v165 offset:1024
	ds_read_b128 v[174:177], v165 offset:2048
	ds_read_b128 v[178:181], v165 offset:3072
	s_add_u32 s34, s34, 0x80000
	s_addc_u32 s35, s35, 0
	s_mov_b32 m0, s38
	v_lshl_add_u64 v[222:223], s[34:35], 0, v[144:145]
	ds_read_b128 v[182:185], v164 offset:32768
	ds_read_b128 v[188:191], v164 offset:33792
	ds_read_b128 v[192:195], v164 offset:34816
	ds_read_b128 v[196:199], v164 offset:35840
	ds_read_b128 v[200:203], v164 offset:36864
	ds_read_b128 v[204:207], v164 offset:37888
	ds_read_b128 v[208:211], v164 offset:38912
	ds_read_b128 v[212:215], v164 offset:39936
	global_load_lds_dwordx4 v[222:223], off
	v_lshl_add_u64 v[222:223], s[34:35], 0, v[146:147]
	s_mov_b32 m0, s39
	s_nop 0
	global_load_lds_dwordx4 v[222:223], off
	s_waitcnt vmcnt(8)
	s_waitcnt lgkmcnt(0)
	s_barrier
	s_setprio 1
	s_waitcnt lgkmcnt(0)
	v_mfma_f32_16x16x32_bf16 v[124:127], v[128:131], v[182:185], v[124:127]
	v_mfma_f32_16x16x32_bf16 v[120:123], v[136:139], v[182:185], v[120:123]
	v_mfma_f32_16x16x32_bf16 v[112:115], v[128:131], v[192:195], v[112:115]
	v_mfma_f32_16x16x32_bf16 v[108:111], v[136:139], v[192:195], v[108:111]
	v_mfma_f32_16x16x32_bf16 v[96:99], v[128:131], v[200:203], v[96:99]
	v_mfma_f32_16x16x32_bf16 v[92:95], v[136:139], v[200:203], v[92:95]
	v_mfma_f32_16x16x32_bf16 v[80:83], v[128:131], v[208:211], v[80:83]
	v_mfma_f32_16x16x32_bf16 v[76:79], v[136:139], v[208:211], v[76:79]
	v_mfma_f32_16x16x32_bf16 v[124:127], v[132:135], v[188:191], v[124:127]
	v_mfma_f32_16x16x32_bf16 v[120:123], v[140:143], v[188:191], v[120:123]
	v_mfma_f32_16x16x32_bf16 v[112:115], v[132:135], v[196:199], v[112:115]
	v_mfma_f32_16x16x32_bf16 v[108:111], v[140:143], v[196:199], v[108:111]
	v_mfma_f32_16x16x32_bf16 v[96:99], v[132:135], v[204:207], v[96:99]
	v_mfma_f32_16x16x32_bf16 v[92:95], v[140:143], v[204:207], v[92:95]
	v_mfma_f32_16x16x32_bf16 v[80:83], v[132:135], v[212:215], v[80:83]
	v_mfma_f32_16x16x32_bf16 v[76:79], v[140:143], v[212:215], v[76:79]
	v_mfma_f32_16x16x32_bf16 v[116:119], v[166:169], v[182:185], v[116:119]
	v_mfma_f32_16x16x32_bf16 v[104:107], v[174:177], v[182:185], v[104:107]
	v_mfma_f32_16x16x32_bf16 v[100:103], v[166:169], v[192:195], v[100:103]
	v_mfma_f32_16x16x32_bf16 v[88:91], v[174:177], v[192:195], v[88:91]
	v_mfma_f32_16x16x32_bf16 v[84:87], v[166:169], v[200:203], v[84:87]
	v_mfma_f32_16x16x32_bf16 v[72:75], v[174:177], v[200:203], v[72:75]
	v_mfma_f32_16x16x32_bf16 v[68:71], v[166:169], v[208:211], v[68:71]
	v_mfma_f32_16x16x32_bf16 v[64:67], v[174:177], v[208:211], v[64:67]
	v_mfma_f32_16x16x32_bf16 v[116:119], v[170:173], v[188:191], v[116:119]
	v_mfma_f32_16x16x32_bf16 v[104:107], v[178:181], v[188:191], v[104:107]
	v_mfma_f32_16x16x32_bf16 v[100:103], v[170:173], v[196:199], v[100:103]
	v_mfma_f32_16x16x32_bf16 v[88:91], v[178:181], v[196:199], v[88:91]
	v_mfma_f32_16x16x32_bf16 v[84:87], v[170:173], v[204:207], v[84:87]
	v_mfma_f32_16x16x32_bf16 v[72:75], v[178:181], v[204:207], v[72:75]
	v_mfma_f32_16x16x32_bf16 v[68:71], v[170:173], v[212:215], v[68:71]
	v_mfma_f32_16x16x32_bf16 v[64:67], v[178:181], v[212:215], v[64:67]
	s_setprio 0
	s_barrier
; #define PG8_STAGE(bufoff, gbase, voff) do { _Pragma("unroll") for (int _i = 0; _i < 2; ++_i) \
;         __builtin_amdgcn_global_load_lds((const unsigned*)((const char*)(gbase) + (voff)[_i]), (PG8_LAS unsigned*)(lds + (bufoff) + ldsw + _i * 8192), 16, 0, 0); } while (0)
; #define PG8_LDA(dst, b, h) do { _Pragma("unroll") for (int m = 0; m < 4; ++m) _Pragma("unroll") for (int k = 0; k < 2; ++k) dst[m][k] = *(const PG8_LAS bf16x8*)(lds + PG8_SA(b, h) + aoff + m * 2048 + k * 1024); } while (0)
; #define PG8_MMA(ai, bj, At, Bt) do { __builtin_amdgcn_s_setprio(1); _Pragma("unroll") for (int m = 0; m < 4; ++m) _Pragma("unroll") for (int n = 0; n < 2; ++n) _Pragma("unroll") for (int k = 0; k < 2; ++k) \
;         acc[ai][bj][m][n] = __builtin_amdgcn_mfma_f32_16x16x32_bf16(Bt[n][k], At[m][k], acc[ai][bj][m][n], 0, 0, 0); __builtin_amdgcn_s_setprio(0); } while (0)
; #define PG8_WAIT_V(n) asm volatile("s_waitcnt vmcnt(" #n ")" ::: "memory")
; #define PG8_WAIT_L(n) asm volatile("s_waitcnt lgkmcnt(" #n ")" ::: "memory")
; #define PG8_BAR __builtin_amdgcn_s_barrier()
; #define PG8_SCHED __builtin_amdgcn_sched_barrier(0)
; template <class Epi, class Sched, bool ALIGN_EPI = false, bool SP2 = false>
; __device__ __forceinline__ void gemm_phase(PG8_LAS unsigned char* lds, const Gemm g, const Sched& S, const Epi& E) {
;     ...
;             PG8_LDA(At, 1, 1); PG8_STAGE(PG8_SB(1, 0), b3, voffB); PG8_STAGE(PG8_SB(1, 1), b3 + hstep, voffB); PG8_STAGE(PG8_SA(1, 0), a3, voffA);
;             PG8_WAIT_V(8); PG8_WAIT_L(0); PG8_BAR; PG8_MMA(1, 0, At, B0); PG8_MMA(1, 1, At, B1); PG8_BAR; PG8_SCHED;
;     ...
;         if constexpr (ALIGN_EPI) { if (wr == 0) PG8_BAR; }
	s_add_i32 s34, s55, s36
	v_lshl_add_u64 v[156:157], v[156:157], 0, s[6:7]
	s_mov_b32 m0, s34
	ds_read_b128 v[182:185], v164 offset:49152
	ds_read_b128 v[188:191], v164 offset:50176
	ds_read_b128 v[192:195], v164 offset:51200
	ds_read_b128 v[196:199], v164 offset:52224
	ds_read_b128 v[200:203], v164 offset:53248
	ds_read_b128 v[204:207], v164 offset:54272
	ds_read_b128 v[208:211], v164 offset:55296
	ds_read_b128 v[212:215], v164 offset:56320
	global_load_lds_dwordx4 v[156:157], off
	s_add_i32 m0, s34, 0x2000
	s_add_u32 s30, s30, 0x80080
	v_lshl_add_u64 v[156:157], v[216:217], 0, s[6:7]
	s_addc_u32 s31, s31, 0
	s_add_i32 s34, s56, s36
	global_load_lds_dwordx4 v[156:157], off
	v_lshl_add_u64 v[156:157], s[30:31], 0, v[144:145]
	s_mov_b32 m0, s34
	s_nop 0
	global_load_lds_dwordx4 v[156:157], off
	v_lshl_add_u64 v[156:157], s[30:31], 0, v[146:147]
	s_add_i32 m0, s34, 0x2000
	s_nop 0
	global_load_lds_dwordx4 v[156:157], off
	v_lshl_add_u64 v[156:157], v[218:219], 0, s[6:7]
	s_mov_b32 m0, s43
	s_nop 0
	global_load_lds_dwordx4 v[156:157], off
	v_lshl_add_u64 v[156:157], v[220:221], 0, s[6:7]
	s_mov_b32 m0, s44
	s_nop 0
	global_load_lds_dwordx4 v[156:157], off
	s_waitcnt vmcnt(8)
	s_waitcnt lgkmcnt(0)
	s_barrier
	s_setprio 1
	s_waitcnt lgkmcnt(0)
	v_mfma_f32_16x16x32_bf16 v[60:63], v[128:131], v[182:185], v[60:63]
	v_mfma_f32_16x16x32_bf16 v[56:59], v[136:139], v[182:185], v[56:59]
	v_mfma_f32_16x16x32_bf16 v[48:51], v[128:131], v[192:195], v[48:51]
	v_mfma_f32_16x16x32_bf16 v[44:47], v[136:139], v[192:195], v[44:47]
	v_mfma_f32_16x16x32_bf16 v[32:35], v[128:131], v[200:203], v[32:35]
	v_mfma_f32_16x16x32_bf16 v[28:31], v[136:139], v[200:203], v[28:31]
	v_mfma_f32_16x16x32_bf16 v[16:19], v[128:131], v[208:211], v[16:19]
	v_mfma_f32_16x16x32_bf16 v[12:15], v[136:139], v[208:211], v[12:15]
	v_mfma_f32_16x16x32_bf16 v[60:63], v[132:135], v[188:191], v[60:63]
	v_mfma_f32_16x16x32_bf16 v[56:59], v[140:143], v[188:191], v[56:59]
	v_mfma_f32_16x16x32_bf16 v[48:51], v[132:135], v[196:199], v[48:51]
	v_mfma_f32_16x16x32_bf16 v[44:47], v[140:143], v[196:199], v[44:47]
	v_mfma_f32_16x16x32_bf16 v[32:35], v[132:135], v[204:207], v[32:35]
	v_mfma_f32_16x16x32_bf16 v[28:31], v[140:143], v[204:207], v[28:31]
	v_mfma_f32_16x16x32_bf16 v[16:19], v[132:135], v[212:215], v[16:19]
	v_mfma_f32_16x16x32_bf16 v[12:15], v[140:143], v[212:215], v[12:15]
	v_mfma_f32_16x16x32_bf16 v[52:55], v[166:169], v[182:185], v[52:55]
	v_mfma_f32_16x16x32_bf16 v[40:43], v[174:177], v[182:185], v[40:43]
	v_mfma_f32_16x16x32_bf16 v[36:39], v[166:169], v[192:195], v[36:39]
	v_mfma_f32_16x16x32_bf16 v[24:27], v[174:177], v[192:195], v[24:27]
	v_mfma_f32_16x16x32_bf16 v[20:23], v[166:169], v[200:203], v[20:23]
	v_mfma_f32_16x16x32_bf16 v[8:11], v[174:177], v[200:203], v[8:11]
	v_mfma_f32_16x16x32_bf16 v[4:7], v[166:169], v[208:211], v[4:7]
	v_mfma_f32_16x16x32_bf16 v[0:3], v[174:177], v[208:211], v[0:3]
	v_mfma_f32_16x16x32_bf16 v[52:55], v[170:173], v[188:191], v[52:55]
	v_mfma_f32_16x16x32_bf16 v[40:43], v[178:181], v[188:191], v[40:43]
	v_mfma_f32_16x16x32_bf16 v[36:39], v[170:173], v[196:199], v[36:39]
	v_mfma_f32_16x16x32_bf16 v[24:27], v[178:181], v[196:199], v[24:27]
	v_mfma_f32_16x16x32_bf16 v[20:23], v[170:173], v[204:207], v[20:23]
	v_mfma_f32_16x16x32_bf16 v[8:11], v[178:181], v[204:207], v[8:11]
	v_mfma_f32_16x16x32_bf16 v[4:7], v[170:173], v[212:215], v[4:7]
	v_mfma_f32_16x16x32_bf16 v[0:3], v[178:181], v[212:215], v[0:3]
	s_setprio 0
	s_barrier
	s_add_i32 s54, s54, 2
	s_add_u32 s28, s28, 0x100
	s_addc_u32 s29, s29, 0
	s_add_u32 s52, s52, 0x100
	s_addc_u32 s53, s53, 0
	s_cmp_gt_u32 s54, 29
	s_cbranch_scc0 .LBB0_681
	s_and_b64 vcc, exec, s[8:9]
	s_cbranch_vccz .LBB0_684
	s_barrier

; #define PG8_STAGE(bufoff, gbase, voff) do { _Pragma("unroll") for (int _i = 0; _i < 2; ++_i) \
;         __builtin_amdgcn_global_load_lds((const unsigned*)((const char*)(gbase) + (voff)[_i]), (PG8_LAS unsigned*)(lds + (bufoff) + ldsw + _i * 8192), 16, 0, 0); } while (0)
; #define PG8_LDA(dst, b, h) do { _Pragma("unroll") for (int m = 0; m < 4; ++m) _Pragma("unroll") for (int k = 0; k < 2; ++k) dst[m][k] = *(const PG8_LAS bf16x8*)(lds + PG8_SA(b, h) + aoff + m * 2048 + k * 1024); } while (0)
; #define PG8_LDB(dst, b, h) do { _Pragma("unroll") for (int n = 0; n < 2; ++n) _Pragma("unroll") for (int k = 0; k < 2; ++k) dst[n][k] = *(const PG8_LAS bf16x8*)(lds + PG8_SB(b, h) + boff + n * 2048 + k * 1024); } while (0)
; #define PG8_WAIT_V(n) asm volatile("s_waitcnt vmcnt(" #n ")" ::: "memory")
; #define PG8_WAIT_L(n) asm volatile("s_waitcnt lgkmcnt(" #n ")" ::: "memory")
; #define PG8_BAR __builtin_amdgcn_s_barrier()
; #define PG8_SCHED __builtin_amdgcn_sched_barrier(0)
; template <class Epi, class Sched, bool ALIGN_EPI = false, bool SP2 = false>
; __device__ __forceinline__ void gemm_phase(PG8_LAS unsigned char* lds, const Gemm g, const Sched& S, const Epi& E) {
;     ...
;         const char* nA = has_next ? (const char*)g.A + (size_t)nxt.pm * tstep : cA; const char* nB = has_next ? (const char*)g.Bt + (size_t)nxt.pn * tstep : cB;
;         for (int t = 0; t < nt; t += 2) {
;             const bool last = (t == nt - 2);
;             const char* a1 = cA + (size_t)(t + 1) * kstep;
;             const char* a2 = last ? nA : cA + (size_t)(t + 2) * kstep; const char* b2 = last ? nB : cB + (size_t)(t + 2) * kstep;
;             const char* a3 = a2 + kstep; const char* b3 = b2 + kstep;
;             if (last && has_next) S.a_ready(nxt);
;             if constexpr (SP2) {
;             PG8_LDB(B0, 0, 0); PG8_LDB(B1, 0, 1); PG8_SCHED; PG8_LDA(At, 0, 0); PG8_STAGE(PG8_SA(1, 1), a1 + hstep, voffA);
;             PG8_WAIT_V(8); PG8_WAIT_L(0); PG8_BAR; PG8_MMA(0, 0, At, B0); PG8_MMA(0, 1, At, B1); PG8_BAR; PG8_SCHED;
;             PG8_LDA(At, 0, 1); PG8_STAGE(PG8_SB(0, 0), b2, voffB); PG8_STAGE(PG8_SB(0, 1), b2 + hstep, voffB); PG8_STAGE(PG8_SA(0, 0), a2, voffA);
;             PG8_WAIT_V(8); PG8_WAIT_L(0); PG8_BAR; PG8_MMA(1, 0, At, B0); PG8_MMA(1, 1, At, B1); PG8_BAR; PG8_SCHED;
.LBB0_814:
	ds_read_b128 v[152:155], v149
	ds_read_b128 v[156:159], v149 offset:1024
	ds_read_b128 v[160:163], v149 offset:2048
	ds_read_b128 v[164:167], v149 offset:3072
	ds_read_b128 v[168:171], v150
	ds_read_b128 v[172:175], v150 offset:1024
	ds_read_b128 v[176:179], v150 offset:2048
	ds_read_b128 v[180:183], v150 offset:3072
	s_add_u32 s30, s28, 0xfff80080
	s_addc_u32 s31, s29, -1
	s_cmp_eq_u32 s56, 28
	s_cselect_b32 s35, s21, s31
	s_cselect_b32 s34, s52, s30
	s_cselect_b32 s31, s19, s55
	s_cselect_b32 s30, s53, s54
	v_lshl_add_u64 v[144:145], s[28:29], 0, v[136:137]
	s_add_i32 m0, s27, 0xc000
	ds_read_b128 v[188:191], v151
	ds_read_b128 v[192:195], v151 offset:1024
	ds_read_b128 v[196:199], v151 offset:2048
	ds_read_b128 v[200:203], v151 offset:3072
	ds_read_b128 v[204:207], v151 offset:4096
	ds_read_b128 v[208:211], v151 offset:5120
	ds_read_b128 v[212:215], v151 offset:6144
	ds_read_b128 v[216:219], v151 offset:7168
	global_load_lds_dwordx4 v[144:145], off
	v_lshl_add_u64 v[144:145], s[28:29], 0, v[138:139]
	s_add_i32 m0, s27, 0xe000
	s_nop 0
	global_load_lds_dwordx4 v[144:145], off
	s_waitcnt vmcnt(8)
	s_waitcnt lgkmcnt(0)
	s_barrier
	s_setprio 1
	s_waitcnt lgkmcnt(0)
	v_mfma_f32_16x16x32_bf16 v[124:127], v[152:155], v[188:191], v[124:127]
	v_mfma_f32_16x16x32_bf16 v[120:123], v[160:163], v[188:191], v[120:123]
	v_mfma_f32_16x16x32_bf16 v[112:115], v[152:155], v[196:199], v[112:115]
	v_mfma_f32_16x16x32_bf16 v[104:107], v[160:163], v[196:199], v[104:107]
	v_mfma_f32_16x16x32_bf16 v[96:99], v[152:155], v[204:207], v[96:99]
	v_mfma_f32_16x16x32_bf16 v[88:91], v[160:163], v[204:207], v[88:91]
	v_mfma_f32_16x16x32_bf16 v[80:83], v[152:155], v[212:215], v[80:83]
	v_mfma_f32_16x16x32_bf16 v[72:75], v[160:163], v[212:215], v[72:75]
	v_mfma_f32_16x16x32_bf16 v[124:127], v[156:159], v[192:195], v[124:127]
	v_mfma_f32_16x16x32_bf16 v[120:123], v[164:167], v[192:195], v[120:123]
	v_mfma_f32_16x16x32_bf16 v[112:115], v[156:159], v[200:203], v[112:115]
	v_mfma_f32_16x16x32_bf16 v[104:107], v[164:167], v[200:203], v[104:107]
	v_mfma_f32_16x16x32_bf16 v[96:99], v[156:159], v[208:211], v[96:99]
	v_mfma_f32_16x16x32_bf16 v[88:91], v[164:167], v[208:211], v[88:91]
	v_mfma_f32_16x16x32_bf16 v[80:83], v[156:159], v[216:219], v[80:83]
	v_mfma_f32_16x16x32_bf16 v[72:75], v[164:167], v[216:219], v[72:75]
	v_mfma_f32_16x16x32_bf16 v[116:119], v[168:171], v[188:191], v[116:119]
	v_mfma_f32_16x16x32_bf16 v[108:111], v[176:179], v[188:191], v[108:111]
	v_mfma_f32_16x16x32_bf16 v[100:103], v[168:171], v[196:199], v[100:103]
	v_mfma_f32_16x16x32_bf16 v[92:95], v[176:179], v[196:199], v[92:95]
	v_mfma_f32_16x16x32_bf16 v[84:87], v[168:171], v[204:207], v[84:87]
	v_mfma_f32_16x16x32_bf16 v[76:79], v[176:179], v[204:207], v[76:79]
	v_mfma_f32_16x16x32_bf16 v[68:71], v[168:171], v[212:215], v[68:71]
	v_mfma_f32_16x16x32_bf16 v[64:67], v[176:179], v[212:215], v[64:67]
	v_mfma_f32_16x16x32_bf16 v[116:119], v[172:175], v[192:195], v[116:119]
	v_mfma_f32_16x16x32_bf16 v[108:111], v[180:183], v[192:195], v[108:111]
	v_mfma_f32_16x16x32_bf16 v[100:103], v[172:175], v[200:203], v[100:103]
	v_mfma_f32_16x16x32_bf16 v[92:95], v[180:183], v[200:203], v[92:95]
	v_mfma_f32_16x16x32_bf16 v[84:87], v[172:175], v[208:211], v[84:87]
	v_mfma_f32_16x16x32_bf16 v[76:79], v[180:183], v[208:211], v[76:79]
	v_mfma_f32_16x16x32_bf16 v[68:71], v[172:175], v[216:219], v[68:71]
	v_mfma_f32_16x16x32_bf16 v[64:67], v[180:183], v[216:219], v[64:67]
	s_setprio 0
	s_barrier
	s_add_i32 s57, s45, s36
	v_lshl_add_u64 v[144:145], s[30:31], 0, v[130:131]
	s_mov_b32 m0, s57
	ds_read_b128 v[188:191], v151 offset:16384
	ds_read_b128 v[192:195], v151 offset:17408
	ds_read_b128 v[196:199], v151 offset:18432
	ds_read_b128 v[200:203], v151 offset:19456
	ds_read_b128 v[204:207], v151 offset:20480
	ds_read_b128 v[208:211], v151 offset:21504
	ds_read_b128 v[212:215], v151 offset:22528
	ds_read_b128 v[216:219], v151 offset:23552
	global_load_lds_dwordx4 v[144:145], off
	s_add_i32 m0, s57, 0x2000
	s_add_u32 s58, s30, 0x80000
	v_lshl_add_u64 v[184:185], s[30:31], 0, v[134:135]
	s_addc_u32 s59, s31, 0
	s_add_i32 s57, s46, s36
	global_load_lds_dwordx4 v[184:185], off
	v_lshl_add_u64 v[220:221], s[58:59], 0, v[130:131]
	s_mov_b32 m0, s57
	v_lshl_add_u64 v[222:223], s[34:35], 0, v[132:133]
	global_load_lds_dwordx4 v[220:221], off
	v_lshl_add_u64 v[220:221], s[58:59], 0, v[134:135]
	s_add_i32 m0, s57, 0x2000
	s_nop 0
	global_load_lds_dwordx4 v[220:221], off
	v_lshl_add_u64 v[220:221], s[34:35], 0, v[128:129]
	s_mov_b32 m0, s27
	s_nop 0
	global_load_lds_dwordx4 v[220:221], off
	s_mov_b32 m0, s37
	s_nop 0
	global_load_lds_dwordx4 v[222:223], off
	s_waitcnt vmcnt(8)
	s_waitcnt lgkmcnt(0)
	s_barrier
; #define PG8_STAGE(bufoff, gbase, voff) do { _Pragma("unroll") for (int _i = 0; _i < 2; ++_i) \
;         __builtin_amdgcn_global_load_lds((const unsigned*)((const char*)(gbase) + (voff)[_i]), (PG8_LAS unsigned*)(lds + (bufoff) + ldsw + _i * 8192), 16, 0, 0); } while (0)
; #define PG8_LDA(dst, b, h) do { _Pragma("unroll") for (int m = 0; m < 4; ++m) _Pragma("unroll") for (int k = 0; k < 2; ++k) dst[m][k] = *(const PG8_LAS bf16x8*)(lds + PG8_SA(b, h) + aoff + m * 2048 + k * 1024); } while (0)
; #define PG8_LDB(dst, b, h) do { _Pragma("unroll") for (int n = 0; n < 2; ++n) _Pragma("unroll") for (int k = 0; k < 2; ++k) dst[n][k] = *(const PG8_LAS bf16x8*)(lds + PG8_SB(b, h) + boff + n * 2048 + k * 1024); } while (0)
; #define PG8_MMA(ai, bj, At, Bt) do { __builtin_amdgcn_s_setprio(1); _Pragma("unroll") for (int m = 0; m < 4; ++m) _Pragma("unroll") for (int n = 0; n < 2; ++n) _Pragma("unroll") for (int k = 0; k < 2; ++k) \
;         acc[ai][bj][m][n] = __builtin_amdgcn_mfma_f32_16x16x32_bf16(Bt[n][k], At[m][k], acc[ai][bj][m][n], 0, 0, 0); __builtin_amdgcn_s_setprio(0); } while (0)
; #define PG8_WAIT_V(n) asm volatile("s_waitcnt vmcnt(" #n ")" ::: "memory")
; #define PG8_WAIT_L(n) asm volatile("s_waitcnt lgkmcnt(" #n ")" ::: "memory")
; #define PG8_BAR __builtin_amdgcn_s_barrier()
; #define PG8_SCHED __builtin_amdgcn_sched_barrier(0)
; template <class Epi, class Sched, bool ALIGN_EPI = false, bool SP2 = false>
; __device__ __forceinline__ void gemm_phase(PG8_LAS unsigned char* lds, const Gemm g, const Sched& S, const Epi& E) {
;     ...
;             PG8_WAIT_V(8); PG8_WAIT_L(0); PG8_BAR; PG8_MMA(1, 0, At, B0); PG8_MMA(1, 1, At, B1); PG8_BAR; PG8_SCHED;
;             PG8_LDB(B0, 1, 0); PG8_LDB(B1, 1, 1); PG8_SCHED; PG8_LDA(At, 1, 0); PG8_STAGE(PG8_SA(0, 1), a2 + hstep, voffA);
;             PG8_WAIT_V(8); PG8_WAIT_L(0); PG8_BAR; PG8_MMA(0, 0, At, B0); PG8_MMA(0, 1, At, B1); PG8_BAR; PG8_SCHED;
	s_setprio 1
	s_waitcnt lgkmcnt(0)
	v_mfma_f32_16x16x32_bf16 v[60:63], v[152:155], v[188:191], v[60:63]
	v_mfma_f32_16x16x32_bf16 v[56:59], v[160:163], v[188:191], v[56:59]
	v_mfma_f32_16x16x32_bf16 v[48:51], v[152:155], v[196:199], v[48:51]
	v_mfma_f32_16x16x32_bf16 v[40:43], v[160:163], v[196:199], v[40:43]
	v_mfma_f32_16x16x32_bf16 v[32:35], v[152:155], v[204:207], v[32:35]
	v_mfma_f32_16x16x32_bf16 v[24:27], v[160:163], v[204:207], v[24:27]
	v_mfma_f32_16x16x32_bf16 v[16:19], v[152:155], v[212:215], v[16:19]
	v_mfma_f32_16x16x32_bf16 v[8:11], v[160:163], v[212:215], v[8:11]
	v_mfma_f32_16x16x32_bf16 v[60:63], v[156:159], v[192:195], v[60:63]
	v_mfma_f32_16x16x32_bf16 v[56:59], v[164:167], v[192:195], v[56:59]
	v_mfma_f32_16x16x32_bf16 v[48:51], v[156:159], v[200:203], v[48:51]
	v_mfma_f32_16x16x32_bf16 v[40:43], v[164:167], v[200:203], v[40:43]
	v_mfma_f32_16x16x32_bf16 v[32:35], v[156:159], v[208:211], v[32:35]
	v_mfma_f32_16x16x32_bf16 v[24:27], v[164:167], v[208:211], v[24:27]
	v_mfma_f32_16x16x32_bf16 v[16:19], v[156:159], v[216:219], v[16:19]
	v_mfma_f32_16x16x32_bf16 v[8:11], v[164:167], v[216:219], v[8:11]
	v_mfma_f32_16x16x32_bf16 v[52:55], v[168:171], v[188:191], v[52:55]
	v_mfma_f32_16x16x32_bf16 v[44:47], v[176:179], v[188:191], v[44:47]
	v_mfma_f32_16x16x32_bf16 v[36:39], v[168:171], v[196:199], v[36:39]
	v_mfma_f32_16x16x32_bf16 v[28:31], v[176:179], v[196:199], v[28:31]
	v_mfma_f32_16x16x32_bf16 v[20:23], v[168:171], v[204:207], v[20:23]
	v_mfma_f32_16x16x32_bf16 v[12:15], v[176:179], v[204:207], v[12:15]
	v_mfma_f32_16x16x32_bf16 v[4:7], v[168:171], v[212:215], v[4:7]
	v_mfma_f32_16x16x32_bf16 v[0:3], v[176:179], v[212:215], v[0:3]
	v_mfma_f32_16x16x32_bf16 v[52:55], v[172:175], v[192:195], v[52:55]
	v_mfma_f32_16x16x32_bf16 v[44:47], v[180:183], v[192:195], v[44:47]
	v_mfma_f32_16x16x32_bf16 v[36:39], v[172:175], v[200:203], v[36:39]
	v_mfma_f32_16x16x32_bf16 v[28:31], v[180:183], v[200:203], v[28:31]
	v_mfma_f32_16x16x32_bf16 v[20:23], v[172:175], v[208:211], v[20:23]
	v_mfma_f32_16x16x32_bf16 v[12:15], v[180:183], v[208:211], v[12:15]
	v_mfma_f32_16x16x32_bf16 v[4:7], v[172:175], v[216:219], v[4:7]
	v_mfma_f32_16x16x32_bf16 v[0:3], v[180:183], v[216:219], v[0:3]
	s_setprio 0
	s_barrier
	s_add_i32 s57, 0, 0x18000
	s_add_i32 s58, 0, 0x1c000
	v_add_u32_e32 v164, s57, v147
	v_add_u32_e32 v180, s58, v147
	ds_read_b128 v[152:155], v164
	ds_read_b128 v[156:159], v164 offset:1024
	ds_read_b128 v[160:163], v164 offset:2048
	ds_read_b128 v[164:167], v164 offset:3072
	ds_read_b128 v[168:171], v180
	ds_read_b128 v[172:175], v180 offset:1024
	ds_read_b128 v[176:179], v180 offset:2048
	ds_read_b128 v[180:183], v180 offset:3072
	s_add_u32 s34, s34, 0x80000
	s_addc_u32 s35, s35, 0
	s_mov_b32 m0, s38
	v_lshl_add_u64 v[224:225], s[34:35], 0, v[128:129]
	ds_read_b128 v[188:191], v151 offset:32768
	ds_read_b128 v[192:195], v151 offset:33792
	ds_read_b128 v[196:199], v151 offset:34816
	ds_read_b128 v[200:203], v151 offset:35840
	ds_read_b128 v[204:207], v151 offset:36864
	ds_read_b128 v[208:211], v151 offset:37888
	ds_read_b128 v[212:215], v151 offset:38912
	ds_read_b128 v[216:219], v151 offset:39936
	global_load_lds_dwordx4 v[224:225], off
	v_lshl_add_u64 v[224:225], s[34:35], 0, v[132:133]
	s_mov_b32 m0, s39
	s_nop 0
	global_load_lds_dwordx4 v[224:225], off
	s_waitcnt vmcnt(8)
	s_waitcnt lgkmcnt(0)
	s_barrier
	s_setprio 1
	s_waitcnt lgkmcnt(0)
	v_mfma_f32_16x16x32_bf16 v[124:127], v[152:155], v[188:191], v[124:127]
	v_mfma_f32_16x16x32_bf16 v[120:123], v[160:163], v[188:191], v[120:123]
	v_mfma_f32_16x16x32_bf16 v[112:115], v[152:155], v[196:199], v[112:115]
	v_mfma_f32_16x16x32_bf16 v[104:107], v[160:163], v[196:199], v[104:107]
	v_mfma_f32_16x16x32_bf16 v[96:99], v[152:155], v[204:207], v[96:99]
	v_mfma_f32_16x16x32_bf16 v[88:91], v[160:163], v[204:207], v[88:91]
	v_mfma_f32_16x16x32_bf16 v[80:83], v[152:155], v[212:215], v[80:83]
	v_mfma_f32_16x16x32_bf16 v[72:75], v[160:163], v[212:215], v[72:75]
	v_mfma_f32_16x16x32_bf16 v[124:127], v[156:159], v[192:195], v[124:127]
	v_mfma_f32_16x16x32_bf16 v[120:123], v[164:167], v[192:195], v[120:123]
	v_mfma_f32_16x16x32_bf16 v[112:115], v[156:159], v[200:203], v[112:115]
	v_mfma_f32_16x16x32_bf16 v[104:107], v[164:167], v[200:203], v[104:107]
	v_mfma_f32_16x16x32_bf16 v[96:99], v[156:159], v[208:211], v[96:99]
	v_mfma_f32_16x16x32_bf16 v[88:91], v[164:167], v[208:211], v[88:91]
	v_mfma_f32_16x16x32_bf16 v[80:83], v[156:159], v[216:219], v[80:83]
	v_mfma_f32_16x16x32_bf16 v[72:75], v[164:167], v[216:219], v[72:75]
	v_mfma_f32_16x16x32_bf16 v[116:119], v[168:171], v[188:191], v[116:119]
	v_mfma_f32_16x16x32_bf16 v[108:111], v[176:179], v[188:191], v[108:111]
	v_mfma_f32_16x16x32_bf16 v[100:103], v[168:171], v[196:199], v[100:103]
	v_mfma_f32_16x16x32_bf16 v[92:95], v[176:179], v[196:199], v[92:95]
	v_mfma_f32_16x16x32_bf16 v[84:87], v[168:171], v[204:207], v[84:87]
	v_mfma_f32_16x16x32_bf16 v[76:79], v[176:179], v[204:207], v[76:79]
	v_mfma_f32_16x16x32_bf16 v[68:71], v[168:171], v[212:215], v[68:71]
	v_mfma_f32_16x16x32_bf16 v[64:67], v[176:179], v[212:215], v[64:67]
	v_mfma_f32_16x16x32_bf16 v[116:119], v[172:175], v[192:195], v[116:119]
	v_mfma_f32_16x16x32_bf16 v[108:111], v[180:183], v[192:195], v[108:111]
	v_mfma_f32_16x16x32_bf16 v[100:103], v[172:175], v[200:203], v[100:103]
	v_mfma_f32_16x16x32_bf16 v[92:95], v[180:183], v[200:203], v[92:95]
	v_mfma_f32_16x16x32_bf16 v[84:87], v[172:175], v[208:211], v[84:87]
	v_mfma_f32_16x16x32_bf16 v[76:79], v[180:183], v[208:211], v[76:79]
	v_mfma_f32_16x16x32_bf16 v[68:71], v[172:175], v[216:219], v[68:71]
	v_mfma_f32_16x16x32_bf16 v[64:67], v[180:183], v[216:219], v[64:67]
	s_setprio 0
	s_barrier
; #define PG8_STAGE(bufoff, gbase, voff) do { _Pragma("unroll") for (int _i = 0; _i < 2; ++_i) \
;         __builtin_amdgcn_global_load_lds((const unsigned*)((const char*)(gbase) + (voff)[_i]), (PG8_LAS unsigned*)(lds + (bufoff) + ldsw + _i * 8192), 16, 0, 0); } while (0)
; #define PG8_LDA(dst, b, h) do { _Pragma("unroll") for (int m = 0; m < 4; ++m) _Pragma("unroll") for (int k = 0; k < 2; ++k) dst[m][k] = *(const PG8_LAS bf16x8*)(lds + PG8_SA(b, h) + aoff + m * 2048 + k * 1024); } while (0)
; #define PG8_MMA(ai, bj, At, Bt) do { __builtin_amdgcn_s_setprio(1); _Pragma("unroll") for (int m = 0; m < 4; ++m) _Pragma("unroll") for (int n = 0; n < 2; ++n) _Pragma("unroll") for (int k = 0; k < 2; ++k) \
;         acc[ai][bj][m][n] = __builtin_amdgcn_mfma_f32_16x16x32_bf16(Bt[n][k], At[m][k], acc[ai][bj][m][n], 0, 0, 0); __builtin_amdgcn_s_setprio(0); } while (0)
; #define PG8_WAIT_V(n) asm volatile("s_waitcnt vmcnt(" #n ")" ::: "memory")
; #define PG8_WAIT_L(n) asm volatile("s_waitcnt lgkmcnt(" #n ")" ::: "memory")
; #define PG8_BAR __builtin_amdgcn_s_barrier()
; #define PG8_SCHED __builtin_amdgcn_sched_barrier(0)
; template <class Epi, class Sched, bool ALIGN_EPI = false, bool SP2 = false>
; __device__ __forceinline__ void gemm_phase(PG8_LAS unsigned char* lds, const Gemm g, const Sched& S, const Epi& E) {
;     ...
;             PG8_LDA(At, 1, 1); PG8_STAGE(PG8_SB(1, 0), b3, voffB); PG8_STAGE(PG8_SB(1, 1), b3 + hstep, voffB); PG8_STAGE(PG8_SA(1, 0), a3, voffA);
;             PG8_WAIT_V(8); PG8_WAIT_L(0); PG8_BAR; PG8_MMA(1, 0, At, B0); PG8_MMA(1, 1, At, B1); PG8_BAR; PG8_SCHED;
;     ...
;         if constexpr (ALIGN_EPI) { if (wr == 0) PG8_BAR; }
	s_add_i32 s34, s57, s36
	v_lshl_add_u64 v[144:145], v[144:145], 0, s[6:7]
	s_mov_b32 m0, s34
	ds_read_b128 v[188:191], v151 offset:49152
	ds_read_b128 v[192:195], v151 offset:50176
	ds_read_b128 v[196:199], v151 offset:51200
	ds_read_b128 v[200:203], v151 offset:52224
	ds_read_b128 v[204:207], v151 offset:53248
	ds_read_b128 v[208:211], v151 offset:54272
	ds_read_b128 v[212:215], v151 offset:55296
	ds_read_b128 v[216:219], v151 offset:56320
	global_load_lds_dwordx4 v[144:145], off
	s_add_i32 m0, s34, 0x2000
	s_add_u32 s30, s30, 0x80080
	v_lshl_add_u64 v[144:145], v[184:185], 0, s[6:7]
	s_addc_u32 s31, s31, 0
	s_add_i32 s34, s58, s36
	global_load_lds_dwordx4 v[144:145], off
	v_lshl_add_u64 v[144:145], s[30:31], 0, v[130:131]
	s_mov_b32 m0, s34
	s_nop 0
	global_load_lds_dwordx4 v[144:145], off
	v_lshl_add_u64 v[144:145], s[30:31], 0, v[134:135]
	s_add_i32 m0, s34, 0x2000
	s_nop 0
	global_load_lds_dwordx4 v[144:145], off
	v_lshl_add_u64 v[144:145], v[220:221], 0, s[6:7]
	s_mov_b32 m0, s41
	s_nop 0
	global_load_lds_dwordx4 v[144:145], off
	v_lshl_add_u64 v[144:145], v[222:223], 0, s[6:7]
	s_mov_b32 m0, s42
	s_nop 0
	global_load_lds_dwordx4 v[144:145], off
	s_waitcnt vmcnt(8)
	s_waitcnt lgkmcnt(0)
	s_barrier
	s_setprio 1
	s_waitcnt lgkmcnt(0)
	v_mfma_f32_16x16x32_bf16 v[60:63], v[152:155], v[188:191], v[60:63]
	v_mfma_f32_16x16x32_bf16 v[56:59], v[160:163], v[188:191], v[56:59]
	v_mfma_f32_16x16x32_bf16 v[48:51], v[152:155], v[196:199], v[48:51]
	v_mfma_f32_16x16x32_bf16 v[40:43], v[160:163], v[196:199], v[40:43]
	v_mfma_f32_16x16x32_bf16 v[32:35], v[152:155], v[204:207], v[32:35]
	v_mfma_f32_16x16x32_bf16 v[24:27], v[160:163], v[204:207], v[24:27]
	v_mfma_f32_16x16x32_bf16 v[16:19], v[152:155], v[212:215], v[16:19]
	v_mfma_f32_16x16x32_bf16 v[8:11], v[160:163], v[212:215], v[8:11]
	v_mfma_f32_16x16x32_bf16 v[60:63], v[156:159], v[192:195], v[60:63]
	v_mfma_f32_16x16x32_bf16 v[56:59], v[164:167], v[192:195], v[56:59]
	v_mfma_f32_16x16x32_bf16 v[48:51], v[156:159], v[200:203], v[48:51]
	v_mfma_f32_16x16x32_bf16 v[40:43], v[164:167], v[200:203], v[40:43]
	v_mfma_f32_16x16x32_bf16 v[32:35], v[156:159], v[208:211], v[32:35]
	v_mfma_f32_16x16x32_bf16 v[24:27], v[164:167], v[208:211], v[24:27]
	v_mfma_f32_16x16x32_bf16 v[16:19], v[156:159], v[216:219], v[16:19]
	v_mfma_f32_16x16x32_bf16 v[8:11], v[164:167], v[216:219], v[8:11]
	v_mfma_f32_16x16x32_bf16 v[52:55], v[168:171], v[188:191], v[52:55]
	v_mfma_f32_16x16x32_bf16 v[44:47], v[176:179], v[188:191], v[44:47]
	v_mfma_f32_16x16x32_bf16 v[36:39], v[168:171], v[196:199], v[36:39]
	v_mfma_f32_16x16x32_bf16 v[28:31], v[176:179], v[196:199], v[28:31]
	v_mfma_f32_16x16x32_bf16 v[20:23], v[168:171], v[204:207], v[20:23]
	v_mfma_f32_16x16x32_bf16 v[12:15], v[176:179], v[204:207], v[12:15]
	v_mfma_f32_16x16x32_bf16 v[4:7], v[168:171], v[212:215], v[4:7]
	v_mfma_f32_16x16x32_bf16 v[0:3], v[176:179], v[212:215], v[0:3]
	v_mfma_f32_16x16x32_bf16 v[52:55], v[172:175], v[192:195], v[52:55]
	v_mfma_f32_16x16x32_bf16 v[44:47], v[180:183], v[192:195], v[44:47]
	v_mfma_f32_16x16x32_bf16 v[36:39], v[172:175], v[200:203], v[36:39]
	v_mfma_f32_16x16x32_bf16 v[28:31], v[180:183], v[200:203], v[28:31]
	v_mfma_f32_16x16x32_bf16 v[20:23], v[172:175], v[208:211], v[20:23]
	v_mfma_f32_16x16x32_bf16 v[12:15], v[180:183], v[208:211], v[12:15]
	v_mfma_f32_16x16x32_bf16 v[4:7], v[172:175], v[216:219], v[4:7]
	v_mfma_f32_16x16x32_bf16 v[0:3], v[180:183], v[216:219], v[0:3]
	s_setprio 0
	s_barrier
	s_add_i32 s56, s56, 2
	s_add_u32 s28, s28, 0x100
	s_addc_u32 s29, s29, 0
	s_add_u32 s54, s54, 0x100
	s_addc_u32 s55, s55, 0
	s_cmp_gt_u32 s56, 29
	s_cbranch_scc0 .LBB0_814
	s_and_b64 vcc, exec, s[8:9]
	s_cbranch_vccz .LBB0_817
	s_barrier

; #define PG8_STAGE(bufoff, gbase, voff) do { _Pragma("unroll") for (int _i = 0; _i < 2; ++_i) \
;         __builtin_amdgcn_global_load_lds((const unsigned*)((const char*)(gbase) + (voff)[_i]), (PG8_LAS unsigned*)(lds + (bufoff) + ldsw + _i * 8192), 16, 0, 0); } while (0)
; #define PG8_LDA(dst, b, h) do { _Pragma("unroll") for (int m = 0; m < 4; ++m) _Pragma("unroll") for (int k = 0; k < 2; ++k) dst[m][k] = *(const PG8_LAS bf16x8*)(lds + PG8_SA(b, h) + aoff + m * 2048 + k * 1024); } while (0)
; #define PG8_LDB(dst, b, h) do { _Pragma("unroll") for (int n = 0; n < 2; ++n) _Pragma("unroll") for (int k = 0; k < 2; ++k) dst[n][k] = *(const PG8_LAS bf16x8*)(lds + PG8_SB(b, h) + boff + n * 2048 + k * 1024); } while (0)
; #define PG8_WAIT_V(n) asm volatile("s_waitcnt vmcnt(" #n ")" ::: "memory")
; #define PG8_WAIT_L(n) asm volatile("s_waitcnt lgkmcnt(" #n ")" ::: "memory")
; #define PG8_BAR __builtin_amdgcn_s_barrier()
; #define PG8_SCHED __builtin_amdgcn_sched_barrier(0)
; template <class Epi, class Sched, bool ALIGN_EPI = false, bool SP2 = false>
; __device__ __forceinline__ void gemm_phase(PG8_LAS unsigned char* lds, const Gemm g, const Sched& S, const Epi& E) {
;     ...
;         const char* nA = has_next ? (const char*)g.A + (size_t)nxt.pm * tstep : cA; const char* nB = has_next ? (const char*)g.Bt + (size_t)nxt.pn * tstep : cB;
;         for (int t = 0; t < nt; t += 2) {
;             const bool last = (t == nt - 2);
;             const char* a1 = cA + (size_t)(t + 1) * kstep;
;             const char* a2 = last ? nA : cA + (size_t)(t + 2) * kstep; const char* b2 = last ? nB : cB + (size_t)(t + 2) * kstep;
;             const char* a3 = a2 + kstep; const char* b3 = b2 + kstep;
;             if (last && has_next) S.a_ready(nxt);
;             if constexpr (SP2) {
;             PG8_LDB(B0, 0, 0); PG8_LDB(B1, 0, 1); PG8_SCHED; PG8_LDA(At, 0, 0); PG8_STAGE(PG8_SA(1, 1), a1 + hstep, voffA);
;             PG8_WAIT_V(8); PG8_WAIT_L(0); PG8_BAR; PG8_MMA(0, 0, At, B0); PG8_MMA(0, 1, At, B1); PG8_BAR; PG8_SCHED;
;             PG8_LDA(At, 0, 1); PG8_STAGE(PG8_SB(0, 0), b2, voffB); PG8_STAGE(PG8_SB(0, 1), b2 + hstep, voffB); PG8_STAGE(PG8_SA(0, 0), a2, voffA);
;             PG8_WAIT_V(8); PG8_WAIT_L(0); PG8_BAR; PG8_MMA(1, 0, At, B0); PG8_MMA(1, 1, At, B1); PG8_BAR; PG8_SCHED;
.LBB0_894:
	ds_read_b128 v[72:75], v169
	ds_read_b128 v[84:87], v169 offset:1024
	ds_read_b128 v[92:95], v169 offset:2048
	ds_read_b128 v[96:99], v169 offset:3072
	ds_read_b128 v[156:159], v170
	ds_read_b128 v[160:163], v170 offset:1024
	ds_read_b128 v[174:177], v170 offset:2048
	ds_read_b128 v[178:181], v170 offset:3072
	s_add_u32 s40, s38, 0xfff80080
	s_addc_u32 s41, s39, -1
	s_cmp_eq_u32 s58, 28
	s_cselect_b32 s43, s25, s41
	s_cselect_b32 s42, s35, s40
	s_cselect_b32 s41, s27, s57
	s_cselect_b32 s40, s55, s56
	v_lshl_add_u64 v[164:165], s[38:39], 0, v[148:149]
	s_add_i32 m0, s37, 0xc000
	ds_read_b128 v[182:185], v171
	ds_read_b128 v[188:191], v171 offset:1024
	ds_read_b128 v[192:195], v171 offset:2048
	ds_read_b128 v[196:199], v171 offset:3072
	ds_read_b128 v[200:203], v171 offset:4096
	ds_read_b128 v[204:207], v171 offset:5120
	ds_read_b128 v[208:211], v171 offset:6144
	ds_read_b128 v[212:215], v171 offset:7168
	global_load_lds_dwordx4 v[164:165], off
	v_lshl_add_u64 v[164:165], s[38:39], 0, v[150:151]
	s_add_i32 m0, s37, 0xe000
	s_nop 0
	global_load_lds_dwordx4 v[164:165], off
	s_waitcnt vmcnt(8)
	s_waitcnt lgkmcnt(0)
	s_barrier
	s_setprio 1
	s_waitcnt lgkmcnt(0)
	v_mfma_f32_16x16x32_bf16 v[140:143], v[72:75], v[182:185], v[140:143]
	v_mfma_f32_16x16x32_bf16 v[136:139], v[92:95], v[182:185], v[136:139]
	v_mfma_f32_16x16x32_bf16 v[124:127], v[72:75], v[192:195], v[124:127]
	v_mfma_f32_16x16x32_bf16 v[120:123], v[92:95], v[192:195], v[120:123]
	v_mfma_f32_16x16x32_bf16 v[108:111], v[72:75], v[200:203], v[108:111]
	v_mfma_f32_16x16x32_bf16 v[104:107], v[92:95], v[200:203], v[104:107]
	v_mfma_f32_16x16x32_bf16 v[80:83], v[72:75], v[208:211], v[80:83]
	v_mfma_f32_16x16x32_bf16 v[76:79], v[92:95], v[208:211], v[76:79]
	v_mfma_f32_16x16x32_bf16 v[140:143], v[84:87], v[188:191], v[140:143]
	v_mfma_f32_16x16x32_bf16 v[136:139], v[96:99], v[188:191], v[136:139]
	v_mfma_f32_16x16x32_bf16 v[124:127], v[84:87], v[196:199], v[124:127]
	v_mfma_f32_16x16x32_bf16 v[120:123], v[96:99], v[196:199], v[120:123]
	v_mfma_f32_16x16x32_bf16 v[108:111], v[84:87], v[204:207], v[108:111]
	v_mfma_f32_16x16x32_bf16 v[104:107], v[96:99], v[204:207], v[104:107]
	v_mfma_f32_16x16x32_bf16 v[80:83], v[84:87], v[212:215], v[80:83]
	v_mfma_f32_16x16x32_bf16 v[76:79], v[96:99], v[212:215], v[76:79]
	v_mfma_f32_16x16x32_bf16 v[132:135], v[156:159], v[182:185], v[132:135]
	v_mfma_f32_16x16x32_bf16 v[128:131], v[174:177], v[182:185], v[128:131]
	v_mfma_f32_16x16x32_bf16 v[116:119], v[156:159], v[192:195], v[116:119]
	v_mfma_f32_16x16x32_bf16 v[112:115], v[174:177], v[192:195], v[112:115]
	v_mfma_f32_16x16x32_bf16 v[100:103], v[156:159], v[200:203], v[100:103]
	v_mfma_f32_16x16x32_bf16 v[88:91], v[174:177], v[200:203], v[88:91]
	v_mfma_f32_16x16x32_bf16 v[68:71], v[156:159], v[208:211], v[68:71]
	v_mfma_f32_16x16x32_bf16 v[64:67], v[174:177], v[208:211], v[64:67]
	v_mfma_f32_16x16x32_bf16 v[132:135], v[160:163], v[188:191], v[132:135]
	v_mfma_f32_16x16x32_bf16 v[128:131], v[178:181], v[188:191], v[128:131]
	v_mfma_f32_16x16x32_bf16 v[116:119], v[160:163], v[196:199], v[116:119]
	v_mfma_f32_16x16x32_bf16 v[112:115], v[178:181], v[196:199], v[112:115]
	v_mfma_f32_16x16x32_bf16 v[100:103], v[160:163], v[204:207], v[100:103]
	v_mfma_f32_16x16x32_bf16 v[88:91], v[178:181], v[204:207], v[88:91]
	v_mfma_f32_16x16x32_bf16 v[68:71], v[160:163], v[212:215], v[68:71]
	v_mfma_f32_16x16x32_bf16 v[64:67], v[178:181], v[212:215], v[64:67]
	s_setprio 0
	s_barrier
	s_add_i32 s59, s53, s33
	v_lshl_add_u64 v[164:165], s[40:41], 0, v[144:145]
	s_mov_b32 m0, s59
	ds_read_b128 v[182:185], v171 offset:16384
	ds_read_b128 v[188:191], v171 offset:17408
	ds_read_b128 v[192:195], v171 offset:18432
	ds_read_b128 v[196:199], v171 offset:19456
	ds_read_b128 v[200:203], v171 offset:20480
	ds_read_b128 v[204:207], v171 offset:21504
	ds_read_b128 v[208:211], v171 offset:22528
	ds_read_b128 v[212:215], v171 offset:23552
	global_load_lds_dwordx4 v[164:165], off
	s_add_i32 m0, s59, 0x2000
	s_add_u32 s60, s40, 0x80000
	v_lshl_add_u64 v[216:217], s[40:41], 0, v[146:147]
	s_addc_u32 s61, s41, 0
	s_add_i32 s59, s54, s33
	global_load_lds_dwordx4 v[216:217], off
	v_lshl_add_u64 v[218:219], s[60:61], 0, v[144:145]
	s_mov_b32 m0, s59
	v_lshl_add_u64 v[220:221], s[42:43], 0, v[146:147]
	global_load_lds_dwordx4 v[218:219], off
	v_lshl_add_u64 v[218:219], s[60:61], 0, v[146:147]
	s_add_i32 m0, s59, 0x2000
	s_nop 0
	global_load_lds_dwordx4 v[218:219], off
	v_lshl_add_u64 v[218:219], s[42:43], 0, v[144:145]
	s_mov_b32 m0, s37
	s_nop 0
	global_load_lds_dwordx4 v[218:219], off
	s_mov_b32 m0, s44
	s_nop 0
	global_load_lds_dwordx4 v[220:221], off
	s_waitcnt vmcnt(8)
	s_waitcnt lgkmcnt(0)
	s_barrier
; #define PG8_STAGE(bufoff, gbase, voff) do { _Pragma("unroll") for (int _i = 0; _i < 2; ++_i) \
;         __builtin_amdgcn_global_load_lds((const unsigned*)((const char*)(gbase) + (voff)[_i]), (PG8_LAS unsigned*)(lds + (bufoff) + ldsw + _i * 8192), 16, 0, 0); } while (0)
; #define PG8_LDA(dst, b, h) do { _Pragma("unroll") for (int m = 0; m < 4; ++m) _Pragma("unroll") for (int k = 0; k < 2; ++k) dst[m][k] = *(const PG8_LAS bf16x8*)(lds + PG8_SA(b, h) + aoff + m * 2048 + k * 1024); } while (0)
; #define PG8_LDB(dst, b, h) do { _Pragma("unroll") for (int n = 0; n < 2; ++n) _Pragma("unroll") for (int k = 0; k < 2; ++k) dst[n][k] = *(const PG8_LAS bf16x8*)(lds + PG8_SB(b, h) + boff + n * 2048 + k * 1024); } while (0)
; #define PG8_MMA(ai, bj, At, Bt) do { __builtin_amdgcn_s_setprio(1); _Pragma("unroll") for (int m = 0; m < 4; ++m) _Pragma("unroll") for (int n = 0; n < 2; ++n) _Pragma("unroll") for (int k = 0; k < 2; ++k) \
;         acc[ai][bj][m][n] = __builtin_amdgcn_mfma_f32_16x16x32_bf16(Bt[n][k], At[m][k], acc[ai][bj][m][n], 0, 0, 0); __builtin_amdgcn_s_setprio(0); } while (0)
; #define PG8_WAIT_V(n) asm volatile("s_waitcnt vmcnt(" #n ")" ::: "memory")
; #define PG8_WAIT_L(n) asm volatile("s_waitcnt lgkmcnt(" #n ")" ::: "memory")
; #define PG8_BAR __builtin_amdgcn_s_barrier()
; #define PG8_SCHED __builtin_amdgcn_sched_barrier(0)
; template <class Epi, class Sched, bool ALIGN_EPI = false, bool SP2 = false>
; __device__ __forceinline__ void gemm_phase(PG8_LAS unsigned char* lds, const Gemm g, const Sched& S, const Epi& E) {
;     ...
;             PG8_WAIT_V(8); PG8_WAIT_L(0); PG8_BAR; PG8_MMA(1, 0, At, B0); PG8_MMA(1, 1, At, B1); PG8_BAR; PG8_SCHED;
;             PG8_LDB(B0, 1, 0); PG8_LDB(B1, 1, 1); PG8_SCHED; PG8_LDA(At, 1, 0); PG8_STAGE(PG8_SA(0, 1), a2 + hstep, voffA);
;             PG8_WAIT_V(8); PG8_WAIT_L(0); PG8_BAR; PG8_MMA(0, 0, At, B0); PG8_MMA(0, 1, At, B1); PG8_BAR; PG8_SCHED;
	s_setprio 1
	s_waitcnt lgkmcnt(0)
	v_mfma_f32_16x16x32_bf16 v[60:63], v[72:75], v[182:185], v[60:63]
	v_mfma_f32_16x16x32_bf16 v[56:59], v[92:95], v[182:185], v[56:59]
	v_mfma_f32_16x16x32_bf16 v[44:47], v[72:75], v[192:195], v[44:47]
	v_mfma_f32_16x16x32_bf16 v[40:43], v[92:95], v[192:195], v[40:43]
	v_mfma_f32_16x16x32_bf16 v[28:31], v[72:75], v[200:203], v[28:31]
	v_mfma_f32_16x16x32_bf16 v[24:27], v[92:95], v[200:203], v[24:27]
	v_mfma_f32_16x16x32_bf16 v[12:15], v[72:75], v[208:211], v[12:15]
	v_mfma_f32_16x16x32_bf16 v[8:11], v[92:95], v[208:211], v[8:11]
	v_mfma_f32_16x16x32_bf16 v[60:63], v[84:87], v[188:191], v[60:63]
	v_mfma_f32_16x16x32_bf16 v[56:59], v[96:99], v[188:191], v[56:59]
	v_mfma_f32_16x16x32_bf16 v[44:47], v[84:87], v[196:199], v[44:47]
	v_mfma_f32_16x16x32_bf16 v[40:43], v[96:99], v[196:199], v[40:43]
	v_mfma_f32_16x16x32_bf16 v[28:31], v[84:87], v[204:207], v[28:31]
	v_mfma_f32_16x16x32_bf16 v[24:27], v[96:99], v[204:207], v[24:27]
	v_mfma_f32_16x16x32_bf16 v[12:15], v[84:87], v[212:215], v[12:15]
	v_mfma_f32_16x16x32_bf16 v[8:11], v[96:99], v[212:215], v[8:11]
	v_mfma_f32_16x16x32_bf16 v[52:55], v[156:159], v[182:185], v[52:55]
	v_mfma_f32_16x16x32_bf16 v[48:51], v[174:177], v[182:185], v[48:51]
	v_mfma_f32_16x16x32_bf16 v[36:39], v[156:159], v[192:195], v[36:39]
	v_mfma_f32_16x16x32_bf16 v[32:35], v[174:177], v[192:195], v[32:35]
	v_mfma_f32_16x16x32_bf16 v[20:23], v[156:159], v[200:203], v[20:23]
	v_mfma_f32_16x16x32_bf16 v[16:19], v[174:177], v[200:203], v[16:19]
	v_mfma_f32_16x16x32_bf16 v[4:7], v[156:159], v[208:211], v[4:7]
	v_mfma_f32_16x16x32_bf16 v[0:3], v[174:177], v[208:211], v[0:3]
	v_mfma_f32_16x16x32_bf16 v[52:55], v[160:163], v[188:191], v[52:55]
	v_mfma_f32_16x16x32_bf16 v[48:51], v[178:181], v[188:191], v[48:51]
	v_mfma_f32_16x16x32_bf16 v[36:39], v[160:163], v[196:199], v[36:39]
	v_mfma_f32_16x16x32_bf16 v[32:35], v[178:181], v[196:199], v[32:35]
	v_mfma_f32_16x16x32_bf16 v[20:23], v[160:163], v[204:207], v[20:23]
	v_mfma_f32_16x16x32_bf16 v[16:19], v[178:181], v[204:207], v[16:19]
	v_mfma_f32_16x16x32_bf16 v[4:7], v[160:163], v[212:215], v[4:7]
	v_mfma_f32_16x16x32_bf16 v[0:3], v[178:181], v[212:215], v[0:3]
	s_setprio 0
	s_barrier
	s_add_i32 s59, 0, 0x18000
	s_add_i32 s60, 0, 0x1c000
	v_add_u32_e32 v96, s59, v167
	v_add_u32_e32 v173, s60, v167
	ds_read_b128 v[72:75], v96
	ds_read_b128 v[84:87], v96 offset:1024
	ds_read_b128 v[92:95], v96 offset:2048
	ds_read_b128 v[96:99], v96 offset:3072
	ds_read_b128 v[156:159], v173
	ds_read_b128 v[160:163], v173 offset:1024
	ds_read_b128 v[174:177], v173 offset:2048
	ds_read_b128 v[178:181], v173 offset:3072
	s_add_u32 s42, s42, 0x80000
	s_addc_u32 s43, s43, 0
	s_mov_b32 m0, s45
	v_lshl_add_u64 v[222:223], s[42:43], 0, v[144:145]
	ds_read_b128 v[182:185], v171 offset:32768
	ds_read_b128 v[188:191], v171 offset:33792
	ds_read_b128 v[192:195], v171 offset:34816
	ds_read_b128 v[196:199], v171 offset:35840
	ds_read_b128 v[200:203], v171 offset:36864
	ds_read_b128 v[204:207], v171 offset:37888
	ds_read_b128 v[208:211], v171 offset:38912
	ds_read_b128 v[212:215], v171 offset:39936
	global_load_lds_dwordx4 v[222:223], off
	v_lshl_add_u64 v[222:223], s[42:43], 0, v[146:147]
	s_mov_b32 m0, s46
	s_nop 0
	global_load_lds_dwordx4 v[222:223], off
	s_waitcnt vmcnt(8)
	s_waitcnt lgkmcnt(0)
	s_barrier
	s_setprio 1
	s_waitcnt lgkmcnt(0)
	v_mfma_f32_16x16x32_bf16 v[140:143], v[72:75], v[182:185], v[140:143]
	v_mfma_f32_16x16x32_bf16 v[136:139], v[92:95], v[182:185], v[136:139]
	v_mfma_f32_16x16x32_bf16 v[124:127], v[72:75], v[192:195], v[124:127]
	v_mfma_f32_16x16x32_bf16 v[120:123], v[92:95], v[192:195], v[120:123]
	v_mfma_f32_16x16x32_bf16 v[108:111], v[72:75], v[200:203], v[108:111]
	v_mfma_f32_16x16x32_bf16 v[104:107], v[92:95], v[200:203], v[104:107]
	v_mfma_f32_16x16x32_bf16 v[80:83], v[72:75], v[208:211], v[80:83]
	v_mfma_f32_16x16x32_bf16 v[76:79], v[92:95], v[208:211], v[76:79]
	v_mfma_f32_16x16x32_bf16 v[140:143], v[84:87], v[188:191], v[140:143]
	v_mfma_f32_16x16x32_bf16 v[136:139], v[96:99], v[188:191], v[136:139]
	v_mfma_f32_16x16x32_bf16 v[124:127], v[84:87], v[196:199], v[124:127]
	v_mfma_f32_16x16x32_bf16 v[120:123], v[96:99], v[196:199], v[120:123]
	v_mfma_f32_16x16x32_bf16 v[108:111], v[84:87], v[204:207], v[108:111]
	v_mfma_f32_16x16x32_bf16 v[104:107], v[96:99], v[204:207], v[104:107]
	v_mfma_f32_16x16x32_bf16 v[80:83], v[84:87], v[212:215], v[80:83]
	v_mfma_f32_16x16x32_bf16 v[76:79], v[96:99], v[212:215], v[76:79]
	v_mfma_f32_16x16x32_bf16 v[132:135], v[156:159], v[182:185], v[132:135]
	v_mfma_f32_16x16x32_bf16 v[128:131], v[174:177], v[182:185], v[128:131]
	v_mfma_f32_16x16x32_bf16 v[116:119], v[156:159], v[192:195], v[116:119]
	v_mfma_f32_16x16x32_bf16 v[112:115], v[174:177], v[192:195], v[112:115]
	v_mfma_f32_16x16x32_bf16 v[100:103], v[156:159], v[200:203], v[100:103]
	v_mfma_f32_16x16x32_bf16 v[88:91], v[174:177], v[200:203], v[88:91]
	v_mfma_f32_16x16x32_bf16 v[68:71], v[156:159], v[208:211], v[68:71]
	v_mfma_f32_16x16x32_bf16 v[64:67], v[174:177], v[208:211], v[64:67]
	v_mfma_f32_16x16x32_bf16 v[132:135], v[160:163], v[188:191], v[132:135]
	v_mfma_f32_16x16x32_bf16 v[128:131], v[178:181], v[188:191], v[128:131]
	v_mfma_f32_16x16x32_bf16 v[116:119], v[160:163], v[196:199], v[116:119]
	v_mfma_f32_16x16x32_bf16 v[112:115], v[178:181], v[196:199], v[112:115]
	v_mfma_f32_16x16x32_bf16 v[100:103], v[160:163], v[204:207], v[100:103]
	v_mfma_f32_16x16x32_bf16 v[88:91], v[178:181], v[204:207], v[88:91]
	v_mfma_f32_16x16x32_bf16 v[68:71], v[160:163], v[212:215], v[68:71]
	v_mfma_f32_16x16x32_bf16 v[64:67], v[178:181], v[212:215], v[64:67]
	s_setprio 0
	s_barrier
; #define PG8_STAGE(bufoff, gbase, voff) do { _Pragma("unroll") for (int _i = 0; _i < 2; ++_i) \
;         __builtin_amdgcn_global_load_lds((const unsigned*)((const char*)(gbase) + (voff)[_i]), (PG8_LAS unsigned*)(lds + (bufoff) + ldsw + _i * 8192), 16, 0, 0); } while (0)
; #define PG8_LDA(dst, b, h) do { _Pragma("unroll") for (int m = 0; m < 4; ++m) _Pragma("unroll") for (int k = 0; k < 2; ++k) dst[m][k] = *(const PG8_LAS bf16x8*)(lds + PG8_SA(b, h) + aoff + m * 2048 + k * 1024); } while (0)
; #define PG8_MMA(ai, bj, At, Bt) do { __builtin_amdgcn_s_setprio(1); _Pragma("unroll") for (int m = 0; m < 4; ++m) _Pragma("unroll") for (int n = 0; n < 2; ++n) _Pragma("unroll") for (int k = 0; k < 2; ++k) \
;         acc[ai][bj][m][n] = __builtin_amdgcn_mfma_f32_16x16x32_bf16(Bt[n][k], At[m][k], acc[ai][bj][m][n], 0, 0, 0); __builtin_amdgcn_s_setprio(0); } while (0)
; #define PG8_WAIT_V(n) asm volatile("s_waitcnt vmcnt(" #n ")" ::: "memory")
; #define PG8_WAIT_L(n) asm volatile("s_waitcnt lgkmcnt(" #n ")" ::: "memory")
; #define PG8_BAR __builtin_amdgcn_s_barrier()
; #define PG8_SCHED __builtin_amdgcn_sched_barrier(0)
; template <class Epi, class Sched, bool ALIGN_EPI = false, bool SP2 = false>
; __device__ __forceinline__ void gemm_phase(PG8_LAS unsigned char* lds, const Gemm g, const Sched& S, const Epi& E) {
;     ...
;             PG8_LDA(At, 1, 1); PG8_STAGE(PG8_SB(1, 0), b3, voffB); PG8_STAGE(PG8_SB(1, 1), b3 + hstep, voffB); PG8_STAGE(PG8_SA(1, 0), a3, voffA);
;             PG8_WAIT_V(8); PG8_WAIT_L(0); PG8_BAR; PG8_MMA(1, 0, At, B0); PG8_MMA(1, 1, At, B1); PG8_BAR; PG8_SCHED;
;     ...
;         if constexpr (ALIGN_EPI) { if (wr == 0) PG8_BAR; }
	s_add_i32 s42, s59, s33
	v_lshl_add_u64 v[164:165], v[164:165], 0, s[12:13]
	s_mov_b32 m0, s42
	ds_read_b128 v[182:185], v171 offset:49152
	ds_read_b128 v[188:191], v171 offset:50176
	ds_read_b128 v[192:195], v171 offset:51200
	ds_read_b128 v[196:199], v171 offset:52224
	ds_read_b128 v[200:203], v171 offset:53248
	ds_read_b128 v[204:207], v171 offset:54272
	ds_read_b128 v[208:211], v171 offset:55296
	ds_read_b128 v[212:215], v171 offset:56320
	global_load_lds_dwordx4 v[164:165], off
	s_add_i32 m0, s42, 0x2000
	s_add_u32 s40, s40, 0x80080
	v_lshl_add_u64 v[164:165], v[216:217], 0, s[12:13]
	s_addc_u32 s41, s41, 0
	s_add_i32 s42, s60, s33
	global_load_lds_dwordx4 v[164:165], off
	v_lshl_add_u64 v[164:165], s[40:41], 0, v[144:145]
	s_mov_b32 m0, s42
	s_nop 0
	global_load_lds_dwordx4 v[164:165], off
	v_lshl_add_u64 v[164:165], s[40:41], 0, v[146:147]
	s_add_i32 m0, s42, 0x2000
	s_nop 0
	global_load_lds_dwordx4 v[164:165], off
	v_lshl_add_u64 v[164:165], v[218:219], 0, s[12:13]
	s_mov_b32 m0, s50
	s_nop 0
	global_load_lds_dwordx4 v[164:165], off
	v_lshl_add_u64 v[164:165], v[220:221], 0, s[12:13]
	s_mov_b32 m0, s51
	s_nop 0
	global_load_lds_dwordx4 v[164:165], off
	s_waitcnt vmcnt(8)
	s_waitcnt lgkmcnt(0)
	s_barrier
	s_setprio 1
	s_waitcnt lgkmcnt(0)
	v_mfma_f32_16x16x32_bf16 v[60:63], v[72:75], v[182:185], v[60:63]
	v_mfma_f32_16x16x32_bf16 v[56:59], v[92:95], v[182:185], v[56:59]
	v_mfma_f32_16x16x32_bf16 v[44:47], v[72:75], v[192:195], v[44:47]
	v_mfma_f32_16x16x32_bf16 v[40:43], v[92:95], v[192:195], v[40:43]
	v_mfma_f32_16x16x32_bf16 v[28:31], v[72:75], v[200:203], v[28:31]
	v_mfma_f32_16x16x32_bf16 v[24:27], v[92:95], v[200:203], v[24:27]
	v_mfma_f32_16x16x32_bf16 v[12:15], v[72:75], v[208:211], v[12:15]
	v_mfma_f32_16x16x32_bf16 v[8:11], v[92:95], v[208:211], v[8:11]
	v_mfma_f32_16x16x32_bf16 v[60:63], v[84:87], v[188:191], v[60:63]
	v_mfma_f32_16x16x32_bf16 v[56:59], v[96:99], v[188:191], v[56:59]
	v_mfma_f32_16x16x32_bf16 v[44:47], v[84:87], v[196:199], v[44:47]
	v_mfma_f32_16x16x32_bf16 v[40:43], v[96:99], v[196:199], v[40:43]
	v_mfma_f32_16x16x32_bf16 v[28:31], v[84:87], v[204:207], v[28:31]
	v_mfma_f32_16x16x32_bf16 v[24:27], v[96:99], v[204:207], v[24:27]
	v_mfma_f32_16x16x32_bf16 v[12:15], v[84:87], v[212:215], v[12:15]
	v_mfma_f32_16x16x32_bf16 v[8:11], v[96:99], v[212:215], v[8:11]
	v_mfma_f32_16x16x32_bf16 v[52:55], v[156:159], v[182:185], v[52:55]
	v_mfma_f32_16x16x32_bf16 v[48:51], v[174:177], v[182:185], v[48:51]
	v_mfma_f32_16x16x32_bf16 v[36:39], v[156:159], v[192:195], v[36:39]
	v_mfma_f32_16x16x32_bf16 v[32:35], v[174:177], v[192:195], v[32:35]
	v_mfma_f32_16x16x32_bf16 v[20:23], v[156:159], v[200:203], v[20:23]
	v_mfma_f32_16x16x32_bf16 v[16:19], v[174:177], v[200:203], v[16:19]
	v_mfma_f32_16x16x32_bf16 v[4:7], v[156:159], v[208:211], v[4:7]
	v_mfma_f32_16x16x32_bf16 v[0:3], v[174:177], v[208:211], v[0:3]
	v_mfma_f32_16x16x32_bf16 v[52:55], v[160:163], v[188:191], v[52:55]
	v_mfma_f32_16x16x32_bf16 v[48:51], v[178:181], v[188:191], v[48:51]
	v_mfma_f32_16x16x32_bf16 v[36:39], v[160:163], v[196:199], v[36:39]
	v_mfma_f32_16x16x32_bf16 v[32:35], v[178:181], v[196:199], v[32:35]
	v_mfma_f32_16x16x32_bf16 v[20:23], v[160:163], v[204:207], v[20:23]
	v_mfma_f32_16x16x32_bf16 v[16:19], v[178:181], v[204:207], v[16:19]
	v_mfma_f32_16x16x32_bf16 v[4:7], v[160:163], v[212:215], v[4:7]
	v_mfma_f32_16x16x32_bf16 v[0:3], v[178:181], v[212:215], v[0:3]
	s_setprio 0
	s_barrier
	s_add_i32 s58, s58, 2
	s_add_u32 s38, s38, 0x100
	s_addc_u32 s39, s39, 0
	s_add_u32 s56, s56, 0x100
	s_addc_u32 s57, s57, 0
	s_cmp_gt_u32 s58, 29
	s_cbranch_scc0 .LBB0_894
	s_and_b64 vcc, exec, s[14:15]
	s_cbranch_vccz .LBB0_897
	s_barrier

; #define PG8_STAGE(bufoff, gbase, voff) do { _Pragma("unroll") for (int _i = 0; _i < 2; ++_i) \
;         __builtin_amdgcn_global_load_lds((const unsigned*)((const char*)(gbase) + (voff)[_i]), (PG8_LAS unsigned*)(lds + (bufoff) + ldsw + _i * 8192), 16, 0, 0); } while (0)
; #define PG8_LDA(dst, b, h) do { _Pragma("unroll") for (int m = 0; m < 4; ++m) _Pragma("unroll") for (int k = 0; k < 2; ++k) dst[m][k] = *(const PG8_LAS bf16x8*)(lds + PG8_SA(b, h) + aoff + m * 2048 + k * 1024); } while (0)
; #define PG8_LDB(dst, b, h) do { _Pragma("unroll") for (int n = 0; n < 2; ++n) _Pragma("unroll") for (int k = 0; k < 2; ++k) dst[n][k] = *(const PG8_LAS bf16x8*)(lds + PG8_SB(b, h) + boff + n * 2048 + k * 1024); } while (0)
; #define PG8_WAIT_V(n) asm volatile("s_waitcnt vmcnt(" #n ")" ::: "memory")
; #define PG8_WAIT_L(n) asm volatile("s_waitcnt lgkmcnt(" #n ")" ::: "memory")
; #define PG8_BAR __builtin_amdgcn_s_barrier()
; #define PG8_SCHED __builtin_amdgcn_sched_barrier(0)
; template <class Epi, class Sched, bool ALIGN_EPI = false, bool SP2 = false>
; __device__ __forceinline__ void gemm_phase(PG8_LAS unsigned char* lds, const Gemm g, const Sched& S, const Epi& E) {
;     ...
;         const char* nA = has_next ? (const char*)g.A + (size_t)nxt.pm * tstep : cA; const char* nB = has_next ? (const char*)g.Bt + (size_t)nxt.pn * tstep : cB;
;         for (int t = 0; t < nt; t += 2) {
;             const bool last = (t == nt - 2);
;             const char* a1 = cA + (size_t)(t + 1) * kstep;
;             const char* a2 = last ? nA : cA + (size_t)(t + 2) * kstep; const char* b2 = last ? nB : cB + (size_t)(t + 2) * kstep;
;             const char* a3 = a2 + kstep; const char* b3 = b2 + kstep;
;             if (last && has_next) S.a_ready(nxt);
;             if constexpr (SP2) {
;             PG8_LDB(B0, 0, 0); PG8_LDB(B1, 0, 1); PG8_SCHED; PG8_LDA(At, 0, 0); PG8_STAGE(PG8_SA(1, 1), a1 + hstep, voffA);
;             PG8_WAIT_V(8); PG8_WAIT_L(0); PG8_BAR; PG8_MMA(0, 0, At, B0); PG8_MMA(0, 1, At, B1); PG8_BAR; PG8_SCHED;
;             PG8_LDA(At, 0, 1); PG8_STAGE(PG8_SB(0, 0), b2, voffB); PG8_STAGE(PG8_SB(0, 1), b2 + hstep, voffB); PG8_STAGE(PG8_SA(0, 0), a2, voffA);
;             PG8_WAIT_V(8); PG8_WAIT_L(0); PG8_BAR; PG8_MMA(1, 0, At, B0); PG8_MMA(1, 1, At, B1); PG8_BAR; PG8_SCHED;
.LBB0_994:
	ds_read_b128 v[128:131], v173
	ds_read_b128 v[132:135], v173 offset:1024
	ds_read_b128 v[136:139], v173 offset:2048
	ds_read_b128 v[140:143], v173 offset:3072
	ds_read_b128 v[176:179], v174
	ds_read_b128 v[180:183], v174 offset:1024
	ds_read_b128 v[188:191], v174 offset:2048
	ds_read_b128 v[192:195], v174 offset:3072
	s_add_u32 s26, s24, 0xfff80080
	s_addc_u32 s27, s25, -1
	s_cmp_eq_u32 s47, 28
	s_cselect_b32 s29, s15, s27
	s_cselect_b32 s28, s43, s26
	s_cselect_b32 s27, s17, s46
	s_cselect_b32 s26, s44, s45
	v_lshl_add_u64 v[160:161], s[24:25], 0, v[152:153]
	s_add_i32 m0, s23, 0xc000
	ds_read_b128 v[196:199], v175
	ds_read_b128 v[200:203], v175 offset:1024
	ds_read_b128 v[204:207], v175 offset:2048
	ds_read_b128 v[208:211], v175 offset:3072
	ds_read_b128 v[212:215], v175 offset:4096
	ds_read_b128 v[216:219], v175 offset:5120
	ds_read_b128 v[220:223], v175 offset:6144
	ds_read_b128 v[224:227], v175 offset:7168
	global_load_lds_dwordx4 v[160:161], off
	v_lshl_add_u64 v[160:161], s[24:25], 0, v[154:155]
	s_add_i32 m0, s23, 0xe000
	s_nop 0
	global_load_lds_dwordx4 v[160:161], off
	s_waitcnt vmcnt(8)
	s_waitcnt lgkmcnt(0)
	s_barrier
	s_setprio 1
	s_waitcnt lgkmcnt(0)
	v_mfma_f32_16x16x32_bf16 v[124:127], v[128:131], v[196:199], v[124:127]
	v_mfma_f32_16x16x32_bf16 v[120:123], v[136:139], v[196:199], v[120:123]
	v_mfma_f32_16x16x32_bf16 v[108:111], v[128:131], v[204:207], v[108:111]
	v_mfma_f32_16x16x32_bf16 v[104:107], v[136:139], v[204:207], v[104:107]
	v_mfma_f32_16x16x32_bf16 v[92:95], v[128:131], v[212:215], v[92:95]
	v_mfma_f32_16x16x32_bf16 v[88:91], v[136:139], v[212:215], v[88:91]
	v_mfma_f32_16x16x32_bf16 v[76:79], v[128:131], v[220:223], v[76:79]
	v_mfma_f32_16x16x32_bf16 v[72:75], v[136:139], v[220:223], v[72:75]
	v_mfma_f32_16x16x32_bf16 v[124:127], v[132:135], v[200:203], v[124:127]
	v_mfma_f32_16x16x32_bf16 v[120:123], v[140:143], v[200:203], v[120:123]
	v_mfma_f32_16x16x32_bf16 v[108:111], v[132:135], v[208:211], v[108:111]
	v_mfma_f32_16x16x32_bf16 v[104:107], v[140:143], v[208:211], v[104:107]
	v_mfma_f32_16x16x32_bf16 v[92:95], v[132:135], v[216:219], v[92:95]
	v_mfma_f32_16x16x32_bf16 v[88:91], v[140:143], v[216:219], v[88:91]
	v_mfma_f32_16x16x32_bf16 v[76:79], v[132:135], v[224:227], v[76:79]
	v_mfma_f32_16x16x32_bf16 v[72:75], v[140:143], v[224:227], v[72:75]
	v_mfma_f32_16x16x32_bf16 v[116:119], v[176:179], v[196:199], v[116:119]
	v_mfma_f32_16x16x32_bf16 v[112:115], v[188:191], v[196:199], v[112:115]
	v_mfma_f32_16x16x32_bf16 v[100:103], v[176:179], v[204:207], v[100:103]
	v_mfma_f32_16x16x32_bf16 v[96:99], v[188:191], v[204:207], v[96:99]
	v_mfma_f32_16x16x32_bf16 v[84:87], v[176:179], v[212:215], v[84:87]
	v_mfma_f32_16x16x32_bf16 v[80:83], v[188:191], v[212:215], v[80:83]
	v_mfma_f32_16x16x32_bf16 v[68:71], v[176:179], v[220:223], v[68:71]
	v_mfma_f32_16x16x32_bf16 v[64:67], v[188:191], v[220:223], v[64:67]
	v_mfma_f32_16x16x32_bf16 v[116:119], v[180:183], v[200:203], v[116:119]
	v_mfma_f32_16x16x32_bf16 v[112:115], v[192:195], v[200:203], v[112:115]
	v_mfma_f32_16x16x32_bf16 v[100:103], v[180:183], v[208:211], v[100:103]
	v_mfma_f32_16x16x32_bf16 v[96:99], v[192:195], v[208:211], v[96:99]
	v_mfma_f32_16x16x32_bf16 v[84:87], v[180:183], v[216:219], v[84:87]
	v_mfma_f32_16x16x32_bf16 v[80:83], v[192:195], v[216:219], v[80:83]
	v_mfma_f32_16x16x32_bf16 v[68:71], v[180:183], v[224:227], v[68:71]
	v_mfma_f32_16x16x32_bf16 v[64:67], v[192:195], v[224:227], v[64:67]
	s_setprio 0
	s_barrier
	s_add_i32 s48, s40, s31
	v_lshl_add_u64 v[160:161], s[26:27], 0, v[146:147]
	s_mov_b32 m0, s48
	ds_read_b128 v[196:199], v175 offset:16384
	ds_read_b128 v[200:203], v175 offset:17408
	ds_read_b128 v[204:207], v175 offset:18432
	ds_read_b128 v[208:211], v175 offset:19456
	ds_read_b128 v[212:215], v175 offset:20480
	ds_read_b128 v[216:219], v175 offset:21504
	ds_read_b128 v[220:223], v175 offset:22528
	ds_read_b128 v[224:227], v175 offset:23552
	global_load_lds_dwordx4 v[160:161], off
	s_add_i32 m0, s48, 0x2000
	s_add_u32 s48, s26, 0x80000
	v_lshl_add_u64 v[184:185], s[26:27], 0, v[150:151]
	s_addc_u32 s49, s27, 0
	s_add_i32 s50, s41, s31
	global_load_lds_dwordx4 v[184:185], off
	v_lshl_add_u64 v[228:229], s[48:49], 0, v[146:147]
	s_mov_b32 m0, s50
	v_lshl_add_u64 v[230:231], s[28:29], 0, v[148:149]
	global_load_lds_dwordx4 v[228:229], off
	v_lshl_add_u64 v[228:229], s[48:49], 0, v[150:151]
	s_add_i32 m0, s50, 0x2000
	s_nop 0
	global_load_lds_dwordx4 v[228:229], off
	v_lshl_add_u64 v[228:229], s[28:29], 0, v[144:145]
	s_mov_b32 m0, s23
	s_nop 0
	global_load_lds_dwordx4 v[228:229], off
	s_mov_b32 m0, s33
	s_nop 0
	global_load_lds_dwordx4 v[230:231], off
	s_waitcnt vmcnt(8)
	s_waitcnt lgkmcnt(0)
	s_barrier
; #define PG8_STAGE(bufoff, gbase, voff) do { _Pragma("unroll") for (int _i = 0; _i < 2; ++_i) \
;         __builtin_amdgcn_global_load_lds((const unsigned*)((const char*)(gbase) + (voff)[_i]), (PG8_LAS unsigned*)(lds + (bufoff) + ldsw + _i * 8192), 16, 0, 0); } while (0)
; #define PG8_LDA(dst, b, h) do { _Pragma("unroll") for (int m = 0; m < 4; ++m) _Pragma("unroll") for (int k = 0; k < 2; ++k) dst[m][k] = *(const PG8_LAS bf16x8*)(lds + PG8_SA(b, h) + aoff + m * 2048 + k * 1024); } while (0)
; #define PG8_LDB(dst, b, h) do { _Pragma("unroll") for (int n = 0; n < 2; ++n) _Pragma("unroll") for (int k = 0; k < 2; ++k) dst[n][k] = *(const PG8_LAS bf16x8*)(lds + PG8_SB(b, h) + boff + n * 2048 + k * 1024); } while (0)
; #define PG8_MMA(ai, bj, At, Bt) do { __builtin_amdgcn_s_setprio(1); _Pragma("unroll") for (int m = 0; m < 4; ++m) _Pragma("unroll") for (int n = 0; n < 2; ++n) _Pragma("unroll") for (int k = 0; k < 2; ++k) \
;         acc[ai][bj][m][n] = __builtin_amdgcn_mfma_f32_16x16x32_bf16(Bt[n][k], At[m][k], acc[ai][bj][m][n], 0, 0, 0); __builtin_amdgcn_s_setprio(0); } while (0)
; #define PG8_WAIT_V(n) asm volatile("s_waitcnt vmcnt(" #n ")" ::: "memory")
; #define PG8_WAIT_L(n) asm volatile("s_waitcnt lgkmcnt(" #n ")" ::: "memory")
; #define PG8_BAR __builtin_amdgcn_s_barrier()
; #define PG8_SCHED __builtin_amdgcn_sched_barrier(0)
; template <class Epi, class Sched, bool ALIGN_EPI = false, bool SP2 = false>
; __device__ __forceinline__ void gemm_phase(PG8_LAS unsigned char* lds, const Gemm g, const Sched& S, const Epi& E) {
;     ...
;             PG8_WAIT_V(8); PG8_WAIT_L(0); PG8_BAR; PG8_MMA(1, 0, At, B0); PG8_MMA(1, 1, At, B1); PG8_BAR; PG8_SCHED;
;             PG8_LDB(B0, 1, 0); PG8_LDB(B1, 1, 1); PG8_SCHED; PG8_LDA(At, 1, 0); PG8_STAGE(PG8_SA(0, 1), a2 + hstep, voffA);
;             PG8_WAIT_V(8); PG8_WAIT_L(0); PG8_BAR; PG8_MMA(0, 0, At, B0); PG8_MMA(0, 1, At, B1); PG8_BAR; PG8_SCHED;
	s_setprio 1
	s_waitcnt lgkmcnt(0)
	v_mfma_f32_16x16x32_bf16 v[60:63], v[128:131], v[196:199], v[60:63]
	v_mfma_f32_16x16x32_bf16 v[56:59], v[136:139], v[196:199], v[56:59]
	v_mfma_f32_16x16x32_bf16 v[44:47], v[128:131], v[204:207], v[44:47]
	v_mfma_f32_16x16x32_bf16 v[40:43], v[136:139], v[204:207], v[40:43]
	v_mfma_f32_16x16x32_bf16 v[28:31], v[128:131], v[212:215], v[28:31]
	v_mfma_f32_16x16x32_bf16 v[24:27], v[136:139], v[212:215], v[24:27]
	v_mfma_f32_16x16x32_bf16 v[12:15], v[128:131], v[220:223], v[12:15]
	v_mfma_f32_16x16x32_bf16 v[8:11], v[136:139], v[220:223], v[8:11]
	v_mfma_f32_16x16x32_bf16 v[60:63], v[132:135], v[200:203], v[60:63]
	v_mfma_f32_16x16x32_bf16 v[56:59], v[140:143], v[200:203], v[56:59]
	v_mfma_f32_16x16x32_bf16 v[44:47], v[132:135], v[208:211], v[44:47]
	v_mfma_f32_16x16x32_bf16 v[40:43], v[140:143], v[208:211], v[40:43]
	v_mfma_f32_16x16x32_bf16 v[28:31], v[132:135], v[216:219], v[28:31]
	v_mfma_f32_16x16x32_bf16 v[24:27], v[140:143], v[216:219], v[24:27]
	v_mfma_f32_16x16x32_bf16 v[12:15], v[132:135], v[224:227], v[12:15]
	v_mfma_f32_16x16x32_bf16 v[8:11], v[140:143], v[224:227], v[8:11]
	v_mfma_f32_16x16x32_bf16 v[52:55], v[176:179], v[196:199], v[52:55]
	v_mfma_f32_16x16x32_bf16 v[48:51], v[188:191], v[196:199], v[48:51]
	v_mfma_f32_16x16x32_bf16 v[36:39], v[176:179], v[204:207], v[36:39]
	v_mfma_f32_16x16x32_bf16 v[32:35], v[188:191], v[204:207], v[32:35]
	v_mfma_f32_16x16x32_bf16 v[20:23], v[176:179], v[212:215], v[20:23]
	v_mfma_f32_16x16x32_bf16 v[16:19], v[188:191], v[212:215], v[16:19]
	v_mfma_f32_16x16x32_bf16 v[4:7], v[176:179], v[220:223], v[4:7]
	v_mfma_f32_16x16x32_bf16 v[0:3], v[188:191], v[220:223], v[0:3]
	v_mfma_f32_16x16x32_bf16 v[52:55], v[180:183], v[200:203], v[52:55]
	v_mfma_f32_16x16x32_bf16 v[48:51], v[192:195], v[200:203], v[48:51]
	v_mfma_f32_16x16x32_bf16 v[36:39], v[180:183], v[208:211], v[36:39]
	v_mfma_f32_16x16x32_bf16 v[32:35], v[192:195], v[208:211], v[32:35]
	v_mfma_f32_16x16x32_bf16 v[20:23], v[180:183], v[216:219], v[20:23]
	v_mfma_f32_16x16x32_bf16 v[16:19], v[192:195], v[216:219], v[16:19]
	v_mfma_f32_16x16x32_bf16 v[4:7], v[180:183], v[224:227], v[4:7]
	v_mfma_f32_16x16x32_bf16 v[0:3], v[192:195], v[224:227], v[0:3]
	s_setprio 0
	s_barrier
	s_add_i32 s48, 0, 0x18000
	s_add_i32 s49, 0, 0x1c000
	v_add_u32_e32 v140, s48, v163
	v_add_u32_e32 v187, s49, v163
	ds_read_b128 v[128:131], v140
	ds_read_b128 v[132:135], v140 offset:1024
	ds_read_b128 v[136:139], v140 offset:2048
	ds_read_b128 v[140:143], v140 offset:3072
	ds_read_b128 v[176:179], v187
	ds_read_b128 v[180:183], v187 offset:1024
	ds_read_b128 v[188:191], v187 offset:2048
	ds_read_b128 v[192:195], v187 offset:3072
	s_add_u32 s28, s28, 0x80000
	s_addc_u32 s29, s29, 0
	s_mov_b32 m0, s34
	v_lshl_add_u64 v[232:233], s[28:29], 0, v[144:145]
	ds_read_b128 v[196:199], v175 offset:32768
	ds_read_b128 v[200:203], v175 offset:33792
	ds_read_b128 v[204:207], v175 offset:34816
	ds_read_b128 v[208:211], v175 offset:35840
	ds_read_b128 v[212:215], v175 offset:36864
	ds_read_b128 v[216:219], v175 offset:37888
	ds_read_b128 v[220:223], v175 offset:38912
	ds_read_b128 v[224:227], v175 offset:39936
	global_load_lds_dwordx4 v[232:233], off
	v_lshl_add_u64 v[232:233], s[28:29], 0, v[148:149]
	s_mov_b32 m0, s35
	s_nop 0
	global_load_lds_dwordx4 v[232:233], off
	s_waitcnt vmcnt(8)
	s_waitcnt lgkmcnt(0)
	s_barrier
	s_setprio 1
	s_waitcnt lgkmcnt(0)
	v_mfma_f32_16x16x32_bf16 v[124:127], v[128:131], v[196:199], v[124:127]
	v_mfma_f32_16x16x32_bf16 v[120:123], v[136:139], v[196:199], v[120:123]
	v_mfma_f32_16x16x32_bf16 v[108:111], v[128:131], v[204:207], v[108:111]
	v_mfma_f32_16x16x32_bf16 v[104:107], v[136:139], v[204:207], v[104:107]
	v_mfma_f32_16x16x32_bf16 v[92:95], v[128:131], v[212:215], v[92:95]
	v_mfma_f32_16x16x32_bf16 v[88:91], v[136:139], v[212:215], v[88:91]
	v_mfma_f32_16x16x32_bf16 v[76:79], v[128:131], v[220:223], v[76:79]
	v_mfma_f32_16x16x32_bf16 v[72:75], v[136:139], v[220:223], v[72:75]
	v_mfma_f32_16x16x32_bf16 v[124:127], v[132:135], v[200:203], v[124:127]
	v_mfma_f32_16x16x32_bf16 v[120:123], v[140:143], v[200:203], v[120:123]
	v_mfma_f32_16x16x32_bf16 v[108:111], v[132:135], v[208:211], v[108:111]
	v_mfma_f32_16x16x32_bf16 v[104:107], v[140:143], v[208:211], v[104:107]
	v_mfma_f32_16x16x32_bf16 v[92:95], v[132:135], v[216:219], v[92:95]
	v_mfma_f32_16x16x32_bf16 v[88:91], v[140:143], v[216:219], v[88:91]
	v_mfma_f32_16x16x32_bf16 v[76:79], v[132:135], v[224:227], v[76:79]
	v_mfma_f32_16x16x32_bf16 v[72:75], v[140:143], v[224:227], v[72:75]
	v_mfma_f32_16x16x32_bf16 v[116:119], v[176:179], v[196:199], v[116:119]
	v_mfma_f32_16x16x32_bf16 v[112:115], v[188:191], v[196:199], v[112:115]
	v_mfma_f32_16x16x32_bf16 v[100:103], v[176:179], v[204:207], v[100:103]
	v_mfma_f32_16x16x32_bf16 v[96:99], v[188:191], v[204:207], v[96:99]
	v_mfma_f32_16x16x32_bf16 v[84:87], v[176:179], v[212:215], v[84:87]
	v_mfma_f32_16x16x32_bf16 v[80:83], v[188:191], v[212:215], v[80:83]
	v_mfma_f32_16x16x32_bf16 v[68:71], v[176:179], v[220:223], v[68:71]
	v_mfma_f32_16x16x32_bf16 v[64:67], v[188:191], v[220:223], v[64:67]
	v_mfma_f32_16x16x32_bf16 v[116:119], v[180:183], v[200:203], v[116:119]
	v_mfma_f32_16x16x32_bf16 v[112:115], v[192:195], v[200:203], v[112:115]
	v_mfma_f32_16x16x32_bf16 v[100:103], v[180:183], v[208:211], v[100:103]
	v_mfma_f32_16x16x32_bf16 v[96:99], v[192:195], v[208:211], v[96:99]
	v_mfma_f32_16x16x32_bf16 v[84:87], v[180:183], v[216:219], v[84:87]
	v_mfma_f32_16x16x32_bf16 v[80:83], v[192:195], v[216:219], v[80:83]
	v_mfma_f32_16x16x32_bf16 v[68:71], v[180:183], v[224:227], v[68:71]
	v_mfma_f32_16x16x32_bf16 v[64:67], v[192:195], v[224:227], v[64:67]
	s_setprio 0
	s_barrier
; #define PG8_STAGE(bufoff, gbase, voff) do { _Pragma("unroll") for (int _i = 0; _i < 2; ++_i) \
;         __builtin_amdgcn_global_load_lds((const unsigned*)((const char*)(gbase) + (voff)[_i]), (PG8_LAS unsigned*)(lds + (bufoff) + ldsw + _i * 8192), 16, 0, 0); } while (0)
; #define PG8_LDA(dst, b, h) do { _Pragma("unroll") for (int m = 0; m < 4; ++m) _Pragma("unroll") for (int k = 0; k < 2; ++k) dst[m][k] = *(const PG8_LAS bf16x8*)(lds + PG8_SA(b, h) + aoff + m * 2048 + k * 1024); } while (0)
; #define PG8_MMA(ai, bj, At, Bt) do { __builtin_amdgcn_s_setprio(1); _Pragma("unroll") for (int m = 0; m < 4; ++m) _Pragma("unroll") for (int n = 0; n < 2; ++n) _Pragma("unroll") for (int k = 0; k < 2; ++k) \
;         acc[ai][bj][m][n] = __builtin_amdgcn_mfma_f32_16x16x32_bf16(Bt[n][k], At[m][k], acc[ai][bj][m][n], 0, 0, 0); __builtin_amdgcn_s_setprio(0); } while (0)
; #define PG8_WAIT_V(n) asm volatile("s_waitcnt vmcnt(" #n ")" ::: "memory")
; #define PG8_WAIT_L(n) asm volatile("s_waitcnt lgkmcnt(" #n ")" ::: "memory")
; #define PG8_BAR __builtin_amdgcn_s_barrier()
; #define PG8_SCHED __builtin_amdgcn_sched_barrier(0)
; template <class Epi, class Sched, bool ALIGN_EPI = false, bool SP2 = false>
; __device__ __forceinline__ void gemm_phase(PG8_LAS unsigned char* lds, const Gemm g, const Sched& S, const Epi& E) {
;     ...
;             PG8_LDA(At, 1, 1); PG8_STAGE(PG8_SB(1, 0), b3, voffB); PG8_STAGE(PG8_SB(1, 1), b3 + hstep, voffB); PG8_STAGE(PG8_SA(1, 0), a3, voffA);
;             PG8_WAIT_V(8); PG8_WAIT_L(0); PG8_BAR; PG8_MMA(1, 0, At, B0); PG8_MMA(1, 1, At, B1); PG8_BAR; PG8_SCHED;
;     ...
;         if constexpr (ALIGN_EPI) { if (wr == 0) PG8_BAR; }
	s_add_i32 s28, s48, s31
	v_lshl_add_u64 v[160:161], v[160:161], 0, s[10:11]
	s_mov_b32 m0, s28
	ds_read_b128 v[196:199], v175 offset:49152
	ds_read_b128 v[200:203], v175 offset:50176
	ds_read_b128 v[204:207], v175 offset:51200
	ds_read_b128 v[208:211], v175 offset:52224
	ds_read_b128 v[212:215], v175 offset:53248
	ds_read_b128 v[216:219], v175 offset:54272
	ds_read_b128 v[220:223], v175 offset:55296
	ds_read_b128 v[224:227], v175 offset:56320
	global_load_lds_dwordx4 v[160:161], off
	s_add_i32 m0, s28, 0x2000
	s_add_u32 s26, s26, 0x80080
	v_lshl_add_u64 v[160:161], v[184:185], 0, s[10:11]
	s_addc_u32 s27, s27, 0
	s_add_i32 s28, s49, s31
	global_load_lds_dwordx4 v[160:161], off
	v_lshl_add_u64 v[160:161], s[26:27], 0, v[146:147]
	s_mov_b32 m0, s28
	s_nop 0
	global_load_lds_dwordx4 v[160:161], off
	v_lshl_add_u64 v[160:161], s[26:27], 0, v[150:151]
	s_add_i32 m0, s28, 0x2000
	s_nop 0
	global_load_lds_dwordx4 v[160:161], off
	v_lshl_add_u64 v[160:161], v[228:229], 0, s[10:11]
	s_mov_b32 m0, s38
	s_nop 0
	global_load_lds_dwordx4 v[160:161], off
	v_lshl_add_u64 v[160:161], v[230:231], 0, s[10:11]
	s_mov_b32 m0, s39
	s_nop 0
	global_load_lds_dwordx4 v[160:161], off
	s_waitcnt vmcnt(8)
	s_waitcnt lgkmcnt(0)
	s_barrier
	s_setprio 1
	s_waitcnt lgkmcnt(0)
	v_mfma_f32_16x16x32_bf16 v[60:63], v[128:131], v[196:199], v[60:63]
	v_mfma_f32_16x16x32_bf16 v[56:59], v[136:139], v[196:199], v[56:59]
	v_mfma_f32_16x16x32_bf16 v[44:47], v[128:131], v[204:207], v[44:47]
	v_mfma_f32_16x16x32_bf16 v[40:43], v[136:139], v[204:207], v[40:43]
	v_mfma_f32_16x16x32_bf16 v[28:31], v[128:131], v[212:215], v[28:31]
	v_mfma_f32_16x16x32_bf16 v[24:27], v[136:139], v[212:215], v[24:27]
	v_mfma_f32_16x16x32_bf16 v[12:15], v[128:131], v[220:223], v[12:15]
	v_mfma_f32_16x16x32_bf16 v[8:11], v[136:139], v[220:223], v[8:11]
	v_mfma_f32_16x16x32_bf16 v[60:63], v[132:135], v[200:203], v[60:63]
	v_mfma_f32_16x16x32_bf16 v[56:59], v[140:143], v[200:203], v[56:59]
	v_mfma_f32_16x16x32_bf16 v[44:47], v[132:135], v[208:211], v[44:47]
	v_mfma_f32_16x16x32_bf16 v[40:43], v[140:143], v[208:211], v[40:43]
	v_mfma_f32_16x16x32_bf16 v[28:31], v[132:135], v[216:219], v[28:31]
	v_mfma_f32_16x16x32_bf16 v[24:27], v[140:143], v[216:219], v[24:27]
	v_mfma_f32_16x16x32_bf16 v[12:15], v[132:135], v[224:227], v[12:15]
	v_mfma_f32_16x16x32_bf16 v[8:11], v[140:143], v[224:227], v[8:11]
	v_mfma_f32_16x16x32_bf16 v[52:55], v[176:179], v[196:199], v[52:55]
	v_mfma_f32_16x16x32_bf16 v[48:51], v[188:191], v[196:199], v[48:51]
	v_mfma_f32_16x16x32_bf16 v[36:39], v[176:179], v[204:207], v[36:39]
	v_mfma_f32_16x16x32_bf16 v[32:35], v[188:191], v[204:207], v[32:35]
	v_mfma_f32_16x16x32_bf16 v[20:23], v[176:179], v[212:215], v[20:23]
	v_mfma_f32_16x16x32_bf16 v[16:19], v[188:191], v[212:215], v[16:19]
	v_mfma_f32_16x16x32_bf16 v[4:7], v[176:179], v[220:223], v[4:7]
	v_mfma_f32_16x16x32_bf16 v[0:3], v[188:191], v[220:223], v[0:3]
	v_mfma_f32_16x16x32_bf16 v[52:55], v[180:183], v[200:203], v[52:55]
	v_mfma_f32_16x16x32_bf16 v[48:51], v[192:195], v[200:203], v[48:51]
	v_mfma_f32_16x16x32_bf16 v[36:39], v[180:183], v[208:211], v[36:39]
	v_mfma_f32_16x16x32_bf16 v[32:35], v[192:195], v[208:211], v[32:35]
	v_mfma_f32_16x16x32_bf16 v[20:23], v[180:183], v[216:219], v[20:23]
	v_mfma_f32_16x16x32_bf16 v[16:19], v[192:195], v[216:219], v[16:19]
	v_mfma_f32_16x16x32_bf16 v[4:7], v[180:183], v[224:227], v[4:7]
	v_mfma_f32_16x16x32_bf16 v[0:3], v[192:195], v[224:227], v[0:3]
	s_setprio 0
	s_barrier
	s_add_i32 s47, s47, 2
	s_add_u32 s24, s24, 0x100
	s_addc_u32 s25, s25, 0
	s_add_u32 s45, s45, 0x100
	s_addc_u32 s46, s46, 0
	s_cmp_gt_u32 s47, 29
	s_cbranch_scc0 .LBB0_994
	s_and_b64 vcc, exec, s[12:13]
	s_cbranch_vccz .LBB0_997
	s_barrier

; #define PG8_STAGE(bufoff, gbase, voff) do { _Pragma("unroll") for (int _i = 0; _i < 2; ++_i) \
;         __builtin_amdgcn_global_load_lds((const unsigned*)((const char*)(gbase) + (voff)[_i]), (PG8_LAS unsigned*)(lds + (bufoff) + ldsw + _i * 8192), 16, 0, 0); } while (0)
; #define PG8_LDA(dst, b, h) do { _Pragma("unroll") for (int m = 0; m < 4; ++m) _Pragma("unroll") for (int k = 0; k < 2; ++k) dst[m][k] = *(const PG8_LAS bf16x8*)(lds + PG8_SA(b, h) + aoff + m * 2048 + k * 1024); } while (0)
; #define PG8_LDB(dst, b, h) do { _Pragma("unroll") for (int n = 0; n < 2; ++n) _Pragma("unroll") for (int k = 0; k < 2; ++k) dst[n][k] = *(const PG8_LAS bf16x8*)(lds + PG8_SB(b, h) + boff + n * 2048 + k * 1024); } while (0)
; #define PG8_WAIT_V(n) asm volatile("s_waitcnt vmcnt(" #n ")" ::: "memory")
; #define PG8_WAIT_L(n) asm volatile("s_waitcnt lgkmcnt(" #n ")" ::: "memory")
; #define PG8_BAR __builtin_amdgcn_s_barrier()
; #define PG8_SCHED __builtin_amdgcn_sched_barrier(0)
; template <class Epi, class Sched, bool ALIGN_EPI = false, bool SP2 = false>
; __device__ __forceinline__ void gemm_phase(PG8_LAS unsigned char* lds, const Gemm g, const Sched& S, const Epi& E) {
;     ...
;         const char* nA = has_next ? (const char*)g.A + (size_t)nxt.pm * tstep : cA; const char* nB = has_next ? (const char*)g.Bt + (size_t)nxt.pn * tstep : cB;
;         for (int t = 0; t < nt; t += 2) {
;             const bool last = (t == nt - 2);
;             const char* a1 = cA + (size_t)(t + 1) * kstep;
;             const char* a2 = last ? nA : cA + (size_t)(t + 2) * kstep; const char* b2 = last ? nB : cB + (size_t)(t + 2) * kstep;
;             const char* a3 = a2 + kstep; const char* b3 = b2 + kstep;
;             if (last && has_next) S.a_ready(nxt);
;             if constexpr (SP2) {
;             PG8_LDB(B0, 0, 0); PG8_LDB(B1, 0, 1); PG8_SCHED; PG8_LDA(At, 0, 0); PG8_STAGE(PG8_SA(1, 1), a1 + hstep, voffA);
;             PG8_WAIT_V(8); PG8_WAIT_L(0); PG8_BAR; PG8_MMA(0, 0, At, B0); PG8_MMA(0, 1, At, B1); PG8_BAR; PG8_SCHED;
;             PG8_LDA(At, 0, 1); PG8_STAGE(PG8_SB(0, 0), b2, voffB); PG8_STAGE(PG8_SB(0, 1), b2 + hstep, voffB); PG8_STAGE(PG8_SA(0, 0), a2, voffA);
;             PG8_WAIT_V(8); PG8_WAIT_L(0); PG8_BAR; PG8_MMA(1, 0, At, B0); PG8_MMA(1, 1, At, B1); PG8_BAR; PG8_SCHED;
.LBB0_1071:
	ds_read_b128 v[64:67], v165
	ds_read_b128 v[108:111], v165 offset:1024
	ds_read_b128 v[116:119], v165 offset:2048
	ds_read_b128 v[128:131], v165 offset:3072
	ds_read_b128 v[156:159], v166
	ds_read_b128 v[168:171], v166 offset:1024
	ds_read_b128 v[172:175], v166 offset:2048
	ds_read_b128 v[176:179], v166 offset:3072
	s_add_u32 s28, s26, 0xffe00080
	s_addc_u32 s29, s27, -1
	s_cmpk_eq_i32 s55, 0x7c
	s_cselect_b32 s31, s19, s29
	s_cselect_b32 s30, s51, s28
	s_cselect_b32 s29, s17, s54
	s_cselect_b32 s28, s52, s53
	v_lshl_add_u64 v[160:161], s[26:27], 0, v[148:149]
	s_add_i32 m0, s35, 0xc000
	ds_read_b128 v[180:183], v167
	ds_read_b128 v[184:187], v167 offset:1024
	ds_read_b128 v[188:191], v167 offset:2048
	ds_read_b128 v[192:195], v167 offset:3072
	ds_read_b128 v[196:199], v167 offset:4096
	ds_read_b128 v[200:203], v167 offset:5120
	ds_read_b128 v[204:207], v167 offset:6144
	ds_read_b128 v[208:211], v167 offset:7168
	global_load_lds_dwordx4 v[160:161], off
	v_lshl_add_u64 v[160:161], s[26:27], 0, v[150:151]
	s_add_i32 m0, s35, 0xe000
	s_nop 0
	global_load_lds_dwordx4 v[160:161], off
	s_waitcnt vmcnt(8)
	s_waitcnt lgkmcnt(0)
	s_barrier
	s_setprio 1
	s_waitcnt lgkmcnt(0)
	v_mfma_f32_16x16x32_bf16 v[140:143], v[64:67], v[180:183], v[140:143]
	v_mfma_f32_16x16x32_bf16 v[136:139], v[116:119], v[180:183], v[136:139]
	v_mfma_f32_16x16x32_bf16 v[120:123], v[64:67], v[188:191], v[120:123]
	v_mfma_f32_16x16x32_bf16 v[112:115], v[116:119], v[188:191], v[112:115]
	v_mfma_f32_16x16x32_bf16 v[96:99], v[64:67], v[196:199], v[96:99]
	v_mfma_f32_16x16x32_bf16 v[92:95], v[116:119], v[196:199], v[92:95]
	v_mfma_f32_16x16x32_bf16 v[80:83], v[64:67], v[204:207], v[80:83]
	v_mfma_f32_16x16x32_bf16 v[76:79], v[116:119], v[204:207], v[76:79]
	v_mfma_f32_16x16x32_bf16 v[140:143], v[108:111], v[184:187], v[140:143]
	v_mfma_f32_16x16x32_bf16 v[136:139], v[128:131], v[184:187], v[136:139]
	v_mfma_f32_16x16x32_bf16 v[120:123], v[108:111], v[192:195], v[120:123]
	v_mfma_f32_16x16x32_bf16 v[112:115], v[128:131], v[192:195], v[112:115]
	v_mfma_f32_16x16x32_bf16 v[96:99], v[108:111], v[200:203], v[96:99]
	v_mfma_f32_16x16x32_bf16 v[92:95], v[128:131], v[200:203], v[92:95]
	v_mfma_f32_16x16x32_bf16 v[80:83], v[108:111], v[208:211], v[80:83]
	v_mfma_f32_16x16x32_bf16 v[76:79], v[128:131], v[208:211], v[76:79]
	v_mfma_f32_16x16x32_bf16 v[132:135], v[156:159], v[180:183], v[132:135]
	v_mfma_f32_16x16x32_bf16 v[124:127], v[172:175], v[180:183], v[124:127]
	v_mfma_f32_16x16x32_bf16 v[104:107], v[156:159], v[188:191], v[104:107]
	v_mfma_f32_16x16x32_bf16 v[100:103], v[172:175], v[188:191], v[100:103]
	v_mfma_f32_16x16x32_bf16 v[88:91], v[156:159], v[196:199], v[88:91]
	v_mfma_f32_16x16x32_bf16 v[84:87], v[172:175], v[196:199], v[84:87]
	v_mfma_f32_16x16x32_bf16 v[72:75], v[156:159], v[204:207], v[72:75]
	v_mfma_f32_16x16x32_bf16 v[68:71], v[172:175], v[204:207], v[68:71]
	v_mfma_f32_16x16x32_bf16 v[132:135], v[168:171], v[184:187], v[132:135]
	v_mfma_f32_16x16x32_bf16 v[124:127], v[176:179], v[184:187], v[124:127]
	v_mfma_f32_16x16x32_bf16 v[104:107], v[168:171], v[192:195], v[104:107]
	v_mfma_f32_16x16x32_bf16 v[100:103], v[176:179], v[192:195], v[100:103]
	v_mfma_f32_16x16x32_bf16 v[88:91], v[168:171], v[200:203], v[88:91]
	v_mfma_f32_16x16x32_bf16 v[84:87], v[176:179], v[200:203], v[84:87]
	v_mfma_f32_16x16x32_bf16 v[72:75], v[168:171], v[208:211], v[72:75]
	v_mfma_f32_16x16x32_bf16 v[68:71], v[176:179], v[208:211], v[68:71]
	s_setprio 0
	s_barrier
	s_add_i32 s56, s45, s34
	v_lshl_add_u64 v[160:161], s[28:29], 0, v[144:145]
	s_mov_b32 m0, s56
	ds_read_b128 v[180:183], v167 offset:16384
	ds_read_b128 v[184:187], v167 offset:17408
	ds_read_b128 v[188:191], v167 offset:18432
	ds_read_b128 v[192:195], v167 offset:19456
	ds_read_b128 v[196:199], v167 offset:20480
	ds_read_b128 v[200:203], v167 offset:21504
	ds_read_b128 v[204:207], v167 offset:22528
	ds_read_b128 v[208:211], v167 offset:23552
	global_load_lds_dwordx4 v[160:161], off
	s_add_i32 m0, s56, 0x2000
	s_add_u32 s56, s28, 0x200000
	v_lshl_add_u64 v[212:213], s[28:29], 0, v[146:147]
	s_addc_u32 s57, s29, 0
	s_add_i32 s58, s46, s34
	global_load_lds_dwordx4 v[212:213], off
	v_lshl_add_u64 v[214:215], s[56:57], 0, v[144:145]
	s_mov_b32 m0, s58
	v_lshl_add_u64 v[216:217], s[30:31], 0, v[146:147]
	global_load_lds_dwordx4 v[214:215], off
	v_lshl_add_u64 v[214:215], s[56:57], 0, v[146:147]
	s_add_i32 m0, s58, 0x2000
	s_nop 0
	global_load_lds_dwordx4 v[214:215], off
	v_lshl_add_u64 v[214:215], s[30:31], 0, v[144:145]
	s_mov_b32 m0, s35
	s_nop 0
	global_load_lds_dwordx4 v[214:215], off
	s_mov_b32 m0, s36
	s_nop 0
	global_load_lds_dwordx4 v[216:217], off
	s_waitcnt vmcnt(8)
	s_waitcnt lgkmcnt(0)
	s_barrier
; #define PG8_STAGE(bufoff, gbase, voff) do { _Pragma("unroll") for (int _i = 0; _i < 2; ++_i) \
;         __builtin_amdgcn_global_load_lds((const unsigned*)((const char*)(gbase) + (voff)[_i]), (PG8_LAS unsigned*)(lds + (bufoff) + ldsw + _i * 8192), 16, 0, 0); } while (0)
; #define PG8_LDA(dst, b, h) do { _Pragma("unroll") for (int m = 0; m < 4; ++m) _Pragma("unroll") for (int k = 0; k < 2; ++k) dst[m][k] = *(const PG8_LAS bf16x8*)(lds + PG8_SA(b, h) + aoff + m * 2048 + k * 1024); } while (0)
; #define PG8_LDB(dst, b, h) do { _Pragma("unroll") for (int n = 0; n < 2; ++n) _Pragma("unroll") for (int k = 0; k < 2; ++k) dst[n][k] = *(const PG8_LAS bf16x8*)(lds + PG8_SB(b, h) + boff + n * 2048 + k * 1024); } while (0)
; #define PG8_MMA(ai, bj, At, Bt) do { __builtin_amdgcn_s_setprio(1); _Pragma("unroll") for (int m = 0; m < 4; ++m) _Pragma("unroll") for (int n = 0; n < 2; ++n) _Pragma("unroll") for (int k = 0; k < 2; ++k) \
;         acc[ai][bj][m][n] = __builtin_amdgcn_mfma_f32_16x16x32_bf16(Bt[n][k], At[m][k], acc[ai][bj][m][n], 0, 0, 0); __builtin_amdgcn_s_setprio(0); } while (0)
; #define PG8_WAIT_V(n) asm volatile("s_waitcnt vmcnt(" #n ")" ::: "memory")
; #define PG8_WAIT_L(n) asm volatile("s_waitcnt lgkmcnt(" #n ")" ::: "memory")
; #define PG8_BAR __builtin_amdgcn_s_barrier()
; #define PG8_SCHED __builtin_amdgcn_sched_barrier(0)
; template <class Epi, class Sched, bool ALIGN_EPI = false, bool SP2 = false>
; __device__ __forceinline__ void gemm_phase(PG8_LAS unsigned char* lds, const Gemm g, const Sched& S, const Epi& E) {
;     ...
;             PG8_WAIT_V(8); PG8_WAIT_L(0); PG8_BAR; PG8_MMA(1, 0, At, B0); PG8_MMA(1, 1, At, B1); PG8_BAR; PG8_SCHED;
;             PG8_LDB(B0, 1, 0); PG8_LDB(B1, 1, 1); PG8_SCHED; PG8_LDA(At, 1, 0); PG8_STAGE(PG8_SA(0, 1), a2 + hstep, voffA);
;             PG8_WAIT_V(8); PG8_WAIT_L(0); PG8_BAR; PG8_MMA(0, 0, At, B0); PG8_MMA(0, 1, At, B1); PG8_BAR; PG8_SCHED;
	s_setprio 1
	s_waitcnt lgkmcnt(0)
	v_mfma_f32_16x16x32_bf16 v[60:63], v[64:67], v[180:183], v[60:63]
	v_mfma_f32_16x16x32_bf16 v[56:59], v[116:119], v[180:183], v[56:59]
	v_mfma_f32_16x16x32_bf16 v[44:47], v[64:67], v[188:191], v[44:47]
	v_mfma_f32_16x16x32_bf16 v[40:43], v[116:119], v[188:191], v[40:43]
	v_mfma_f32_16x16x32_bf16 v[28:31], v[64:67], v[196:199], v[28:31]
	v_mfma_f32_16x16x32_bf16 v[24:27], v[116:119], v[196:199], v[24:27]
	v_mfma_f32_16x16x32_bf16 v[12:15], v[64:67], v[204:207], v[12:15]
	v_mfma_f32_16x16x32_bf16 v[8:11], v[116:119], v[204:207], v[8:11]
	v_mfma_f32_16x16x32_bf16 v[60:63], v[108:111], v[184:187], v[60:63]
	v_mfma_f32_16x16x32_bf16 v[56:59], v[128:131], v[184:187], v[56:59]
	v_mfma_f32_16x16x32_bf16 v[44:47], v[108:111], v[192:195], v[44:47]
	v_mfma_f32_16x16x32_bf16 v[40:43], v[128:131], v[192:195], v[40:43]
	v_mfma_f32_16x16x32_bf16 v[28:31], v[108:111], v[200:203], v[28:31]
	v_mfma_f32_16x16x32_bf16 v[24:27], v[128:131], v[200:203], v[24:27]
	v_mfma_f32_16x16x32_bf16 v[12:15], v[108:111], v[208:211], v[12:15]
	v_mfma_f32_16x16x32_bf16 v[8:11], v[128:131], v[208:211], v[8:11]
	v_mfma_f32_16x16x32_bf16 v[52:55], v[156:159], v[180:183], v[52:55]
	v_mfma_f32_16x16x32_bf16 v[48:51], v[172:175], v[180:183], v[48:51]
	v_mfma_f32_16x16x32_bf16 v[36:39], v[156:159], v[188:191], v[36:39]
	v_mfma_f32_16x16x32_bf16 v[32:35], v[172:175], v[188:191], v[32:35]
	v_mfma_f32_16x16x32_bf16 v[20:23], v[156:159], v[196:199], v[20:23]
	v_mfma_f32_16x16x32_bf16 v[16:19], v[172:175], v[196:199], v[16:19]
	v_mfma_f32_16x16x32_bf16 v[4:7], v[156:159], v[204:207], v[4:7]
	v_mfma_f32_16x16x32_bf16 v[0:3], v[172:175], v[204:207], v[0:3]
	v_mfma_f32_16x16x32_bf16 v[52:55], v[168:171], v[184:187], v[52:55]
	v_mfma_f32_16x16x32_bf16 v[48:51], v[176:179], v[184:187], v[48:51]
	v_mfma_f32_16x16x32_bf16 v[36:39], v[168:171], v[192:195], v[36:39]
	v_mfma_f32_16x16x32_bf16 v[32:35], v[176:179], v[192:195], v[32:35]
	v_mfma_f32_16x16x32_bf16 v[20:23], v[168:171], v[200:203], v[20:23]
	v_mfma_f32_16x16x32_bf16 v[16:19], v[176:179], v[200:203], v[16:19]
	v_mfma_f32_16x16x32_bf16 v[4:7], v[168:171], v[208:211], v[4:7]
	v_mfma_f32_16x16x32_bf16 v[0:3], v[176:179], v[208:211], v[0:3]
	s_setprio 0
	s_barrier
	s_add_i32 s56, 0, 0x18000
	s_add_i32 s57, 0, 0x1c000
	v_add_u32_e32 v128, s56, v163
	v_add_u32_e32 v176, s57, v163
	ds_read_b128 v[64:67], v128
	ds_read_b128 v[108:111], v128 offset:1024
	ds_read_b128 v[116:119], v128 offset:2048
	ds_read_b128 v[128:131], v128 offset:3072
	ds_read_b128 v[156:159], v176
	ds_read_b128 v[168:171], v176 offset:1024
	ds_read_b128 v[172:175], v176 offset:2048
	ds_read_b128 v[176:179], v176 offset:3072
	s_add_u32 s30, s30, 0x200000
	s_addc_u32 s31, s31, 0
	s_mov_b32 m0, s37
	v_lshl_add_u64 v[218:219], s[30:31], 0, v[144:145]
	ds_read_b128 v[180:183], v167 offset:32768
	ds_read_b128 v[184:187], v167 offset:33792
	ds_read_b128 v[188:191], v167 offset:34816
	ds_read_b128 v[192:195], v167 offset:35840
	ds_read_b128 v[196:199], v167 offset:36864
	ds_read_b128 v[200:203], v167 offset:37888
	ds_read_b128 v[204:207], v167 offset:38912
	ds_read_b128 v[208:211], v167 offset:39936
	global_load_lds_dwordx4 v[218:219], off
	v_lshl_add_u64 v[218:219], s[30:31], 0, v[146:147]
	s_mov_b32 m0, s38
	s_nop 0
	global_load_lds_dwordx4 v[218:219], off
	s_waitcnt vmcnt(8)
	s_waitcnt lgkmcnt(0)
	s_barrier
	s_setprio 1
	s_waitcnt lgkmcnt(0)
	v_mfma_f32_16x16x32_bf16 v[140:143], v[64:67], v[180:183], v[140:143]
	v_mfma_f32_16x16x32_bf16 v[136:139], v[116:119], v[180:183], v[136:139]
	v_mfma_f32_16x16x32_bf16 v[120:123], v[64:67], v[188:191], v[120:123]
	v_mfma_f32_16x16x32_bf16 v[112:115], v[116:119], v[188:191], v[112:115]
	v_mfma_f32_16x16x32_bf16 v[96:99], v[64:67], v[196:199], v[96:99]
	v_mfma_f32_16x16x32_bf16 v[92:95], v[116:119], v[196:199], v[92:95]
	v_mfma_f32_16x16x32_bf16 v[80:83], v[64:67], v[204:207], v[80:83]
	v_mfma_f32_16x16x32_bf16 v[76:79], v[116:119], v[204:207], v[76:79]
	v_mfma_f32_16x16x32_bf16 v[140:143], v[108:111], v[184:187], v[140:143]
	v_mfma_f32_16x16x32_bf16 v[136:139], v[128:131], v[184:187], v[136:139]
	v_mfma_f32_16x16x32_bf16 v[120:123], v[108:111], v[192:195], v[120:123]
	v_mfma_f32_16x16x32_bf16 v[112:115], v[128:131], v[192:195], v[112:115]
	v_mfma_f32_16x16x32_bf16 v[96:99], v[108:111], v[200:203], v[96:99]
	v_mfma_f32_16x16x32_bf16 v[92:95], v[128:131], v[200:203], v[92:95]
	v_mfma_f32_16x16x32_bf16 v[80:83], v[108:111], v[208:211], v[80:83]
	v_mfma_f32_16x16x32_bf16 v[76:79], v[128:131], v[208:211], v[76:79]
	v_mfma_f32_16x16x32_bf16 v[132:135], v[156:159], v[180:183], v[132:135]
	v_mfma_f32_16x16x32_bf16 v[124:127], v[172:175], v[180:183], v[124:127]
	v_mfma_f32_16x16x32_bf16 v[104:107], v[156:159], v[188:191], v[104:107]
	v_mfma_f32_16x16x32_bf16 v[100:103], v[172:175], v[188:191], v[100:103]
	v_mfma_f32_16x16x32_bf16 v[88:91], v[156:159], v[196:199], v[88:91]
	v_mfma_f32_16x16x32_bf16 v[84:87], v[172:175], v[196:199], v[84:87]
	v_mfma_f32_16x16x32_bf16 v[72:75], v[156:159], v[204:207], v[72:75]
	v_mfma_f32_16x16x32_bf16 v[68:71], v[172:175], v[204:207], v[68:71]
	v_mfma_f32_16x16x32_bf16 v[132:135], v[168:171], v[184:187], v[132:135]
	v_mfma_f32_16x16x32_bf16 v[124:127], v[176:179], v[184:187], v[124:127]
	v_mfma_f32_16x16x32_bf16 v[104:107], v[168:171], v[192:195], v[104:107]
	v_mfma_f32_16x16x32_bf16 v[100:103], v[176:179], v[192:195], v[100:103]
	v_mfma_f32_16x16x32_bf16 v[88:91], v[168:171], v[200:203], v[88:91]
	v_mfma_f32_16x16x32_bf16 v[84:87], v[176:179], v[200:203], v[84:87]
	v_mfma_f32_16x16x32_bf16 v[72:75], v[168:171], v[208:211], v[72:75]
	v_mfma_f32_16x16x32_bf16 v[68:71], v[176:179], v[208:211], v[68:71]
	s_setprio 0
	s_barrier
; #define PG8_STAGE(bufoff, gbase, voff) do { _Pragma("unroll") for (int _i = 0; _i < 2; ++_i) \
;         __builtin_amdgcn_global_load_lds((const unsigned*)((const char*)(gbase) + (voff)[_i]), (PG8_LAS unsigned*)(lds + (bufoff) + ldsw + _i * 8192), 16, 0, 0); } while (0)
; #define PG8_LDA(dst, b, h) do { _Pragma("unroll") for (int m = 0; m < 4; ++m) _Pragma("unroll") for (int k = 0; k < 2; ++k) dst[m][k] = *(const PG8_LAS bf16x8*)(lds + PG8_SA(b, h) + aoff + m * 2048 + k * 1024); } while (0)
; #define PG8_MMA(ai, bj, At, Bt) do { __builtin_amdgcn_s_setprio(1); _Pragma("unroll") for (int m = 0; m < 4; ++m) _Pragma("unroll") for (int n = 0; n < 2; ++n) _Pragma("unroll") for (int k = 0; k < 2; ++k) \
;         acc[ai][bj][m][n] = __builtin_amdgcn_mfma_f32_16x16x32_bf16(Bt[n][k], At[m][k], acc[ai][bj][m][n], 0, 0, 0); __builtin_amdgcn_s_setprio(0); } while (0)
; #define PG8_WAIT_V(n) asm volatile("s_waitcnt vmcnt(" #n ")" ::: "memory")
; #define PG8_WAIT_L(n) asm volatile("s_waitcnt lgkmcnt(" #n ")" ::: "memory")
; #define PG8_BAR __builtin_amdgcn_s_barrier()
; #define PG8_SCHED __builtin_amdgcn_sched_barrier(0)
; template <class Epi, class Sched, bool ALIGN_EPI = false, bool SP2 = false>
; __device__ __forceinline__ void gemm_phase(PG8_LAS unsigned char* lds, const Gemm g, const Sched& S, const Epi& E) {
;     ...
;             PG8_LDA(At, 1, 1); PG8_STAGE(PG8_SB(1, 0), b3, voffB); PG8_STAGE(PG8_SB(1, 1), b3 + hstep, voffB); PG8_STAGE(PG8_SA(1, 0), a3, voffA);
;             PG8_WAIT_V(8); PG8_WAIT_L(0); PG8_BAR; PG8_MMA(1, 0, At, B0); PG8_MMA(1, 1, At, B1); PG8_BAR; PG8_SCHED;
;     ...
;         if constexpr (ALIGN_EPI) { if (wr == 0) PG8_BAR; }
	s_add_i32 s30, s56, s34
	v_lshl_add_u64 v[160:161], v[160:161], 0, s[4:5]
	s_mov_b32 m0, s30
	ds_read_b128 v[180:183], v167 offset:49152
	ds_read_b128 v[184:187], v167 offset:50176
	ds_read_b128 v[188:191], v167 offset:51200
	ds_read_b128 v[192:195], v167 offset:52224
	ds_read_b128 v[196:199], v167 offset:53248
	ds_read_b128 v[200:203], v167 offset:54272
	ds_read_b128 v[204:207], v167 offset:55296
	ds_read_b128 v[208:211], v167 offset:56320
	global_load_lds_dwordx4 v[160:161], off
	s_add_i32 m0, s30, 0x2000
	s_add_u32 s28, s28, 0x200080
	v_lshl_add_u64 v[160:161], v[212:213], 0, s[4:5]
	s_addc_u32 s29, s29, 0
	s_add_i32 s30, s57, s34
	global_load_lds_dwordx4 v[160:161], off
	v_lshl_add_u64 v[160:161], s[28:29], 0, v[144:145]
	s_mov_b32 m0, s30
	s_nop 0
	global_load_lds_dwordx4 v[160:161], off
	v_lshl_add_u64 v[160:161], s[28:29], 0, v[146:147]
	s_add_i32 m0, s30, 0x2000
	s_nop 0
	global_load_lds_dwordx4 v[160:161], off
	v_lshl_add_u64 v[160:161], v[214:215], 0, s[4:5]
	s_mov_b32 m0, s42
	s_nop 0
	global_load_lds_dwordx4 v[160:161], off
	v_lshl_add_u64 v[160:161], v[216:217], 0, s[4:5]
	s_mov_b32 m0, s43
	s_nop 0
	global_load_lds_dwordx4 v[160:161], off
	s_waitcnt vmcnt(8)
	s_waitcnt lgkmcnt(0)
	s_barrier
	s_setprio 1
	s_waitcnt lgkmcnt(0)
	v_mfma_f32_16x16x32_bf16 v[60:63], v[64:67], v[180:183], v[60:63]
	v_mfma_f32_16x16x32_bf16 v[56:59], v[116:119], v[180:183], v[56:59]
	v_mfma_f32_16x16x32_bf16 v[44:47], v[64:67], v[188:191], v[44:47]
	v_mfma_f32_16x16x32_bf16 v[40:43], v[116:119], v[188:191], v[40:43]
	v_mfma_f32_16x16x32_bf16 v[28:31], v[64:67], v[196:199], v[28:31]
	v_mfma_f32_16x16x32_bf16 v[24:27], v[116:119], v[196:199], v[24:27]
	v_mfma_f32_16x16x32_bf16 v[12:15], v[64:67], v[204:207], v[12:15]
	v_mfma_f32_16x16x32_bf16 v[8:11], v[116:119], v[204:207], v[8:11]
	v_mfma_f32_16x16x32_bf16 v[60:63], v[108:111], v[184:187], v[60:63]
	v_mfma_f32_16x16x32_bf16 v[56:59], v[128:131], v[184:187], v[56:59]
	v_mfma_f32_16x16x32_bf16 v[44:47], v[108:111], v[192:195], v[44:47]
	v_mfma_f32_16x16x32_bf16 v[40:43], v[128:131], v[192:195], v[40:43]
	v_mfma_f32_16x16x32_bf16 v[28:31], v[108:111], v[200:203], v[28:31]
	v_mfma_f32_16x16x32_bf16 v[24:27], v[128:131], v[200:203], v[24:27]
	v_mfma_f32_16x16x32_bf16 v[12:15], v[108:111], v[208:211], v[12:15]
	v_mfma_f32_16x16x32_bf16 v[8:11], v[128:131], v[208:211], v[8:11]
	v_mfma_f32_16x16x32_bf16 v[52:55], v[156:159], v[180:183], v[52:55]
	v_mfma_f32_16x16x32_bf16 v[48:51], v[172:175], v[180:183], v[48:51]
	v_mfma_f32_16x16x32_bf16 v[36:39], v[156:159], v[188:191], v[36:39]
	v_mfma_f32_16x16x32_bf16 v[32:35], v[172:175], v[188:191], v[32:35]
	v_mfma_f32_16x16x32_bf16 v[20:23], v[156:159], v[196:199], v[20:23]
	v_mfma_f32_16x16x32_bf16 v[16:19], v[172:175], v[196:199], v[16:19]
	v_mfma_f32_16x16x32_bf16 v[4:7], v[156:159], v[204:207], v[4:7]
	v_mfma_f32_16x16x32_bf16 v[0:3], v[172:175], v[204:207], v[0:3]
	v_mfma_f32_16x16x32_bf16 v[52:55], v[168:171], v[184:187], v[52:55]
	v_mfma_f32_16x16x32_bf16 v[48:51], v[176:179], v[184:187], v[48:51]
	v_mfma_f32_16x16x32_bf16 v[36:39], v[168:171], v[192:195], v[36:39]
	v_mfma_f32_16x16x32_bf16 v[32:35], v[176:179], v[192:195], v[32:35]
	v_mfma_f32_16x16x32_bf16 v[20:23], v[168:171], v[200:203], v[20:23]
	v_mfma_f32_16x16x32_bf16 v[16:19], v[176:179], v[200:203], v[16:19]
	v_mfma_f32_16x16x32_bf16 v[4:7], v[168:171], v[208:211], v[4:7]
	v_mfma_f32_16x16x32_bf16 v[0:3], v[176:179], v[208:211], v[0:3]
	s_setprio 0
	s_barrier
	s_add_i32 s55, s55, 2
	s_add_u32 s26, s26, 0x100
	s_addc_u32 s27, s27, 0
	s_add_u32 s53, s53, 0x100
	s_addc_u32 s54, s54, 0
	s_cmpk_gt_u32 s55, 0x7d
	s_cbranch_scc0 .LBB0_1071
	s_and_b64 vcc, exec, s[6:7]
	s_cbranch_vccz .LBB0_1074
	s_barrier
